# v043 + s_nop padding so every MFMA in the six K-loops starts on an 8-byte boundary
# baseline (speedup 1.0000x reference)
.LBB0_134:
	s_add_u32 s28, s66, 0xfffc0080
	s_addc_u32 s29, s67, -1
	s_add_i32 s88, 0, 0x10000
	v_add_u32_e32 v152, s88, v191
	ds_read_b128 v[128:131], v152
	ds_read_b128 v[132:135], v152 offset:1024
	ds_read_b128 v[148:151], v152 offset:2048
	ds_read_b128 v[152:155], v152 offset:3072
	s_cmp_eq_u32 vcc_lo, 12
	s_cselect_b32 s71, s5, s29
	s_cselect_b32 s70, s7, s28
	s_cselect_b32 s69, s17, s91
	s_cselect_b32 s68, s19, s85
	s_add_i32 m0, s73, 0xc000
	ds_read_b128 v[156:159], v192
	ds_read_b128 v[164:167], v192 offset:2048
	ds_read_b128 v[194:197], v192 offset:4096
	ds_read_b128 v[202:205], v192 offset:6144
	ds_read_b128 v[160:163], v192 offset:1024
	ds_read_b128 v[168:171], v192 offset:3072
	ds_read_b128 v[198:201], v192 offset:5120
	ds_read_b128 v[206:209], v192 offset:7168
	global_load_lds_dwordx4 v144, s[66:67]
	v_lshl_add_u64 v[172:173], s[66:67], 0, v[146:147]
	s_add_i32 m0, s73, 0xe000
	s_nop 0
	global_load_lds_dwordx4 v[172:173], off
	s_waitcnt lgkmcnt(8)
	s_barrier
	s_waitcnt lgkmcnt(7)
	s_nop 0
	v_mfma_f32_16x16x32_bf16 v[124:127], v[128:131], v[156:159], v[124:127]
	v_mfma_f32_16x16x32_bf16 v[120:123], v[148:151], v[156:159], v[120:123]
	s_waitcnt lgkmcnt(6)
	s_nop 0
	v_mfma_f32_16x16x32_bf16 v[108:111], v[128:131], v[164:167], v[108:111]
	v_mfma_f32_16x16x32_bf16 v[104:107], v[148:151], v[164:167], v[104:107]
	s_waitcnt lgkmcnt(5)
	s_nop 0
	v_mfma_f32_16x16x32_bf16 v[92:95], v[128:131], v[194:197], v[92:95]
	v_mfma_f32_16x16x32_bf16 v[88:91], v[148:151], v[194:197], v[88:91]
	s_waitcnt lgkmcnt(4)
	s_nop 0
	v_mfma_f32_16x16x32_bf16 v[76:79], v[128:131], v[202:205], v[76:79]
	v_mfma_f32_16x16x32_bf16 v[72:75], v[148:151], v[202:205], v[72:75]
	s_waitcnt lgkmcnt(3)
	s_nop 0
	v_mfma_f32_16x16x32_bf16 v[124:127], v[132:135], v[160:163], v[124:127]
	v_mfma_f32_16x16x32_bf16 v[120:123], v[152:155], v[160:163], v[120:123]
	s_waitcnt lgkmcnt(2)
	s_nop 0
	v_mfma_f32_16x16x32_bf16 v[108:111], v[132:135], v[168:171], v[108:111]
	v_mfma_f32_16x16x32_bf16 v[104:107], v[152:155], v[168:171], v[104:107]
	s_waitcnt lgkmcnt(1)
	s_nop 0
	v_mfma_f32_16x16x32_bf16 v[92:95], v[132:135], v[198:201], v[92:95]
	v_mfma_f32_16x16x32_bf16 v[88:91], v[152:155], v[198:201], v[88:91]
	s_waitcnt lgkmcnt(0)
	s_nop 0
	v_mfma_f32_16x16x32_bf16 v[76:79], v[132:135], v[206:209], v[76:79]
	v_mfma_f32_16x16x32_bf16 v[72:75], v[152:155], v[206:209], v[72:75]
	s_barrier
	s_add_i32 s89, 0, 0x14000
	v_add_u32_e32 v172, s89, v191
	s_add_i32 s28, s88, s72
	ds_read_b128 v[210:213], v172
	ds_read_b128 v[214:217], v172 offset:1024
	ds_read_b128 v[232:235], v172 offset:2048
	ds_read_b128 v[236:239], v172 offset:3072
	v_lshl_add_u64 v[172:173], s[68:69], 0, v[138:139]
	s_mov_b32 m0, s28
	v_lshl_add_u64 v[188:189], s[68:69], 0, v[142:143]
	global_load_lds_dwordx4 v[172:173], off
	s_add_i32 m0, s28, 0x2000
	s_nop 0
	global_load_lds_dwordx4 v[188:189], off
	s_barrier
	s_waitcnt lgkmcnt(3)
	s_nop 0
	v_mfma_f32_16x16x32_bf16 v[116:119], v[210:213], v[156:159], v[116:119]
	s_waitcnt lgkmcnt(1)
	s_nop 0
	v_mfma_f32_16x16x32_bf16 v[112:115], v[232:235], v[156:159], v[112:115]
	v_mfma_f32_16x16x32_bf16 v[100:103], v[210:213], v[164:167], v[100:103]
	v_mfma_f32_16x16x32_bf16 v[96:99], v[232:235], v[164:167], v[96:99]
	v_mfma_f32_16x16x32_bf16 v[84:87], v[210:213], v[194:197], v[84:87]
	v_mfma_f32_16x16x32_bf16 v[80:83], v[232:235], v[194:197], v[80:83]
	v_mfma_f32_16x16x32_bf16 v[68:71], v[210:213], v[202:205], v[68:71]
	v_mfma_f32_16x16x32_bf16 v[64:67], v[232:235], v[202:205], v[64:67]
	v_mfma_f32_16x16x32_bf16 v[116:119], v[214:217], v[160:163], v[116:119]
	s_waitcnt lgkmcnt(0)
	s_nop 0
	v_mfma_f32_16x16x32_bf16 v[112:115], v[236:239], v[160:163], v[112:115]
	v_mfma_f32_16x16x32_bf16 v[100:103], v[214:217], v[168:171], v[100:103]
	v_mfma_f32_16x16x32_bf16 v[96:99], v[236:239], v[168:171], v[96:99]
	v_mfma_f32_16x16x32_bf16 v[84:87], v[214:217], v[198:201], v[84:87]
	v_mfma_f32_16x16x32_bf16 v[80:83], v[236:239], v[198:201], v[80:83]
	v_mfma_f32_16x16x32_bf16 v[68:71], v[214:217], v[206:209], v[68:71]
	v_mfma_f32_16x16x32_bf16 v[64:67], v[236:239], v[206:209], v[64:67]
	s_mov_b32 m0, s73
	v_lshl_add_u64 v[240:241], s[70:71], 0, v[136:137]
	s_barrier
	ds_read_b128 v[156:159], v192 offset:16384
	ds_read_b128 v[164:167], v192 offset:18432
	ds_read_b128 v[194:197], v192 offset:20480
	ds_read_b128 v[202:205], v192 offset:22528
	ds_read_b128 v[160:163], v192 offset:17408
	ds_read_b128 v[168:171], v192 offset:19456
	ds_read_b128 v[198:201], v192 offset:21504
	ds_read_b128 v[206:209], v192 offset:23552
	global_load_lds_dwordx4 v[240:241], off
	v_lshl_add_u64 v[242:243], s[70:71], 0, v[140:141]
	s_mov_b32 m0, s74
	s_nop 0
	global_load_lds_dwordx4 v[242:243], off
	s_barrier
	s_waitcnt lgkmcnt(7)
	v_mfma_f32_16x16x32_bf16 v[60:63], v[128:131], v[156:159], v[60:63]
	v_mfma_f32_16x16x32_bf16 v[56:59], v[148:151], v[156:159], v[56:59]
	s_waitcnt lgkmcnt(6)
	s_nop 0
	v_mfma_f32_16x16x32_bf16 v[44:47], v[128:131], v[164:167], v[44:47]
	v_mfma_f32_16x16x32_bf16 v[40:43], v[148:151], v[164:167], v[40:43]
	s_waitcnt lgkmcnt(5)
	s_nop 0
	v_mfma_f32_16x16x32_bf16 v[28:31], v[128:131], v[194:197], v[28:31]
	v_mfma_f32_16x16x32_bf16 v[24:27], v[148:151], v[194:197], v[24:27]
	s_waitcnt lgkmcnt(4)
	s_nop 0
	v_mfma_f32_16x16x32_bf16 v[12:15], v[128:131], v[202:205], v[12:15]
	v_mfma_f32_16x16x32_bf16 v[8:11], v[148:151], v[202:205], v[8:11]
	s_waitcnt lgkmcnt(3)
	s_nop 0
	v_mfma_f32_16x16x32_bf16 v[60:63], v[132:135], v[160:163], v[60:63]
	v_mfma_f32_16x16x32_bf16 v[56:59], v[152:155], v[160:163], v[56:59]
	s_waitcnt lgkmcnt(2)
	s_nop 0
	v_mfma_f32_16x16x32_bf16 v[44:47], v[132:135], v[168:171], v[44:47]
	v_mfma_f32_16x16x32_bf16 v[40:43], v[152:155], v[168:171], v[40:43]
	s_waitcnt lgkmcnt(1)
	s_nop 0
	v_mfma_f32_16x16x32_bf16 v[28:31], v[132:135], v[198:201], v[28:31]
	v_mfma_f32_16x16x32_bf16 v[24:27], v[152:155], v[198:201], v[24:27]
	s_waitcnt lgkmcnt(0)
	s_nop 0
	v_mfma_f32_16x16x32_bf16 v[12:15], v[132:135], v[206:209], v[12:15]
	v_mfma_f32_16x16x32_bf16 v[8:11], v[152:155], v[206:209], v[8:11]
	s_barrier
	s_add_u32 s28, s68, 0x40000
	s_addc_u32 s29, s69, 0
	s_add_i32 s88, s89, s72
	s_mov_b32 m0, s88
	s_nop 0
	global_load_lds_dwordx4 v138, s[28:29]
	s_add_i32 m0, s88, 0x2000
	s_nop 0
	global_load_lds_dwordx4 v142, s[28:29]
	s_waitcnt vmcnt(6)
	s_barrier
	v_mfma_f32_16x16x32_bf16 v[52:55], v[210:213], v[156:159], v[52:55]
	v_mfma_f32_16x16x32_bf16 v[48:51], v[232:235], v[156:159], v[48:51]
	v_mfma_f32_16x16x32_bf16 v[36:39], v[210:213], v[164:167], v[36:39]
	v_mfma_f32_16x16x32_bf16 v[32:35], v[232:235], v[164:167], v[32:35]
	v_mfma_f32_16x16x32_bf16 v[20:23], v[210:213], v[194:197], v[20:23]
	v_mfma_f32_16x16x32_bf16 v[16:19], v[232:235], v[194:197], v[16:19]
	v_mfma_f32_16x16x32_bf16 v[4:7], v[210:213], v[202:205], v[4:7]
	v_mfma_f32_16x16x32_bf16 v[0:3], v[232:235], v[202:205], v[0:3]
	v_mfma_f32_16x16x32_bf16 v[52:55], v[214:217], v[160:163], v[52:55]
	v_mfma_f32_16x16x32_bf16 v[48:51], v[236:239], v[160:163], v[48:51]
	v_mfma_f32_16x16x32_bf16 v[36:39], v[214:217], v[168:171], v[36:39]
	v_mfma_f32_16x16x32_bf16 v[32:35], v[236:239], v[168:171], v[32:35]
	v_mfma_f32_16x16x32_bf16 v[20:23], v[214:217], v[198:201], v[20:23]
	v_mfma_f32_16x16x32_bf16 v[16:19], v[236:239], v[198:201], v[16:19]
	v_mfma_f32_16x16x32_bf16 v[4:7], v[214:217], v[206:209], v[4:7]
	v_mfma_f32_16x16x32_bf16 v[0:3], v[236:239], v[206:209], v[0:3]
	s_add_i32 s88, 0, 0x18000
	v_add_u32_e32 v152, s88, v191
	s_barrier
	ds_read_b128 v[128:131], v152
	ds_read_b128 v[132:135], v152 offset:1024
	ds_read_b128 v[148:151], v152 offset:2048
	ds_read_b128 v[152:155], v152 offset:3072
	s_add_u32 s28, s70, 0x40000
	s_addc_u32 s29, s71, 0
	s_mov_b32 m0, s75
	ds_read_b128 v[156:159], v192 offset:32768
	ds_read_b128 v[164:167], v192 offset:34816
	ds_read_b128 v[194:197], v192 offset:36864
	ds_read_b128 v[202:205], v192 offset:38912
	ds_read_b128 v[160:163], v192 offset:33792
	ds_read_b128 v[168:171], v192 offset:35840
	ds_read_b128 v[198:201], v192 offset:37888
	ds_read_b128 v[206:209], v192 offset:39936
	global_load_lds_dwordx4 v136, s[28:29]
	s_mov_b32 m0, s76
	s_nop 0
	global_load_lds_dwordx4 v140, s[28:29]
	s_waitcnt lgkmcnt(8)
	s_barrier
	s_waitcnt lgkmcnt(7)
	s_nop 0
	v_mfma_f32_16x16x32_bf16 v[124:127], v[128:131], v[156:159], v[124:127]
	v_mfma_f32_16x16x32_bf16 v[120:123], v[148:151], v[156:159], v[120:123]
	s_waitcnt lgkmcnt(6)
	s_nop 0
	v_mfma_f32_16x16x32_bf16 v[108:111], v[128:131], v[164:167], v[108:111]
	v_mfma_f32_16x16x32_bf16 v[104:107], v[148:151], v[164:167], v[104:107]
	s_waitcnt lgkmcnt(5)
	s_nop 0
	v_mfma_f32_16x16x32_bf16 v[92:95], v[128:131], v[194:197], v[92:95]
	v_mfma_f32_16x16x32_bf16 v[88:91], v[148:151], v[194:197], v[88:91]
	s_waitcnt lgkmcnt(4)
	s_nop 0
	v_mfma_f32_16x16x32_bf16 v[76:79], v[128:131], v[202:205], v[76:79]
	v_mfma_f32_16x16x32_bf16 v[72:75], v[148:151], v[202:205], v[72:75]
	s_waitcnt lgkmcnt(3)
	s_nop 0
	v_mfma_f32_16x16x32_bf16 v[124:127], v[132:135], v[160:163], v[124:127]
	v_mfma_f32_16x16x32_bf16 v[120:123], v[152:155], v[160:163], v[120:123]
	s_waitcnt lgkmcnt(2)
	s_nop 0
	v_mfma_f32_16x16x32_bf16 v[108:111], v[132:135], v[168:171], v[108:111]
	v_mfma_f32_16x16x32_bf16 v[104:107], v[152:155], v[168:171], v[104:107]
	s_waitcnt lgkmcnt(1)
	s_nop 0
	v_mfma_f32_16x16x32_bf16 v[92:95], v[132:135], v[198:201], v[92:95]
	v_mfma_f32_16x16x32_bf16 v[88:91], v[152:155], v[198:201], v[88:91]
	s_waitcnt lgkmcnt(0)
	s_nop 0
	v_mfma_f32_16x16x32_bf16 v[76:79], v[132:135], v[206:209], v[76:79]
	v_mfma_f32_16x16x32_bf16 v[72:75], v[152:155], v[206:209], v[72:75]
	s_barrier
	s_add_i32 s70, 0, 0x1c000
	s_add_i32 s28, s88, s72
	v_add_u32_e32 v174, s70, v191
	v_lshl_add_u64 v[172:173], v[172:173], 0, s[40:41]
	s_mov_b32 m0, s28
	ds_read_b128 v[210:213], v174
	ds_read_b128 v[214:217], v174 offset:1024
	ds_read_b128 v[232:235], v174 offset:2048
	ds_read_b128 v[236:239], v174 offset:3072
	global_load_lds_dwordx4 v[172:173], off
	v_lshl_add_u64 v[172:173], v[188:189], 0, s[40:41]
	s_add_i32 m0, s28, 0x2000
	s_nop 0
	global_load_lds_dwordx4 v[172:173], off
	s_barrier
	s_waitcnt lgkmcnt(3)
	s_nop 0
	v_mfma_f32_16x16x32_bf16 v[116:119], v[210:213], v[156:159], v[116:119]
	s_waitcnt lgkmcnt(1)
	s_nop 0
	v_mfma_f32_16x16x32_bf16 v[112:115], v[232:235], v[156:159], v[112:115]
	v_mfma_f32_16x16x32_bf16 v[100:103], v[210:213], v[164:167], v[100:103]
	v_mfma_f32_16x16x32_bf16 v[96:99], v[232:235], v[164:167], v[96:99]
	v_mfma_f32_16x16x32_bf16 v[84:87], v[210:213], v[194:197], v[84:87]
	v_mfma_f32_16x16x32_bf16 v[80:83], v[232:235], v[194:197], v[80:83]
	v_mfma_f32_16x16x32_bf16 v[68:71], v[210:213], v[202:205], v[68:71]
	v_mfma_f32_16x16x32_bf16 v[64:67], v[232:235], v[202:205], v[64:67]
	v_mfma_f32_16x16x32_bf16 v[116:119], v[214:217], v[160:163], v[116:119]
	s_waitcnt lgkmcnt(0)
	s_nop 0
	v_mfma_f32_16x16x32_bf16 v[112:115], v[236:239], v[160:163], v[112:115]
	v_mfma_f32_16x16x32_bf16 v[100:103], v[214:217], v[168:171], v[100:103]
	v_mfma_f32_16x16x32_bf16 v[96:99], v[236:239], v[168:171], v[96:99]
	v_mfma_f32_16x16x32_bf16 v[84:87], v[214:217], v[198:201], v[84:87]
	v_mfma_f32_16x16x32_bf16 v[80:83], v[236:239], v[198:201], v[80:83]
	v_mfma_f32_16x16x32_bf16 v[68:71], v[214:217], v[206:209], v[68:71]
	v_mfma_f32_16x16x32_bf16 v[64:67], v[236:239], v[206:209], v[64:67]
	s_mov_b32 m0, s79
	v_lshl_add_u64 v[172:173], v[240:241], 0, s[40:41]
	s_barrier
	ds_read_b128 v[156:159], v192 offset:49152
	ds_read_b128 v[164:167], v192 offset:51200
	ds_read_b128 v[194:197], v192 offset:53248
	ds_read_b128 v[202:205], v192 offset:55296
	ds_read_b128 v[160:163], v192 offset:50176
	ds_read_b128 v[168:171], v192 offset:52224
	ds_read_b128 v[198:201], v192 offset:54272
	ds_read_b128 v[206:209], v192 offset:56320
	global_load_lds_dwordx4 v[172:173], off
	v_lshl_add_u64 v[172:173], v[242:243], 0, s[40:41]
	s_mov_b32 m0, s80
	s_nop 0
	global_load_lds_dwordx4 v[172:173], off
	s_barrier
	s_waitcnt lgkmcnt(7)
	v_mfma_f32_16x16x32_bf16 v[60:63], v[128:131], v[156:159], v[60:63]
	v_mfma_f32_16x16x32_bf16 v[56:59], v[148:151], v[156:159], v[56:59]
	s_waitcnt lgkmcnt(6)
	s_nop 0
	v_mfma_f32_16x16x32_bf16 v[44:47], v[128:131], v[164:167], v[44:47]
	v_mfma_f32_16x16x32_bf16 v[40:43], v[148:151], v[164:167], v[40:43]
	s_waitcnt lgkmcnt(5)
	s_nop 0
	v_mfma_f32_16x16x32_bf16 v[28:31], v[128:131], v[194:197], v[28:31]
	v_mfma_f32_16x16x32_bf16 v[24:27], v[148:151], v[194:197], v[24:27]
	s_waitcnt lgkmcnt(4)
	s_nop 0
	v_mfma_f32_16x16x32_bf16 v[12:15], v[128:131], v[202:205], v[12:15]
	v_mfma_f32_16x16x32_bf16 v[8:11], v[148:151], v[202:205], v[8:11]
	s_waitcnt lgkmcnt(3)
	s_nop 0
	v_mfma_f32_16x16x32_bf16 v[60:63], v[132:135], v[160:163], v[60:63]
	v_mfma_f32_16x16x32_bf16 v[56:59], v[152:155], v[160:163], v[56:59]
	s_waitcnt lgkmcnt(2)
	s_nop 0
	v_mfma_f32_16x16x32_bf16 v[44:47], v[132:135], v[168:171], v[44:47]
	v_mfma_f32_16x16x32_bf16 v[40:43], v[152:155], v[168:171], v[40:43]
	s_waitcnt lgkmcnt(1)
	s_nop 0
	v_mfma_f32_16x16x32_bf16 v[28:31], v[132:135], v[198:201], v[28:31]
	v_mfma_f32_16x16x32_bf16 v[24:27], v[152:155], v[198:201], v[24:27]
	s_waitcnt lgkmcnt(0)
	s_nop 0
	v_mfma_f32_16x16x32_bf16 v[12:15], v[132:135], v[206:209], v[12:15]
	v_mfma_f32_16x16x32_bf16 v[8:11], v[152:155], v[206:209], v[8:11]
	s_barrier
	s_add_u32 s28, s68, 0x40080
	s_addc_u32 s29, s69, 0
	s_add_i32 s68, s70, s72
	s_mov_b32 m0, s68
	s_nop 0
	global_load_lds_dwordx4 v138, s[28:29]
	s_add_i32 m0, s68, 0x2000
	s_nop 0
	global_load_lds_dwordx4 v142, s[28:29]
	s_waitcnt vmcnt(6)
	s_barrier
	v_mfma_f32_16x16x32_bf16 v[52:55], v[210:213], v[156:159], v[52:55]
	v_mfma_f32_16x16x32_bf16 v[48:51], v[232:235], v[156:159], v[48:51]
	v_mfma_f32_16x16x32_bf16 v[36:39], v[210:213], v[164:167], v[36:39]
	v_mfma_f32_16x16x32_bf16 v[32:35], v[232:235], v[164:167], v[32:35]
	v_mfma_f32_16x16x32_bf16 v[20:23], v[210:213], v[194:197], v[20:23]
	v_mfma_f32_16x16x32_bf16 v[16:19], v[232:235], v[194:197], v[16:19]
	v_mfma_f32_16x16x32_bf16 v[4:7], v[210:213], v[202:205], v[4:7]
	v_mfma_f32_16x16x32_bf16 v[0:3], v[232:235], v[202:205], v[0:3]
	v_mfma_f32_16x16x32_bf16 v[52:55], v[214:217], v[160:163], v[52:55]
	v_mfma_f32_16x16x32_bf16 v[48:51], v[236:239], v[160:163], v[48:51]
	v_mfma_f32_16x16x32_bf16 v[36:39], v[214:217], v[168:171], v[36:39]
	v_mfma_f32_16x16x32_bf16 v[32:35], v[236:239], v[168:171], v[32:35]
	v_mfma_f32_16x16x32_bf16 v[20:23], v[214:217], v[198:201], v[20:23]
	v_mfma_f32_16x16x32_bf16 v[16:19], v[236:239], v[198:201], v[16:19]
	v_mfma_f32_16x16x32_bf16 v[4:7], v[214:217], v[206:209], v[4:7]
	v_mfma_f32_16x16x32_bf16 v[0:3], v[236:239], v[206:209], v[0:3]
	s_add_i32 vcc_lo, vcc_lo, 2
	s_add_u32 s66, s66, 0x100
	s_addc_u32 s67, s67, 0
	s_add_u32 s85, s85, 0x100
	s_addc_u32 s91, s91, 0
	s_cmp_lt_u32 vcc_lo, 14
	s_barrier
	s_cbranch_scc1 .LBB0_134
	s_lshl_b32 s4, s4, 8
	v_mov_b32_e32 v176, v175
	v_mov_b32_e32 v188, v190
	s_add_i32 s4, s4, s77
	s_cmp_gt_i32 s6, 7
	v_add_u32_e32 v148, s4, v176
	v_lshlrev_b32_e32 v128, 2, v188
	v_ashrrev_i32_e32 v129, 31, v128
	v_ashrrev_i32_e32 v149, 31, v148
	v_lshl_add_u64 v[128:129], v[128:129], 2, s[8:9]
	v_lshlrev_b64 v[130:131], 6, v[148:149]
	v_add_u32_e32 v166, 16, v148
	v_lshl_add_u64 v[130:131], v[128:129], 0, v[130:131]
	v_ashrrev_i32_e32 v167, 31, v166
	global_load_dwordx4 v[160:163], v[130:131], off
	v_lshlrev_b64 v[130:131], 6, v[166:167]
	v_lshl_add_u64 v[130:131], v[128:129], 0, v[130:131]
	global_load_dwordx4 v[168:171], v[130:131], off
	v_add_u32_e32 v164, 32, v148
	v_ashrrev_i32_e32 v165, 31, v164
	v_lshlrev_b64 v[130:131], 6, v[164:165]
	v_add_u32_e32 v158, 48, v148
	v_lshl_add_u64 v[130:131], v[128:129], 0, v[130:131]
	v_ashrrev_i32_e32 v159, 31, v158
	global_load_dwordx4 v[194:197], v[130:131], off
	v_lshlrev_b64 v[130:131], 6, v[158:159]
	v_lshl_add_u64 v[130:131], v[128:129], 0, v[130:131]
	global_load_dwordx4 v[198:201], v[130:131], off
	v_add_u32_e32 v156, 0x80, v148
	v_ashrrev_i32_e32 v157, 31, v156
	v_lshlrev_b64 v[130:131], 6, v[156:157]
	v_add_u32_e32 v154, 0x90, v148
	v_lshl_add_u64 v[130:131], v[128:129], 0, v[130:131]
	v_ashrrev_i32_e32 v155, 31, v154
	global_load_dwordx4 v[202:205], v[130:131], off
	v_lshlrev_b64 v[130:131], 6, v[154:155]
	v_add_u32_e32 v152, 0xa0, v148
	v_lshl_add_u64 v[130:131], v[128:129], 0, v[130:131]
	v_ashrrev_i32_e32 v153, 31, v152
	global_load_dwordx4 v[206:209], v[130:131], off
	v_lshlrev_b64 v[130:131], 6, v[152:153]
	v_add_u32_e32 v150, 0xb0, v148
	v_lshl_add_u64 v[130:131], v[128:129], 0, v[130:131]
	v_ashrrev_i32_e32 v151, 31, v150
	global_load_dwordx4 v[132:135], v[130:131], off
	v_lshlrev_b64 v[130:131], 6, v[150:151]
	v_lshl_add_u64 v[128:129], v[128:129], 0, v[130:131]
	global_load_dwordx4 v[128:131], v[128:129], off
	s_cselect_b64 s[66:67], -1, 0
	s_lshl_b32 s7, s6, 8
	s_add_i32 s7, s81, s7
	s_cmp_lt_i32 s6, 8
	s_mov_b64 s[68:69], -1
	s_waitcnt vmcnt(0)
	v_mov_b32_e32 v172, v161
	v_mov_b32_e32 v173, v162
	v_mov_b32_e32 v161, v163
	v_mov_b32_e32 v162, v169
	v_mov_b32_e32 v163, v170
	v_mov_b32_e32 v169, v171
	v_pk_add_f32 v[160:161], v[172:173], v[160:161]
	v_pk_add_f32 v[162:163], v[162:163], v[168:169]
	v_mov_b32_e32 v169, v160
	v_mov_b32_e32 v168, v162
	v_mov_b32_e32 v160, v163
	v_pk_add_f32 v[160:161], v[168:169], v[160:161]
	ds_bpermute_b32 v163, v219, v161
	ds_bpermute_b32 v162, v219, v160
	s_waitcnt lgkmcnt(0)
	v_pk_add_f32 v[160:161], v[160:161], v[162:163]
	ds_bpermute_b32 v163, v218, v161
	ds_bpermute_b32 v162, v218, v160
	s_waitcnt lgkmcnt(0)
	v_pk_add_f32 v[160:161], v[160:161], v[162:163]
	s_nop 0
	v_pk_fma_f32 v[172:173], v[160:161], s[30:31], v[178:179] op_sel_hi:[1,0,0]
	v_mov_b32_e32 v162, v199
	v_mul_f32_e32 v160, 0x4b800000, v173
	v_cmp_gt_f32_e32 vcc, s86, v173
	v_mov_b32_e32 v163, v200
	v_mov_b32_e32 v199, v201
	v_cndmask_b32_e32 v160, v173, v160, vcc
	v_rsq_f32_e32 v160, v160
	v_pk_add_f32 v[162:163], v[162:163], v[198:199]
	v_cmp_gt_f32_e64 s[4:5], s86, v172
	v_mov_b32_e32 v168, v162
	v_mul_f32_e32 v161, 0x45800000, v160
	v_cndmask_b32_e32 v174, v160, v161, vcc
	v_mov_b32_e32 v160, v195
	v_mov_b32_e32 v161, v196
	v_mov_b32_e32 v195, v197
	v_pk_add_f32 v[160:161], v[160:161], v[194:195]
	s_nop 0
	v_mov_b32_e32 v169, v160
	v_mov_b32_e32 v160, v163
	v_pk_add_f32 v[160:161], v[168:169], v[160:161]
	ds_bpermute_b32 v163, v219, v161
	ds_bpermute_b32 v162, v219, v160
	s_waitcnt lgkmcnt(0)
	v_pk_add_f32 v[168:169], v[160:161], v[162:163]
	v_mov_b32_e32 v160, v203
	v_mov_b32_e32 v161, v204
	v_mov_b32_e32 v203, v205
	v_mov_b32_e32 v162, v207
	v_mov_b32_e32 v163, v208
	v_mov_b32_e32 v207, v209
	v_pk_add_f32 v[160:161], v[160:161], v[202:203]
	v_pk_add_f32 v[162:163], v[162:163], v[206:207]
	v_mov_b32_e32 v195, v160
	v_mov_b32_e32 v194, v162
	v_mov_b32_e32 v160, v163
	v_pk_add_f32 v[160:161], v[194:195], v[160:161]
	v_mov_b32_e32 v194, v133
	v_mov_b32_e32 v195, v134
	v_mov_b32_e32 v133, v135
	v_mov_b32_e32 v134, v129
	v_mov_b32_e32 v135, v130
	v_mov_b32_e32 v129, v131
	v_pk_add_f32 v[132:133], v[194:195], v[132:133]
	v_pk_add_f32 v[128:129], v[134:135], v[128:129]
	v_mov_b32_e32 v131, v132
	v_mov_b32_e32 v130, v128
	v_mov_b32_e32 v132, v129
	v_pk_add_f32 v[128:129], v[130:131], v[132:133]
	ds_bpermute_b32 v163, v219, v161
	ds_bpermute_b32 v162, v219, v160
	ds_bpermute_b32 v131, v219, v129
	ds_bpermute_b32 v130, v219, v128
	ds_bpermute_b32 v171, v218, v169
	ds_bpermute_b32 v170, v218, v168
	s_waitcnt lgkmcnt(4)
	v_pk_add_f32 v[160:161], v[160:161], v[162:163]
	ds_bpermute_b32 v163, v218, v161
	s_waitcnt lgkmcnt(3)
	v_pk_add_f32 v[132:133], v[128:129], v[130:131]
	ds_bpermute_b32 v162, v218, v160
	ds_bpermute_b32 v135, v218, v133
	ds_bpermute_b32 v134, v218, v132
	v_lshlrev_b32_e32 v128, 3, v188
	v_add_u32_e32 v130, s7, v128
	v_lshlrev_b64 v[188:189], 11, v[148:149]
	v_ashrrev_i32_e32 v131, 31, v130
	s_cbranch_scc1 .LBB0_137
	v_mul_f32_e32 v196, v120, v174
	v_mul_f32_e32 v197, v121, v174
	v_mul_f32_e32 v198, v122, v174
	v_mul_f32_e32 v199, v123, v174
	v_mul_f32_e32 v129, v124, v174
	v_mul_f32_e32 v149, v125, v174
	v_mul_f32_e32 v173, v126, v174
	v_mul_f32_e32 v193, v127, v174
	v_cvt_pk_bf16_f32 v194, v129, v149
	v_cvt_pk_bf16_f32 v195, v173, v193
	v_cvt_pk_bf16_f32 v196, v196, v197
	v_cvt_pk_bf16_f32 v197, v198, v199
	v_lshl_add_u64 v[198:199], s[12:13], 0, v[188:189]
	v_lshl_add_u64 v[198:199], v[130:131], 1, v[198:199]
	global_store_dwordx4 v[198:199], v[194:197], off
	s_mov_b64 s[68:69], 0
	v_mul_f32_e32 v129, v116, v174
	v_mul_f32_e32 v196, v112, v174
	v_mul_f32_e32 v197, v113, v174
	v_mul_f32_e32 v149, v117, v174
	v_mul_f32_e32 v173, v118, v174
	v_mul_f32_e32 v193, v119, v174
	v_mul_f32_e32 v200, v114, v174
	v_mul_f32_e32 v201, v115, v174
	v_cvt_pk_bf16_f32 v194, v129, v149
	v_cvt_pk_bf16_f32 v195, v173, v193
	v_cvt_pk_bf16_f32 v196, v196, v197
	v_cvt_pk_bf16_f32 v197, v200, v201
	global_store_dwordx4 v[198:199], v[194:197], off offset:256

.LBB0_413:
	s_add_i32 vcc_lo, s62, 2
	s_add_u32 s4, s18, 0x100
	s_addc_u32 s5, s19, 0
	s_add_i32 s28, 0, 0x10000
	v_add_u32_e32 v140, s28, v164
	ds_read_b128 v[128:131], v140
	ds_read_b128 v[132:135], v140 offset:1024
	ds_read_b128 v[136:139], v140 offset:2048
	ds_read_b128 v[140:143], v140 offset:3072
	s_cmp_eq_u32 s13, s62
	s_cselect_b32 s62, s6, s85
	s_cselect_b32 s65, s17, s5
	s_cselect_b32 s64, s16, s4
	s_cselect_b32 s63, s7, s91
	s_add_i32 m0, s69, 0xc000
	ds_read_b128 v[154:157], v165
	ds_read_b128 v[166:169], v165 offset:2048
	ds_read_b128 v[188:191], v165 offset:4096
	ds_read_b128 v[196:199], v165 offset:6144
	ds_read_b128 v[158:161], v165 offset:1024
	ds_read_b128 v[170:173], v165 offset:3072
	ds_read_b128 v[192:195], v165 offset:5120
	ds_read_b128 v[200:203], v165 offset:7168
	global_load_lds_dwordx4 v150, s[18:19]
	v_lshl_add_u64 v[174:175], s[18:19], 0, v[152:153]
	s_add_i32 m0, s69, 0xe000
	s_nop 0
	global_load_lds_dwordx4 v[174:175], off
	s_waitcnt lgkmcnt(8)
	s_barrier
	s_waitcnt lgkmcnt(7)
	s_nop 0
	v_mfma_f32_16x16x32_bf16 v[124:127], v[128:131], v[154:157], v[124:127]
	v_mfma_f32_16x16x32_bf16 v[120:123], v[136:139], v[154:157], v[120:123]
	s_waitcnt lgkmcnt(6)
	s_nop 0
	v_mfma_f32_16x16x32_bf16 v[108:111], v[128:131], v[166:169], v[108:111]
	v_mfma_f32_16x16x32_bf16 v[104:107], v[136:139], v[166:169], v[104:107]
	s_waitcnt lgkmcnt(5)
	s_nop 0
	v_mfma_f32_16x16x32_bf16 v[92:95], v[128:131], v[188:191], v[92:95]
	v_mfma_f32_16x16x32_bf16 v[88:91], v[136:139], v[188:191], v[88:91]
	s_waitcnt lgkmcnt(4)
	s_nop 0
	v_mfma_f32_16x16x32_bf16 v[76:79], v[128:131], v[196:199], v[76:79]
	v_mfma_f32_16x16x32_bf16 v[72:75], v[136:139], v[196:199], v[72:75]
	s_waitcnt lgkmcnt(3)
	s_nop 0
	v_mfma_f32_16x16x32_bf16 v[124:127], v[132:135], v[158:161], v[124:127]
	v_mfma_f32_16x16x32_bf16 v[120:123], v[140:143], v[158:161], v[120:123]
	s_waitcnt lgkmcnt(2)
	s_nop 0
	v_mfma_f32_16x16x32_bf16 v[108:111], v[132:135], v[170:173], v[108:111]
	v_mfma_f32_16x16x32_bf16 v[104:107], v[140:143], v[170:173], v[104:107]
	s_waitcnt lgkmcnt(1)
	s_nop 0
	v_mfma_f32_16x16x32_bf16 v[92:95], v[132:135], v[192:195], v[92:95]
	v_mfma_f32_16x16x32_bf16 v[88:91], v[140:143], v[192:195], v[88:91]
	s_waitcnt lgkmcnt(0)
	s_nop 0
	v_mfma_f32_16x16x32_bf16 v[76:79], v[132:135], v[200:203], v[76:79]
	v_mfma_f32_16x16x32_bf16 v[72:75], v[140:143], v[200:203], v[72:75]
	s_barrier
	s_add_i32 s29, 0, 0x14000
	v_add_u32_e32 v174, s29, v164
	s_add_i32 s18, s28, s68
	ds_read_b128 v[204:207], v174
	ds_read_b128 v[208:211], v174 offset:1024
	ds_read_b128 v[212:215], v174 offset:2048
	ds_read_b128 v[232:235], v174 offset:3072
	v_lshl_add_u64 v[174:175], s[62:63], 0, v[176:177]
	s_mov_b32 m0, s18
	v_lshl_add_u64 v[216:217], s[62:63], 0, v[148:149]
	global_load_lds_dwordx4 v[174:175], off
	s_add_i32 m0, s18, 0x2000
	s_nop 0
	global_load_lds_dwordx4 v[216:217], off
	s_barrier
	s_waitcnt lgkmcnt(3)
	s_nop 0
	v_mfma_f32_16x16x32_bf16 v[116:119], v[204:207], v[154:157], v[116:119]
	s_waitcnt lgkmcnt(1)
	s_nop 0
	v_mfma_f32_16x16x32_bf16 v[112:115], v[212:215], v[154:157], v[112:115]
	v_mfma_f32_16x16x32_bf16 v[100:103], v[204:207], v[166:169], v[100:103]
	v_mfma_f32_16x16x32_bf16 v[96:99], v[212:215], v[166:169], v[96:99]
	v_mfma_f32_16x16x32_bf16 v[84:87], v[204:207], v[188:191], v[84:87]
	v_mfma_f32_16x16x32_bf16 v[80:83], v[212:215], v[188:191], v[80:83]
	v_mfma_f32_16x16x32_bf16 v[68:71], v[204:207], v[196:199], v[68:71]
	v_mfma_f32_16x16x32_bf16 v[64:67], v[212:215], v[196:199], v[64:67]
	v_mfma_f32_16x16x32_bf16 v[116:119], v[208:211], v[158:161], v[116:119]
	s_waitcnt lgkmcnt(0)
	s_nop 0
	v_mfma_f32_16x16x32_bf16 v[112:115], v[232:235], v[158:161], v[112:115]
	v_mfma_f32_16x16x32_bf16 v[100:103], v[208:211], v[170:173], v[100:103]
	v_mfma_f32_16x16x32_bf16 v[96:99], v[232:235], v[170:173], v[96:99]
	v_mfma_f32_16x16x32_bf16 v[84:87], v[208:211], v[192:195], v[84:87]
	v_mfma_f32_16x16x32_bf16 v[80:83], v[232:235], v[192:195], v[80:83]
	v_mfma_f32_16x16x32_bf16 v[68:71], v[208:211], v[200:203], v[68:71]
	v_mfma_f32_16x16x32_bf16 v[64:67], v[232:235], v[200:203], v[64:67]
	s_mov_b32 m0, s69
	v_lshl_add_u64 v[236:237], s[64:65], 0, v[144:145]
	s_barrier
	ds_read_b128 v[154:157], v165 offset:16384
	ds_read_b128 v[166:169], v165 offset:18432
	ds_read_b128 v[188:191], v165 offset:20480
	ds_read_b128 v[196:199], v165 offset:22528
	ds_read_b128 v[158:161], v165 offset:17408
	ds_read_b128 v[170:173], v165 offset:19456
	ds_read_b128 v[192:195], v165 offset:21504
	ds_read_b128 v[200:203], v165 offset:23552
	global_load_lds_dwordx4 v[236:237], off
	v_lshl_add_u64 v[238:239], s[64:65], 0, v[146:147]
	s_mov_b32 m0, s70
	s_nop 0
	global_load_lds_dwordx4 v[238:239], off
	s_barrier
	s_waitcnt lgkmcnt(7)
	v_mfma_f32_16x16x32_bf16 v[60:63], v[128:131], v[154:157], v[60:63]
	v_mfma_f32_16x16x32_bf16 v[56:59], v[136:139], v[154:157], v[56:59]
	s_waitcnt lgkmcnt(6)
	s_nop 0
	v_mfma_f32_16x16x32_bf16 v[44:47], v[128:131], v[166:169], v[44:47]
	v_mfma_f32_16x16x32_bf16 v[40:43], v[136:139], v[166:169], v[40:43]
	s_waitcnt lgkmcnt(5)
	s_nop 0
	v_mfma_f32_16x16x32_bf16 v[28:31], v[128:131], v[188:191], v[28:31]
	v_mfma_f32_16x16x32_bf16 v[24:27], v[136:139], v[188:191], v[24:27]
	s_waitcnt lgkmcnt(4)
	s_nop 0
	v_mfma_f32_16x16x32_bf16 v[12:15], v[128:131], v[196:199], v[12:15]
	v_mfma_f32_16x16x32_bf16 v[8:11], v[136:139], v[196:199], v[8:11]
	s_waitcnt lgkmcnt(3)
	s_nop 0
	v_mfma_f32_16x16x32_bf16 v[60:63], v[132:135], v[158:161], v[60:63]
	v_mfma_f32_16x16x32_bf16 v[56:59], v[140:143], v[158:161], v[56:59]
	s_waitcnt lgkmcnt(2)
	s_nop 0
	v_mfma_f32_16x16x32_bf16 v[44:47], v[132:135], v[170:173], v[44:47]
	v_mfma_f32_16x16x32_bf16 v[40:43], v[140:143], v[170:173], v[40:43]
	s_waitcnt lgkmcnt(1)
	s_nop 0
	v_mfma_f32_16x16x32_bf16 v[28:31], v[132:135], v[192:195], v[28:31]
	v_mfma_f32_16x16x32_bf16 v[24:27], v[140:143], v[192:195], v[24:27]
	s_waitcnt lgkmcnt(0)
	s_nop 0
	v_mfma_f32_16x16x32_bf16 v[12:15], v[132:135], v[200:203], v[12:15]
	v_mfma_f32_16x16x32_bf16 v[8:11], v[140:143], v[200:203], v[8:11]
	s_barrier
	s_add_u32 s18, s62, 0x18000
	s_addc_u32 s19, s63, 0
	s_add_i32 s28, s29, s68
	s_mov_b32 m0, s28
	s_nop 0
	global_load_lds_dwordx4 v176, s[18:19]
	s_add_i32 m0, s28, 0x2000
	s_nop 0
	global_load_lds_dwordx4 v148, s[18:19]
	s_waitcnt vmcnt(6)
	s_barrier
	v_mfma_f32_16x16x32_bf16 v[52:55], v[204:207], v[154:157], v[52:55]
	v_mfma_f32_16x16x32_bf16 v[48:51], v[212:215], v[154:157], v[48:51]
	v_mfma_f32_16x16x32_bf16 v[36:39], v[204:207], v[166:169], v[36:39]
	v_mfma_f32_16x16x32_bf16 v[32:35], v[212:215], v[166:169], v[32:35]
	v_mfma_f32_16x16x32_bf16 v[20:23], v[204:207], v[188:191], v[20:23]
	v_mfma_f32_16x16x32_bf16 v[16:19], v[212:215], v[188:191], v[16:19]
	v_mfma_f32_16x16x32_bf16 v[4:7], v[204:207], v[196:199], v[4:7]
	v_mfma_f32_16x16x32_bf16 v[0:3], v[212:215], v[196:199], v[0:3]
	v_mfma_f32_16x16x32_bf16 v[52:55], v[208:211], v[158:161], v[52:55]
	v_mfma_f32_16x16x32_bf16 v[48:51], v[232:235], v[158:161], v[48:51]
	v_mfma_f32_16x16x32_bf16 v[36:39], v[208:211], v[170:173], v[36:39]
	v_mfma_f32_16x16x32_bf16 v[32:35], v[232:235], v[170:173], v[32:35]
	v_mfma_f32_16x16x32_bf16 v[20:23], v[208:211], v[192:195], v[20:23]
	v_mfma_f32_16x16x32_bf16 v[16:19], v[232:235], v[192:195], v[16:19]
	v_mfma_f32_16x16x32_bf16 v[4:7], v[208:211], v[200:203], v[4:7]
	v_mfma_f32_16x16x32_bf16 v[0:3], v[232:235], v[200:203], v[0:3]
	s_add_i32 s28, 0, 0x18000
	v_add_u32_e32 v140, s28, v164
	s_barrier
	ds_read_b128 v[128:131], v140
	ds_read_b128 v[132:135], v140 offset:1024
	ds_read_b128 v[136:139], v140 offset:2048
	ds_read_b128 v[140:143], v140 offset:3072
	s_add_u32 s18, s64, 0x18000
	s_addc_u32 s19, s65, 0
	s_mov_b32 m0, s71
	ds_read_b128 v[154:157], v165 offset:32768
	ds_read_b128 v[166:169], v165 offset:34816
	ds_read_b128 v[188:191], v165 offset:36864
	ds_read_b128 v[196:199], v165 offset:38912
	ds_read_b128 v[158:161], v165 offset:33792
	ds_read_b128 v[170:173], v165 offset:35840
	ds_read_b128 v[192:195], v165 offset:37888
	ds_read_b128 v[200:203], v165 offset:39936
	global_load_lds_dwordx4 v144, s[18:19]
	s_mov_b32 m0, s72
	s_nop 0
	global_load_lds_dwordx4 v146, s[18:19]
	s_waitcnt lgkmcnt(8)
	s_barrier
	s_waitcnt lgkmcnt(7)
	s_nop 0
	v_mfma_f32_16x16x32_bf16 v[124:127], v[128:131], v[154:157], v[124:127]
	v_mfma_f32_16x16x32_bf16 v[120:123], v[136:139], v[154:157], v[120:123]
	s_waitcnt lgkmcnt(6)
	s_nop 0
	v_mfma_f32_16x16x32_bf16 v[108:111], v[128:131], v[166:169], v[108:111]
	v_mfma_f32_16x16x32_bf16 v[104:107], v[136:139], v[166:169], v[104:107]
	s_waitcnt lgkmcnt(5)
	s_nop 0
	v_mfma_f32_16x16x32_bf16 v[92:95], v[128:131], v[188:191], v[92:95]
	v_mfma_f32_16x16x32_bf16 v[88:91], v[136:139], v[188:191], v[88:91]
	s_waitcnt lgkmcnt(4)
	s_nop 0
	v_mfma_f32_16x16x32_bf16 v[76:79], v[128:131], v[196:199], v[76:79]
	v_mfma_f32_16x16x32_bf16 v[72:75], v[136:139], v[196:199], v[72:75]
	s_waitcnt lgkmcnt(3)
	s_nop 0
	v_mfma_f32_16x16x32_bf16 v[124:127], v[132:135], v[158:161], v[124:127]
	v_mfma_f32_16x16x32_bf16 v[120:123], v[140:143], v[158:161], v[120:123]
	s_waitcnt lgkmcnt(2)
	s_nop 0
	v_mfma_f32_16x16x32_bf16 v[108:111], v[132:135], v[170:173], v[108:111]
	v_mfma_f32_16x16x32_bf16 v[104:107], v[140:143], v[170:173], v[104:107]
	s_waitcnt lgkmcnt(1)
	s_nop 0
	v_mfma_f32_16x16x32_bf16 v[92:95], v[132:135], v[192:195], v[92:95]
	v_mfma_f32_16x16x32_bf16 v[88:91], v[140:143], v[192:195], v[88:91]
	s_waitcnt lgkmcnt(0)
	s_nop 0
	v_mfma_f32_16x16x32_bf16 v[76:79], v[132:135], v[200:203], v[76:79]
	v_mfma_f32_16x16x32_bf16 v[72:75], v[140:143], v[200:203], v[72:75]
	s_barrier
	s_add_i32 s29, 0, 0x1c000
	s_add_i32 s18, s28, s68
	v_add_u32_e32 v232, s29, v164
	v_lshl_add_u64 v[174:175], v[174:175], 0, s[40:41]
	s_mov_b32 m0, s18
	ds_read_b128 v[204:207], v232
	ds_read_b128 v[208:211], v232 offset:1024
	ds_read_b128 v[212:215], v232 offset:2048
	ds_read_b128 v[232:235], v232 offset:3072
	global_load_lds_dwordx4 v[174:175], off
	v_lshl_add_u64 v[174:175], v[216:217], 0, s[40:41]
	s_add_i32 m0, s18, 0x2000
	s_nop 0
	global_load_lds_dwordx4 v[174:175], off
	s_barrier
	s_waitcnt lgkmcnt(3)
	s_nop 0
	v_mfma_f32_16x16x32_bf16 v[116:119], v[204:207], v[154:157], v[116:119]
	s_waitcnt lgkmcnt(1)
	s_nop 0
	v_mfma_f32_16x16x32_bf16 v[112:115], v[212:215], v[154:157], v[112:115]
	v_mfma_f32_16x16x32_bf16 v[100:103], v[204:207], v[166:169], v[100:103]
	v_mfma_f32_16x16x32_bf16 v[96:99], v[212:215], v[166:169], v[96:99]
	v_mfma_f32_16x16x32_bf16 v[84:87], v[204:207], v[188:191], v[84:87]
	v_mfma_f32_16x16x32_bf16 v[80:83], v[212:215], v[188:191], v[80:83]
	v_mfma_f32_16x16x32_bf16 v[68:71], v[204:207], v[196:199], v[68:71]
	v_mfma_f32_16x16x32_bf16 v[64:67], v[212:215], v[196:199], v[64:67]
	v_mfma_f32_16x16x32_bf16 v[116:119], v[208:211], v[158:161], v[116:119]
	s_waitcnt lgkmcnt(0)
	s_nop 0
	v_mfma_f32_16x16x32_bf16 v[112:115], v[232:235], v[158:161], v[112:115]
	v_mfma_f32_16x16x32_bf16 v[100:103], v[208:211], v[170:173], v[100:103]
	v_mfma_f32_16x16x32_bf16 v[96:99], v[232:235], v[170:173], v[96:99]
	v_mfma_f32_16x16x32_bf16 v[84:87], v[208:211], v[192:195], v[84:87]
	v_mfma_f32_16x16x32_bf16 v[80:83], v[232:235], v[192:195], v[80:83]
	v_mfma_f32_16x16x32_bf16 v[68:71], v[208:211], v[200:203], v[68:71]
	v_mfma_f32_16x16x32_bf16 v[64:67], v[232:235], v[200:203], v[64:67]
	s_mov_b32 m0, s75
	v_lshl_add_u64 v[174:175], v[236:237], 0, s[40:41]
	s_barrier
	ds_read_b128 v[154:157], v165 offset:49152
	ds_read_b128 v[166:169], v165 offset:51200
	ds_read_b128 v[188:191], v165 offset:53248
	ds_read_b128 v[196:199], v165 offset:55296
	ds_read_b128 v[158:161], v165 offset:50176
	ds_read_b128 v[170:173], v165 offset:52224
	ds_read_b128 v[192:195], v165 offset:54272
	ds_read_b128 v[200:203], v165 offset:56320
	global_load_lds_dwordx4 v[174:175], off
	v_lshl_add_u64 v[174:175], v[238:239], 0, s[40:41]
	s_mov_b32 m0, s76
	s_nop 0
	global_load_lds_dwordx4 v[174:175], off
	s_barrier
	s_waitcnt lgkmcnt(7)
	v_mfma_f32_16x16x32_bf16 v[60:63], v[128:131], v[154:157], v[60:63]
	v_mfma_f32_16x16x32_bf16 v[56:59], v[136:139], v[154:157], v[56:59]
	s_waitcnt lgkmcnt(6)
	s_nop 0
	v_mfma_f32_16x16x32_bf16 v[44:47], v[128:131], v[166:169], v[44:47]
	v_mfma_f32_16x16x32_bf16 v[40:43], v[136:139], v[166:169], v[40:43]
	s_waitcnt lgkmcnt(5)
	s_nop 0
	v_mfma_f32_16x16x32_bf16 v[28:31], v[128:131], v[188:191], v[28:31]
	v_mfma_f32_16x16x32_bf16 v[24:27], v[136:139], v[188:191], v[24:27]
	s_waitcnt lgkmcnt(4)
	s_nop 0
	v_mfma_f32_16x16x32_bf16 v[12:15], v[128:131], v[196:199], v[12:15]
	v_mfma_f32_16x16x32_bf16 v[8:11], v[136:139], v[196:199], v[8:11]
	s_waitcnt lgkmcnt(3)
	s_nop 0
	v_mfma_f32_16x16x32_bf16 v[60:63], v[132:135], v[158:161], v[60:63]
	v_mfma_f32_16x16x32_bf16 v[56:59], v[140:143], v[158:161], v[56:59]
	s_waitcnt lgkmcnt(2)
	s_nop 0
	v_mfma_f32_16x16x32_bf16 v[44:47], v[132:135], v[170:173], v[44:47]
	v_mfma_f32_16x16x32_bf16 v[40:43], v[140:143], v[170:173], v[40:43]
	s_waitcnt lgkmcnt(1)
	s_nop 0
	v_mfma_f32_16x16x32_bf16 v[28:31], v[132:135], v[192:195], v[28:31]
	v_mfma_f32_16x16x32_bf16 v[24:27], v[140:143], v[192:195], v[24:27]
	s_waitcnt lgkmcnt(0)
	s_nop 0
	v_mfma_f32_16x16x32_bf16 v[12:15], v[132:135], v[200:203], v[12:15]
	v_mfma_f32_16x16x32_bf16 v[8:11], v[140:143], v[200:203], v[8:11]
	s_barrier
	s_add_u32 s18, s62, 0x18080
	s_addc_u32 s19, s63, 0
	s_add_i32 s28, s29, s68
	s_mov_b32 m0, s28
	s_nop 0
	global_load_lds_dwordx4 v176, s[18:19]
	s_add_i32 m0, s28, 0x2000
	s_nop 0
	global_load_lds_dwordx4 v148, s[18:19]
	s_waitcnt vmcnt(6)
	s_barrier
	v_mfma_f32_16x16x32_bf16 v[52:55], v[204:207], v[154:157], v[52:55]
	v_mfma_f32_16x16x32_bf16 v[48:51], v[212:215], v[154:157], v[48:51]
	v_mfma_f32_16x16x32_bf16 v[36:39], v[204:207], v[166:169], v[36:39]
	v_mfma_f32_16x16x32_bf16 v[32:35], v[212:215], v[166:169], v[32:35]
	v_mfma_f32_16x16x32_bf16 v[20:23], v[204:207], v[188:191], v[20:23]
	v_mfma_f32_16x16x32_bf16 v[16:19], v[212:215], v[188:191], v[16:19]
	v_mfma_f32_16x16x32_bf16 v[4:7], v[204:207], v[196:199], v[4:7]
	v_mfma_f32_16x16x32_bf16 v[0:3], v[212:215], v[196:199], v[0:3]
	v_mfma_f32_16x16x32_bf16 v[52:55], v[208:211], v[158:161], v[52:55]
	v_mfma_f32_16x16x32_bf16 v[48:51], v[232:235], v[158:161], v[48:51]
	v_mfma_f32_16x16x32_bf16 v[36:39], v[208:211], v[170:173], v[36:39]
	v_mfma_f32_16x16x32_bf16 v[32:35], v[232:235], v[170:173], v[32:35]
	v_mfma_f32_16x16x32_bf16 v[20:23], v[208:211], v[192:195], v[20:23]
	v_mfma_f32_16x16x32_bf16 v[16:19], v[232:235], v[192:195], v[16:19]
	v_mfma_f32_16x16x32_bf16 v[4:7], v[208:211], v[200:203], v[4:7]
	v_mfma_f32_16x16x32_bf16 v[0:3], v[232:235], v[200:203], v[0:3]
	s_add_u32 s85, s85, 0x100
	s_addc_u32 s91, s91, 0
	s_cmp_lt_i32 vcc_lo, s67
	s_mov_b64 s[18:19], s[4:5]
	s_mov_b32 s62, vcc_lo
	s_barrier
	s_cbranch_scc1 .LBB0_413
	s_ashr_i32 s4, s66, 2
	v_mov_b32_e32 v128, v163
	v_mov_b32_e32 v166, v162
	s_cmp_eq_u32 s4, 2
	s_cbranch_scc1 .LBB0_416
	s_mul_i32 s13, s4, 0x2280000
	s_mul_hi_i32 s5, s4, 0x2280000
	s_add_u32 s18, s13, 0x5858000
	s_addc_u32 s19, s5, 0
	s_mov_b32 s62, 1.0
	s_branch .LBB0_417

.LBB0_505:
	s_add_u32 s6, s4, 0xfff80080
	s_addc_u32 s7, s5, -1
	s_add_i32 s28, 0, 0x10000
	v_add_u32_e32 v154, s28, v144
	ds_read_b128 v[138:141], v154
	ds_read_b128 v[146:149], v154 offset:1024
	ds_read_b128 v[150:153], v154 offset:2048
	ds_read_b128 v[154:157], v154 offset:3072
	s_cmp_eq_u32 s72, 28
	s_cselect_b32 s9, s10, s7
	s_cselect_b32 s8, s11, s6
	s_cselect_b32 s7, s63, s71
	s_cselect_b32 s6, s65, s70
	s_add_i32 m0, s17, 0xc000
	ds_read_b128 v[158:161], v145
	ds_read_b128 v[166:169], v145 offset:2048
	ds_read_b128 v[188:191], v145 offset:4096
	ds_read_b128 v[196:199], v145 offset:6144
	ds_read_b128 v[162:165], v145 offset:1024
	ds_read_b128 v[170:173], v145 offset:3072
	ds_read_b128 v[192:195], v145 offset:5120
	ds_read_b128 v[200:203], v145 offset:7168
	global_load_lds_dwordx4 v134, s[4:5]
	v_lshl_add_u64 v[174:175], s[4:5], 0, v[136:137]
	s_add_i32 m0, s17, 0xe000
	s_nop 0
	global_load_lds_dwordx4 v[174:175], off
	s_waitcnt lgkmcnt(8)
	s_barrier
	s_waitcnt lgkmcnt(7)
	v_mfma_f32_16x16x32_bf16 v[124:127], v[138:141], v[158:161], v[124:127]
	v_mfma_f32_16x16x32_bf16 v[120:123], v[150:153], v[158:161], v[120:123]
	s_waitcnt lgkmcnt(6)
	s_nop 0
	v_mfma_f32_16x16x32_bf16 v[116:119], v[138:141], v[166:169], v[116:119]
	v_mfma_f32_16x16x32_bf16 v[108:111], v[150:153], v[166:169], v[108:111]
	s_waitcnt lgkmcnt(5)
	s_nop 0
	v_mfma_f32_16x16x32_bf16 v[100:103], v[138:141], v[188:191], v[100:103]
	v_mfma_f32_16x16x32_bf16 v[92:95], v[150:153], v[188:191], v[92:95]
	s_waitcnt lgkmcnt(4)
	s_nop 0
	v_mfma_f32_16x16x32_bf16 v[84:87], v[138:141], v[196:199], v[84:87]
	v_mfma_f32_16x16x32_bf16 v[76:79], v[150:153], v[196:199], v[76:79]
	s_waitcnt lgkmcnt(3)
	s_nop 0
	v_mfma_f32_16x16x32_bf16 v[124:127], v[146:149], v[162:165], v[124:127]
	v_mfma_f32_16x16x32_bf16 v[120:123], v[154:157], v[162:165], v[120:123]
	s_waitcnt lgkmcnt(2)
	s_nop 0
	v_mfma_f32_16x16x32_bf16 v[116:119], v[146:149], v[170:173], v[116:119]
	v_mfma_f32_16x16x32_bf16 v[108:111], v[154:157], v[170:173], v[108:111]
	s_waitcnt lgkmcnt(1)
	s_nop 0
	v_mfma_f32_16x16x32_bf16 v[100:103], v[146:149], v[192:195], v[100:103]
	v_mfma_f32_16x16x32_bf16 v[92:95], v[154:157], v[192:195], v[92:95]
	s_waitcnt lgkmcnt(0)
	s_nop 0
	v_mfma_f32_16x16x32_bf16 v[84:87], v[146:149], v[200:203], v[84:87]
	v_mfma_f32_16x16x32_bf16 v[76:79], v[154:157], v[200:203], v[76:79]
	s_barrier
	s_add_i32 s29, 0, 0x14000
	v_add_u32_e32 v174, s29, v144
	s_add_i32 s28, s28, s77
	ds_read_b128 v[204:207], v174
	ds_read_b128 v[208:211], v174 offset:1024
	ds_read_b128 v[212:215], v174 offset:2048
	ds_read_b128 v[232:235], v174 offset:3072
	v_lshl_add_u64 v[174:175], s[6:7], 0, v[176:177]
	s_mov_b32 m0, s28
	v_lshl_add_u64 v[216:217], s[6:7], 0, v[132:133]
	global_load_lds_dwordx4 v[174:175], off
	s_add_i32 m0, s28, 0x2000
	s_nop 0
	global_load_lds_dwordx4 v[216:217], off
	s_barrier
	s_waitcnt lgkmcnt(3)
	s_nop 0
	v_mfma_f32_16x16x32_bf16 v[112:115], v[204:207], v[158:161], v[112:115]
	s_waitcnt lgkmcnt(1)
	s_nop 0
	v_mfma_f32_16x16x32_bf16 v[104:107], v[212:215], v[158:161], v[104:107]
	v_mfma_f32_16x16x32_bf16 v[96:99], v[204:207], v[166:169], v[96:99]
	v_mfma_f32_16x16x32_bf16 v[88:91], v[212:215], v[166:169], v[88:91]
	v_mfma_f32_16x16x32_bf16 v[80:83], v[204:207], v[188:191], v[80:83]
	v_mfma_f32_16x16x32_bf16 v[72:75], v[212:215], v[188:191], v[72:75]
	v_mfma_f32_16x16x32_bf16 v[68:71], v[204:207], v[196:199], v[68:71]
	v_mfma_f32_16x16x32_bf16 v[64:67], v[212:215], v[196:199], v[64:67]
	v_mfma_f32_16x16x32_bf16 v[112:115], v[208:211], v[162:165], v[112:115]
	s_waitcnt lgkmcnt(0)
	s_nop 0
	v_mfma_f32_16x16x32_bf16 v[104:107], v[232:235], v[162:165], v[104:107]
	v_mfma_f32_16x16x32_bf16 v[96:99], v[208:211], v[170:173], v[96:99]
	v_mfma_f32_16x16x32_bf16 v[88:91], v[232:235], v[170:173], v[88:91]
	v_mfma_f32_16x16x32_bf16 v[80:83], v[208:211], v[192:195], v[80:83]
	v_mfma_f32_16x16x32_bf16 v[72:75], v[232:235], v[192:195], v[72:75]
	v_mfma_f32_16x16x32_bf16 v[68:71], v[208:211], v[200:203], v[68:71]
	v_mfma_f32_16x16x32_bf16 v[64:67], v[232:235], v[200:203], v[64:67]
	s_mov_b32 m0, s17
	v_lshl_add_u64 v[236:237], s[8:9], 0, v[128:129]
	s_barrier
	ds_read_b128 v[158:161], v145 offset:16384
	ds_read_b128 v[166:169], v145 offset:18432
	ds_read_b128 v[188:191], v145 offset:20480
	ds_read_b128 v[196:199], v145 offset:22528
	ds_read_b128 v[162:165], v145 offset:17408
	ds_read_b128 v[170:173], v145 offset:19456
	ds_read_b128 v[192:195], v145 offset:21504
	ds_read_b128 v[200:203], v145 offset:23552
	global_load_lds_dwordx4 v[236:237], off
	v_lshl_add_u64 v[238:239], s[8:9], 0, v[130:131]
	s_mov_b32 m0, s19
	s_nop 0
	global_load_lds_dwordx4 v[238:239], off
	s_barrier
	s_waitcnt lgkmcnt(7)
	v_mfma_f32_16x16x32_bf16 v[60:63], v[138:141], v[158:161], v[60:63]
	v_mfma_f32_16x16x32_bf16 v[56:59], v[150:153], v[158:161], v[56:59]
	s_waitcnt lgkmcnt(6)
	s_nop 0
	v_mfma_f32_16x16x32_bf16 v[52:55], v[138:141], v[166:169], v[52:55]
	v_mfma_f32_16x16x32_bf16 v[44:47], v[150:153], v[166:169], v[44:47]
	s_waitcnt lgkmcnt(5)
	s_nop 0
	v_mfma_f32_16x16x32_bf16 v[36:39], v[138:141], v[188:191], v[36:39]
	v_mfma_f32_16x16x32_bf16 v[28:31], v[150:153], v[188:191], v[28:31]
	s_waitcnt lgkmcnt(4)
	s_nop 0
	v_mfma_f32_16x16x32_bf16 v[20:23], v[138:141], v[196:199], v[20:23]
	v_mfma_f32_16x16x32_bf16 v[12:15], v[150:153], v[196:199], v[12:15]
	s_waitcnt lgkmcnt(3)
	s_nop 0
	v_mfma_f32_16x16x32_bf16 v[60:63], v[146:149], v[162:165], v[60:63]
	v_mfma_f32_16x16x32_bf16 v[56:59], v[154:157], v[162:165], v[56:59]
	s_waitcnt lgkmcnt(2)
	s_nop 0
	v_mfma_f32_16x16x32_bf16 v[52:55], v[146:149], v[170:173], v[52:55]
	v_mfma_f32_16x16x32_bf16 v[44:47], v[154:157], v[170:173], v[44:47]
	s_waitcnt lgkmcnt(1)
	s_nop 0
	v_mfma_f32_16x16x32_bf16 v[36:39], v[146:149], v[192:195], v[36:39]
	v_mfma_f32_16x16x32_bf16 v[28:31], v[154:157], v[192:195], v[28:31]
	s_waitcnt lgkmcnt(0)
	s_nop 0
	v_mfma_f32_16x16x32_bf16 v[20:23], v[146:149], v[200:203], v[20:23]
	v_mfma_f32_16x16x32_bf16 v[12:15], v[154:157], v[200:203], v[12:15]
	s_barrier
	s_add_u32 vcc_lo, s6, 0x80000
	s_addc_u32 vcc_hi, s7, 0
	s_add_i32 s28, s29, s77
	v_lshl_add_u64 v[138:139], vcc, 0, v[176:177]
	s_mov_b32 m0, s28
	s_nop 0
	global_load_lds_dwordx4 v[138:139], off
	v_lshl_add_u64 v[138:139], vcc, 0, v[132:133]
	s_add_i32 m0, s28, 0x2000
	s_nop 0
	global_load_lds_dwordx4 v[138:139], off
	s_waitcnt vmcnt(6)
	s_barrier
	v_mfma_f32_16x16x32_bf16 v[48:51], v[204:207], v[158:161], v[48:51]
	v_mfma_f32_16x16x32_bf16 v[40:43], v[212:215], v[158:161], v[40:43]
	v_mfma_f32_16x16x32_bf16 v[32:35], v[204:207], v[166:169], v[32:35]
	v_mfma_f32_16x16x32_bf16 v[24:27], v[212:215], v[166:169], v[24:27]
	v_mfma_f32_16x16x32_bf16 v[16:19], v[204:207], v[188:191], v[16:19]
	v_mfma_f32_16x16x32_bf16 v[8:11], v[212:215], v[188:191], v[8:11]
	v_mfma_f32_16x16x32_bf16 v[4:7], v[204:207], v[196:199], v[4:7]
	v_mfma_f32_16x16x32_bf16 v[0:3], v[212:215], v[196:199], v[0:3]
	v_mfma_f32_16x16x32_bf16 v[48:51], v[208:211], v[162:165], v[48:51]
	v_mfma_f32_16x16x32_bf16 v[40:43], v[232:235], v[162:165], v[40:43]
	v_mfma_f32_16x16x32_bf16 v[32:35], v[208:211], v[170:173], v[32:35]
	v_mfma_f32_16x16x32_bf16 v[24:27], v[232:235], v[170:173], v[24:27]
	v_mfma_f32_16x16x32_bf16 v[16:19], v[208:211], v[192:195], v[16:19]
	v_mfma_f32_16x16x32_bf16 v[8:11], v[232:235], v[192:195], v[8:11]
	v_mfma_f32_16x16x32_bf16 v[4:7], v[208:211], v[200:203], v[4:7]
	v_mfma_f32_16x16x32_bf16 v[0:3], v[232:235], v[200:203], v[0:3]
	s_add_i32 s28, 0, 0x18000
	v_add_u32_e32 v154, s28, v144
	s_barrier
	ds_read_b128 v[138:141], v154
	ds_read_b128 v[146:149], v154 offset:1024
	ds_read_b128 v[150:153], v154 offset:2048
	ds_read_b128 v[154:157], v154 offset:3072
	s_add_u32 s8, s8, 0x80000
	s_addc_u32 s9, s9, 0
	s_mov_b32 m0, s78
	ds_read_b128 v[158:161], v145 offset:32768
	ds_read_b128 v[166:169], v145 offset:34816
	ds_read_b128 v[188:191], v145 offset:36864
	ds_read_b128 v[196:199], v145 offset:38912
	ds_read_b128 v[162:165], v145 offset:33792
	ds_read_b128 v[170:173], v145 offset:35840
	ds_read_b128 v[192:195], v145 offset:37888
	ds_read_b128 v[200:203], v145 offset:39936
	global_load_lds_dwordx4 v128, s[8:9]
	s_mov_b32 m0, s79
	s_nop 0
	global_load_lds_dwordx4 v130, s[8:9]
	s_waitcnt lgkmcnt(8)
	s_barrier
	s_waitcnt lgkmcnt(7)
	s_nop 0
	v_mfma_f32_16x16x32_bf16 v[124:127], v[138:141], v[158:161], v[124:127]
	v_mfma_f32_16x16x32_bf16 v[120:123], v[150:153], v[158:161], v[120:123]
	s_waitcnt lgkmcnt(6)
	s_nop 0
	v_mfma_f32_16x16x32_bf16 v[116:119], v[138:141], v[166:169], v[116:119]
	v_mfma_f32_16x16x32_bf16 v[108:111], v[150:153], v[166:169], v[108:111]
	s_waitcnt lgkmcnt(5)
	s_nop 0
	v_mfma_f32_16x16x32_bf16 v[100:103], v[138:141], v[188:191], v[100:103]
	v_mfma_f32_16x16x32_bf16 v[92:95], v[150:153], v[188:191], v[92:95]
	s_waitcnt lgkmcnt(4)
	s_nop 0
	v_mfma_f32_16x16x32_bf16 v[84:87], v[138:141], v[196:199], v[84:87]
	v_mfma_f32_16x16x32_bf16 v[76:79], v[150:153], v[196:199], v[76:79]
	s_waitcnt lgkmcnt(3)
	s_nop 0
	v_mfma_f32_16x16x32_bf16 v[124:127], v[146:149], v[162:165], v[124:127]
	v_mfma_f32_16x16x32_bf16 v[120:123], v[154:157], v[162:165], v[120:123]
	s_waitcnt lgkmcnt(2)
	s_nop 0
	v_mfma_f32_16x16x32_bf16 v[116:119], v[146:149], v[170:173], v[116:119]
	v_mfma_f32_16x16x32_bf16 v[108:111], v[154:157], v[170:173], v[108:111]
	s_waitcnt lgkmcnt(1)
	s_nop 0
	v_mfma_f32_16x16x32_bf16 v[100:103], v[146:149], v[192:195], v[100:103]
	v_mfma_f32_16x16x32_bf16 v[92:95], v[154:157], v[192:195], v[92:95]
	s_waitcnt lgkmcnt(0)
	s_nop 0
	v_mfma_f32_16x16x32_bf16 v[84:87], v[146:149], v[200:203], v[84:87]
	v_mfma_f32_16x16x32_bf16 v[76:79], v[154:157], v[200:203], v[76:79]
	s_barrier
	s_add_i32 s8, 0, 0x1c000
	s_add_i32 s9, s28, s77
	v_add_u32_e32 v232, s8, v144
	v_lshl_add_u64 v[174:175], v[174:175], 0, s[40:41]
	s_mov_b32 m0, s9
	ds_read_b128 v[204:207], v232
	ds_read_b128 v[208:211], v232 offset:1024
	ds_read_b128 v[212:215], v232 offset:2048
	ds_read_b128 v[232:235], v232 offset:3072
	global_load_lds_dwordx4 v[174:175], off
	v_lshl_add_u64 v[174:175], v[216:217], 0, s[40:41]
	s_add_i32 m0, s9, 0x2000
	s_nop 0
	global_load_lds_dwordx4 v[174:175], off
	s_barrier
	s_waitcnt lgkmcnt(3)
	s_nop 0
	v_mfma_f32_16x16x32_bf16 v[112:115], v[204:207], v[158:161], v[112:115]
	s_waitcnt lgkmcnt(1)
	s_nop 0
	v_mfma_f32_16x16x32_bf16 v[104:107], v[212:215], v[158:161], v[104:107]
	v_mfma_f32_16x16x32_bf16 v[96:99], v[204:207], v[166:169], v[96:99]
	v_mfma_f32_16x16x32_bf16 v[88:91], v[212:215], v[166:169], v[88:91]
	v_mfma_f32_16x16x32_bf16 v[80:83], v[204:207], v[188:191], v[80:83]
	v_mfma_f32_16x16x32_bf16 v[72:75], v[212:215], v[188:191], v[72:75]
	v_mfma_f32_16x16x32_bf16 v[68:71], v[204:207], v[196:199], v[68:71]
	v_mfma_f32_16x16x32_bf16 v[64:67], v[212:215], v[196:199], v[64:67]
	v_mfma_f32_16x16x32_bf16 v[112:115], v[208:211], v[162:165], v[112:115]
	s_waitcnt lgkmcnt(0)
	s_nop 0
	v_mfma_f32_16x16x32_bf16 v[104:107], v[232:235], v[162:165], v[104:107]
	v_mfma_f32_16x16x32_bf16 v[96:99], v[208:211], v[170:173], v[96:99]
	v_mfma_f32_16x16x32_bf16 v[88:91], v[232:235], v[170:173], v[88:91]
	v_mfma_f32_16x16x32_bf16 v[80:83], v[208:211], v[192:195], v[80:83]
	v_mfma_f32_16x16x32_bf16 v[72:75], v[232:235], v[192:195], v[72:75]
	v_mfma_f32_16x16x32_bf16 v[68:71], v[208:211], v[200:203], v[68:71]
	v_mfma_f32_16x16x32_bf16 v[64:67], v[232:235], v[200:203], v[64:67]
	s_mov_b32 m0, s82
	v_lshl_add_u64 v[174:175], v[236:237], 0, s[40:41]
	s_barrier
	ds_read_b128 v[158:161], v145 offset:49152
	ds_read_b128 v[166:169], v145 offset:51200
	ds_read_b128 v[188:191], v145 offset:53248
	ds_read_b128 v[196:199], v145 offset:55296
	ds_read_b128 v[162:165], v145 offset:50176
	ds_read_b128 v[170:173], v145 offset:52224
	ds_read_b128 v[192:195], v145 offset:54272
	ds_read_b128 v[200:203], v145 offset:56320
	global_load_lds_dwordx4 v[174:175], off
	v_lshl_add_u64 v[174:175], v[238:239], 0, s[40:41]
	s_mov_b32 m0, s83
	s_nop 0
	global_load_lds_dwordx4 v[174:175], off
	s_barrier
	s_waitcnt lgkmcnt(7)
	v_mfma_f32_16x16x32_bf16 v[60:63], v[138:141], v[158:161], v[60:63]
	v_mfma_f32_16x16x32_bf16 v[56:59], v[150:153], v[158:161], v[56:59]
	s_waitcnt lgkmcnt(6)
	s_nop 0
	v_mfma_f32_16x16x32_bf16 v[52:55], v[138:141], v[166:169], v[52:55]
	v_mfma_f32_16x16x32_bf16 v[44:47], v[150:153], v[166:169], v[44:47]
	s_waitcnt lgkmcnt(5)
	s_nop 0
	v_mfma_f32_16x16x32_bf16 v[36:39], v[138:141], v[188:191], v[36:39]
	v_mfma_f32_16x16x32_bf16 v[28:31], v[150:153], v[188:191], v[28:31]
	s_waitcnt lgkmcnt(4)
	s_nop 0
	v_mfma_f32_16x16x32_bf16 v[20:23], v[138:141], v[196:199], v[20:23]
	v_mfma_f32_16x16x32_bf16 v[12:15], v[150:153], v[196:199], v[12:15]
	s_waitcnt lgkmcnt(3)
	s_nop 0
	v_mfma_f32_16x16x32_bf16 v[60:63], v[146:149], v[162:165], v[60:63]
	v_mfma_f32_16x16x32_bf16 v[56:59], v[154:157], v[162:165], v[56:59]
	s_waitcnt lgkmcnt(2)
	s_nop 0
	v_mfma_f32_16x16x32_bf16 v[52:55], v[146:149], v[170:173], v[52:55]
	v_mfma_f32_16x16x32_bf16 v[44:47], v[154:157], v[170:173], v[44:47]
	s_waitcnt lgkmcnt(1)
	s_nop 0
	v_mfma_f32_16x16x32_bf16 v[36:39], v[146:149], v[192:195], v[36:39]
	v_mfma_f32_16x16x32_bf16 v[28:31], v[154:157], v[192:195], v[28:31]
	s_waitcnt lgkmcnt(0)
	s_nop 0
	v_mfma_f32_16x16x32_bf16 v[20:23], v[146:149], v[200:203], v[20:23]
	v_mfma_f32_16x16x32_bf16 v[12:15], v[154:157], v[200:203], v[12:15]
	s_barrier
	s_add_u32 s6, s6, 0x80080
	s_addc_u32 s7, s7, 0
	s_add_i32 s8, s8, s77
	s_mov_b32 m0, s8
	s_nop 0
	global_load_lds_dwordx4 v176, s[6:7]
	s_add_i32 m0, s8, 0x2000
	s_nop 0
	global_load_lds_dwordx4 v132, s[6:7]
	s_waitcnt vmcnt(6)
	s_barrier
	v_mfma_f32_16x16x32_bf16 v[48:51], v[204:207], v[158:161], v[48:51]
	v_mfma_f32_16x16x32_bf16 v[40:43], v[212:215], v[158:161], v[40:43]
	v_mfma_f32_16x16x32_bf16 v[32:35], v[204:207], v[166:169], v[32:35]
	v_mfma_f32_16x16x32_bf16 v[24:27], v[212:215], v[166:169], v[24:27]
	v_mfma_f32_16x16x32_bf16 v[16:19], v[204:207], v[188:191], v[16:19]
	v_mfma_f32_16x16x32_bf16 v[8:11], v[212:215], v[188:191], v[8:11]
	v_mfma_f32_16x16x32_bf16 v[4:7], v[204:207], v[196:199], v[4:7]
	v_mfma_f32_16x16x32_bf16 v[0:3], v[212:215], v[196:199], v[0:3]
	v_mfma_f32_16x16x32_bf16 v[48:51], v[208:211], v[162:165], v[48:51]
	v_mfma_f32_16x16x32_bf16 v[40:43], v[232:235], v[162:165], v[40:43]
	v_mfma_f32_16x16x32_bf16 v[32:35], v[208:211], v[170:173], v[32:35]
	v_mfma_f32_16x16x32_bf16 v[24:27], v[232:235], v[170:173], v[24:27]
	v_mfma_f32_16x16x32_bf16 v[16:19], v[208:211], v[192:195], v[16:19]
	v_mfma_f32_16x16x32_bf16 v[8:11], v[232:235], v[192:195], v[8:11]
	v_mfma_f32_16x16x32_bf16 v[4:7], v[208:211], v[200:203], v[4:7]
	v_mfma_f32_16x16x32_bf16 v[0:3], v[232:235], v[200:203], v[0:3]
	s_add_i32 s72, s72, 2
	s_add_u32 s4, s4, 0x100
	s_addc_u32 s5, s5, 0
	s_add_u32 s70, s70, 0x100
	s_addc_u32 s71, s71, 0
	s_cmp_lt_u32 s72, 30
	s_barrier
	s_cbranch_scc1 .LBB0_505
	v_mov_b32_e32 v147, v142
	v_mov_b32_e32 v146, v143
	s_cmp_lt_i32 s16, 12
	s_mov_b64 s[4:5], -1
	s_cbranch_scc1 .LBB0_1052
	s_lshl_b32 s4, s18, 8
	s_add_i32 s4, s4, s80
	v_add_u32_e32 v149, s4, v147
	s_lshl_b32 s4, s16, 8
	s_add_i32 s4, s84, s4
	v_lshl_add_u32 v138, v146, 3, s4
	v_mad_i64_i32 v[140:141], s[4:5], v149, s97, 0
	v_cmp_gt_i32_e32 vcc, s34, v138
	s_and_saveexec_b64 s[10:11], vcc
	s_cbranch_execz .LBB0_541
	v_cmp_lt_i32_e64 s[8:9], 63, v138
	v_cmp_gt_u32_e64 s[4:5], s93, v138
	v_cmp_gt_u32_e64 s[6:7], s96, v138
	s_and_saveexec_b64 s[70:71], s[8:9]
	s_xor_b64 s[70:71], exec, s[70:71]
	s_cbranch_execz .LBB0_510
	v_mul_f32_e32 v139, 0xbfb8aa3b, v124
	v_exp_f32_e32 v139, v139
	s_nop 0
	v_add_f32_e32 v139, 1.0, v139
	v_rcp_f32_e32 v139, v139
	s_nop 0
	v_cndmask_b32_e64 v139, 0, v139, s[6:7]
	v_cndmask_b32_e64 v139, v139, v124, s[4:5]
	s_andn2_saveexec_b64 s[70:71], s[70:71]
	s_cbranch_execz .LBB0_512
	s_branch .LBB0_511

.LBB0_1114:
	s_add_i32 vcc_hi, s66, 2
	s_add_u32 s28, s64, 0x80
	s_addc_u32 s29, s65, 0
	s_add_i32 s88, 0, 0x10000
	v_add_u32_e32 v140, s88, v194
	ds_read_b128 v[128:131], v140
	ds_read_b128 v[132:135], v140 offset:1024
	ds_read_b128 v[136:139], v140 offset:2048
	ds_read_b128 v[140:143], v140 offset:3072
	s_cmp_eq_u32 s85, s66
	s_cselect_b32 s66, s4, s28
	s_cselect_b32 s67, s5, s29
	s_cselect_b32 s69, s7, vcc_lo
	s_cselect_b32 s68, s6, s91
	s_add_i32 m0, s70, 0xc000
	ds_read_b128 v[144:147], v195
	ds_read_b128 v[162:165], v195 offset:2048
	ds_read_b128 v[170:173], v195 offset:4096
	ds_read_b128 v[196:199], v195 offset:6144
	ds_read_b128 v[148:151], v195 offset:1024
	ds_read_b128 v[166:169], v195 offset:3072
	ds_read_b128 v[188:191], v195 offset:5120
	ds_read_b128 v[200:203], v195 offset:7168
	global_load_lds_dwordx4 v158, s[64:65]
	v_lshl_add_u64 v[174:175], s[64:65], 0, v[160:161]
	s_add_i32 m0, s70, 0xe000
	s_nop 0
	global_load_lds_dwordx4 v[174:175], off
	s_waitcnt lgkmcnt(8)
	s_barrier
	s_waitcnt lgkmcnt(7)
	s_nop 0
	v_mfma_f32_16x16x32_bf16 v[124:127], v[128:131], v[144:147], v[124:127]
	v_mfma_f32_16x16x32_bf16 v[120:123], v[136:139], v[144:147], v[120:123]
	s_waitcnt lgkmcnt(6)
	s_nop 0
	v_mfma_f32_16x16x32_bf16 v[108:111], v[128:131], v[162:165], v[108:111]
	v_mfma_f32_16x16x32_bf16 v[104:107], v[136:139], v[162:165], v[104:107]
	s_waitcnt lgkmcnt(5)
	s_nop 0
	v_mfma_f32_16x16x32_bf16 v[92:95], v[128:131], v[170:173], v[92:95]
	v_mfma_f32_16x16x32_bf16 v[88:91], v[136:139], v[170:173], v[88:91]
	s_waitcnt lgkmcnt(4)
	s_nop 0
	v_mfma_f32_16x16x32_bf16 v[76:79], v[128:131], v[196:199], v[76:79]
	v_mfma_f32_16x16x32_bf16 v[72:75], v[136:139], v[196:199], v[72:75]
	s_waitcnt lgkmcnt(3)
	s_nop 0
	v_mfma_f32_16x16x32_bf16 v[124:127], v[132:135], v[148:151], v[124:127]
	v_mfma_f32_16x16x32_bf16 v[120:123], v[140:143], v[148:151], v[120:123]
	s_waitcnt lgkmcnt(2)
	s_nop 0
	v_mfma_f32_16x16x32_bf16 v[108:111], v[132:135], v[166:169], v[108:111]
	v_mfma_f32_16x16x32_bf16 v[104:107], v[140:143], v[166:169], v[104:107]
	s_waitcnt lgkmcnt(1)
	s_nop 0
	v_mfma_f32_16x16x32_bf16 v[92:95], v[132:135], v[188:191], v[92:95]
	v_mfma_f32_16x16x32_bf16 v[88:91], v[140:143], v[188:191], v[88:91]
	s_waitcnt lgkmcnt(0)
	s_nop 0
	v_mfma_f32_16x16x32_bf16 v[76:79], v[132:135], v[200:203], v[76:79]
	v_mfma_f32_16x16x32_bf16 v[72:75], v[140:143], v[200:203], v[72:75]
	s_barrier
	s_add_i32 s28, 0, 0x14000
	v_add_u32_e32 v174, s28, v194
	s_add_i32 s29, s88, s47
	ds_read_b128 v[204:207], v174
	ds_read_b128 v[208:211], v174 offset:1024
	ds_read_b128 v[212:215], v174 offset:2048
	ds_read_b128 v[232:235], v174 offset:3072
	v_lshl_add_u64 v[174:175], s[68:69], 0, v[176:177]
	s_mov_b32 m0, s29
	v_lshl_add_u64 v[216:217], s[68:69], 0, v[156:157]
	global_load_lds_dwordx4 v[174:175], off
	s_add_i32 m0, s29, 0x2000
	s_nop 0
	global_load_lds_dwordx4 v[216:217], off
	s_barrier
	s_waitcnt lgkmcnt(3)
	s_nop 0
	v_mfma_f32_16x16x32_bf16 v[116:119], v[204:207], v[144:147], v[116:119]
	s_waitcnt lgkmcnt(1)
	s_nop 0
	v_mfma_f32_16x16x32_bf16 v[112:115], v[212:215], v[144:147], v[112:115]
	v_mfma_f32_16x16x32_bf16 v[100:103], v[204:207], v[162:165], v[100:103]
	v_mfma_f32_16x16x32_bf16 v[96:99], v[212:215], v[162:165], v[96:99]
	v_mfma_f32_16x16x32_bf16 v[84:87], v[204:207], v[170:173], v[84:87]
	v_mfma_f32_16x16x32_bf16 v[80:83], v[212:215], v[170:173], v[80:83]
	v_mfma_f32_16x16x32_bf16 v[68:71], v[204:207], v[196:199], v[68:71]
	v_mfma_f32_16x16x32_bf16 v[64:67], v[212:215], v[196:199], v[64:67]
	v_mfma_f32_16x16x32_bf16 v[116:119], v[208:211], v[148:151], v[116:119]
	s_waitcnt lgkmcnt(0)
	s_nop 0
	v_mfma_f32_16x16x32_bf16 v[112:115], v[232:235], v[148:151], v[112:115]
	v_mfma_f32_16x16x32_bf16 v[100:103], v[208:211], v[166:169], v[100:103]
	v_mfma_f32_16x16x32_bf16 v[96:99], v[232:235], v[166:169], v[96:99]
	v_mfma_f32_16x16x32_bf16 v[84:87], v[208:211], v[188:191], v[84:87]
	v_mfma_f32_16x16x32_bf16 v[80:83], v[232:235], v[188:191], v[80:83]
	v_mfma_f32_16x16x32_bf16 v[68:71], v[208:211], v[200:203], v[68:71]
	v_mfma_f32_16x16x32_bf16 v[64:67], v[232:235], v[200:203], v[64:67]
	s_mov_b32 m0, s70
	v_lshl_add_u64 v[236:237], s[66:67], 0, v[152:153]
	s_barrier
	ds_read_b128 v[144:147], v195 offset:16384
	ds_read_b128 v[162:165], v195 offset:18432
	ds_read_b128 v[170:173], v195 offset:20480
	ds_read_b128 v[196:199], v195 offset:22528
	ds_read_b128 v[148:151], v195 offset:17408
	ds_read_b128 v[166:169], v195 offset:19456
	ds_read_b128 v[188:191], v195 offset:21504
	ds_read_b128 v[200:203], v195 offset:23552
	global_load_lds_dwordx4 v[236:237], off
	v_lshl_add_u64 v[238:239], s[66:67], 0, v[154:155]
	s_mov_b32 m0, s71
	s_nop 0
	global_load_lds_dwordx4 v[238:239], off
	s_barrier
	s_waitcnt lgkmcnt(7)
	v_mfma_f32_16x16x32_bf16 v[60:63], v[128:131], v[144:147], v[60:63]
	v_mfma_f32_16x16x32_bf16 v[56:59], v[136:139], v[144:147], v[56:59]
	s_waitcnt lgkmcnt(6)
	s_nop 0
	v_mfma_f32_16x16x32_bf16 v[44:47], v[128:131], v[162:165], v[44:47]
	v_mfma_f32_16x16x32_bf16 v[40:43], v[136:139], v[162:165], v[40:43]
	s_waitcnt lgkmcnt(5)
	s_nop 0
	v_mfma_f32_16x16x32_bf16 v[28:31], v[128:131], v[170:173], v[28:31]
	v_mfma_f32_16x16x32_bf16 v[24:27], v[136:139], v[170:173], v[24:27]
	s_waitcnt lgkmcnt(4)
	s_nop 0
	v_mfma_f32_16x16x32_bf16 v[12:15], v[128:131], v[196:199], v[12:15]
	v_mfma_f32_16x16x32_bf16 v[8:11], v[136:139], v[196:199], v[8:11]
	s_waitcnt lgkmcnt(3)
	s_nop 0
	v_mfma_f32_16x16x32_bf16 v[60:63], v[132:135], v[148:151], v[60:63]
	v_mfma_f32_16x16x32_bf16 v[56:59], v[140:143], v[148:151], v[56:59]
	s_waitcnt lgkmcnt(2)
	s_nop 0
	v_mfma_f32_16x16x32_bf16 v[44:47], v[132:135], v[166:169], v[44:47]
	v_mfma_f32_16x16x32_bf16 v[40:43], v[140:143], v[166:169], v[40:43]
	s_waitcnt lgkmcnt(1)
	s_nop 0
	v_mfma_f32_16x16x32_bf16 v[28:31], v[132:135], v[188:191], v[28:31]
	v_mfma_f32_16x16x32_bf16 v[24:27], v[140:143], v[188:191], v[24:27]
	s_waitcnt lgkmcnt(0)
	s_nop 0
	v_mfma_f32_16x16x32_bf16 v[12:15], v[132:135], v[200:203], v[12:15]
	v_mfma_f32_16x16x32_bf16 v[8:11], v[140:143], v[200:203], v[8:11]
	s_barrier
	s_add_u32 s68, s68, s58
	s_addc_u32 s69, s69, 0
	s_add_i32 s28, s28, s47
	v_lshl_add_u64 v[240:241], s[68:69], 0, v[176:177]
	s_mov_b32 m0, s28
	v_lshl_add_u64 v[242:243], s[68:69], 0, v[156:157]
	global_load_lds_dwordx4 v[240:241], off
	s_add_i32 m0, s28, 0x2000
	s_nop 0
	global_load_lds_dwordx4 v[242:243], off
	s_waitcnt vmcnt(6)
	s_barrier
	v_mfma_f32_16x16x32_bf16 v[52:55], v[204:207], v[144:147], v[52:55]
	v_mfma_f32_16x16x32_bf16 v[48:51], v[212:215], v[144:147], v[48:51]
	v_mfma_f32_16x16x32_bf16 v[36:39], v[204:207], v[162:165], v[36:39]
	v_mfma_f32_16x16x32_bf16 v[32:35], v[212:215], v[162:165], v[32:35]
	v_mfma_f32_16x16x32_bf16 v[20:23], v[204:207], v[170:173], v[20:23]
	v_mfma_f32_16x16x32_bf16 v[16:19], v[212:215], v[170:173], v[16:19]
	v_mfma_f32_16x16x32_bf16 v[4:7], v[204:207], v[196:199], v[4:7]
	v_mfma_f32_16x16x32_bf16 v[0:3], v[212:215], v[196:199], v[0:3]
	v_mfma_f32_16x16x32_bf16 v[52:55], v[208:211], v[148:151], v[52:55]
	v_mfma_f32_16x16x32_bf16 v[48:51], v[232:235], v[148:151], v[48:51]
	v_mfma_f32_16x16x32_bf16 v[36:39], v[208:211], v[166:169], v[36:39]
	v_mfma_f32_16x16x32_bf16 v[32:35], v[232:235], v[166:169], v[32:35]
	v_mfma_f32_16x16x32_bf16 v[20:23], v[208:211], v[188:191], v[20:23]
	v_mfma_f32_16x16x32_bf16 v[16:19], v[232:235], v[188:191], v[16:19]
	v_mfma_f32_16x16x32_bf16 v[4:7], v[208:211], v[200:203], v[4:7]
	v_mfma_f32_16x16x32_bf16 v[0:3], v[232:235], v[200:203], v[0:3]
	s_add_i32 s28, 0, 0x18000
	v_add_u32_e32 v140, s28, v194
	s_barrier
	ds_read_b128 v[128:131], v140
	ds_read_b128 v[132:135], v140 offset:1024
	ds_read_b128 v[136:139], v140 offset:2048
	ds_read_b128 v[140:143], v140 offset:3072
	s_add_u32 s66, s66, s58
	s_addc_u32 s67, s67, 0
	s_mov_b32 m0, s72
	ds_read_b128 v[144:147], v195 offset:32768
	ds_read_b128 v[162:165], v195 offset:34816
	ds_read_b128 v[170:173], v195 offset:36864
	ds_read_b128 v[196:199], v195 offset:38912
	ds_read_b128 v[148:151], v195 offset:33792
	ds_read_b128 v[166:169], v195 offset:35840
	ds_read_b128 v[188:191], v195 offset:37888
	ds_read_b128 v[200:203], v195 offset:39936
	global_load_lds_dwordx4 v152, s[66:67]
	s_mov_b32 m0, s73
	s_nop 0
	global_load_lds_dwordx4 v154, s[66:67]
	s_waitcnt lgkmcnt(8)
	s_barrier
	s_waitcnt lgkmcnt(7)
	v_mfma_f32_16x16x32_bf16 v[124:127], v[128:131], v[144:147], v[124:127]
	v_mfma_f32_16x16x32_bf16 v[120:123], v[136:139], v[144:147], v[120:123]
	s_waitcnt lgkmcnt(6)
	s_nop 0
	v_mfma_f32_16x16x32_bf16 v[108:111], v[128:131], v[162:165], v[108:111]
	v_mfma_f32_16x16x32_bf16 v[104:107], v[136:139], v[162:165], v[104:107]
	s_waitcnt lgkmcnt(5)
	s_nop 0
	v_mfma_f32_16x16x32_bf16 v[92:95], v[128:131], v[170:173], v[92:95]
	v_mfma_f32_16x16x32_bf16 v[88:91], v[136:139], v[170:173], v[88:91]
	s_waitcnt lgkmcnt(4)
	s_nop 0
	v_mfma_f32_16x16x32_bf16 v[76:79], v[128:131], v[196:199], v[76:79]
	v_mfma_f32_16x16x32_bf16 v[72:75], v[136:139], v[196:199], v[72:75]
	s_waitcnt lgkmcnt(3)
	s_nop 0
	v_mfma_f32_16x16x32_bf16 v[124:127], v[132:135], v[148:151], v[124:127]
	v_mfma_f32_16x16x32_bf16 v[120:123], v[140:143], v[148:151], v[120:123]
	s_waitcnt lgkmcnt(2)
	s_nop 0
	v_mfma_f32_16x16x32_bf16 v[108:111], v[132:135], v[166:169], v[108:111]
	v_mfma_f32_16x16x32_bf16 v[104:107], v[140:143], v[166:169], v[104:107]
	s_waitcnt lgkmcnt(1)
	s_nop 0
	v_mfma_f32_16x16x32_bf16 v[92:95], v[132:135], v[188:191], v[92:95]
	v_mfma_f32_16x16x32_bf16 v[88:91], v[140:143], v[188:191], v[88:91]
	s_waitcnt lgkmcnt(0)
	s_nop 0
	v_mfma_f32_16x16x32_bf16 v[76:79], v[132:135], v[200:203], v[76:79]
	v_mfma_f32_16x16x32_bf16 v[72:75], v[140:143], v[200:203], v[72:75]
	s_barrier
	s_add_i32 s29, 0, 0x1c000
	s_add_i32 s28, s28, s47
	v_add_u32_e32 v232, s29, v194
	v_lshl_add_u64 v[174:175], v[174:175], 0, s[40:41]
	s_mov_b32 m0, s28
	ds_read_b128 v[204:207], v232
	ds_read_b128 v[208:211], v232 offset:1024
	ds_read_b128 v[212:215], v232 offset:2048
	ds_read_b128 v[232:235], v232 offset:3072
	global_load_lds_dwordx4 v[174:175], off
	v_lshl_add_u64 v[174:175], v[216:217], 0, s[40:41]
	s_add_i32 m0, s28, 0x2000
	s_nop 0
	global_load_lds_dwordx4 v[174:175], off
	s_barrier
	s_waitcnt lgkmcnt(3)
	s_nop 0
	v_mfma_f32_16x16x32_bf16 v[116:119], v[204:207], v[144:147], v[116:119]
	s_waitcnt lgkmcnt(1)
	s_nop 0
	v_mfma_f32_16x16x32_bf16 v[112:115], v[212:215], v[144:147], v[112:115]
	v_mfma_f32_16x16x32_bf16 v[100:103], v[204:207], v[162:165], v[100:103]
	v_mfma_f32_16x16x32_bf16 v[96:99], v[212:215], v[162:165], v[96:99]
	v_mfma_f32_16x16x32_bf16 v[84:87], v[204:207], v[170:173], v[84:87]
	v_mfma_f32_16x16x32_bf16 v[80:83], v[212:215], v[170:173], v[80:83]
	v_mfma_f32_16x16x32_bf16 v[68:71], v[204:207], v[196:199], v[68:71]
	v_mfma_f32_16x16x32_bf16 v[64:67], v[212:215], v[196:199], v[64:67]
	v_mfma_f32_16x16x32_bf16 v[116:119], v[208:211], v[148:151], v[116:119]
	s_waitcnt lgkmcnt(0)
	s_nop 0
	v_mfma_f32_16x16x32_bf16 v[112:115], v[232:235], v[148:151], v[112:115]
	v_mfma_f32_16x16x32_bf16 v[100:103], v[208:211], v[166:169], v[100:103]
	v_mfma_f32_16x16x32_bf16 v[96:99], v[232:235], v[166:169], v[96:99]
	v_mfma_f32_16x16x32_bf16 v[84:87], v[208:211], v[188:191], v[84:87]
	v_mfma_f32_16x16x32_bf16 v[80:83], v[232:235], v[188:191], v[80:83]
	v_mfma_f32_16x16x32_bf16 v[68:71], v[208:211], v[200:203], v[68:71]
	v_mfma_f32_16x16x32_bf16 v[64:67], v[232:235], v[200:203], v[64:67]
	s_mov_b32 m0, s74
	v_lshl_add_u64 v[174:175], v[236:237], 0, s[40:41]
	s_barrier
	ds_read_b128 v[144:147], v195 offset:49152
	ds_read_b128 v[162:165], v195 offset:51200
	ds_read_b128 v[170:173], v195 offset:53248
	ds_read_b128 v[196:199], v195 offset:55296
	ds_read_b128 v[148:151], v195 offset:50176
	ds_read_b128 v[166:169], v195 offset:52224
	ds_read_b128 v[188:191], v195 offset:54272
	ds_read_b128 v[200:203], v195 offset:56320
	global_load_lds_dwordx4 v[174:175], off
	v_lshl_add_u64 v[174:175], v[238:239], 0, s[40:41]
	s_mov_b32 m0, s75
	s_nop 0
	global_load_lds_dwordx4 v[174:175], off
	s_barrier
	s_waitcnt lgkmcnt(7)
	v_mfma_f32_16x16x32_bf16 v[60:63], v[128:131], v[144:147], v[60:63]
	v_mfma_f32_16x16x32_bf16 v[56:59], v[136:139], v[144:147], v[56:59]
	s_waitcnt lgkmcnt(6)
	s_nop 0
	v_mfma_f32_16x16x32_bf16 v[44:47], v[128:131], v[162:165], v[44:47]
	v_mfma_f32_16x16x32_bf16 v[40:43], v[136:139], v[162:165], v[40:43]
	s_waitcnt lgkmcnt(5)
	s_nop 0
	v_mfma_f32_16x16x32_bf16 v[28:31], v[128:131], v[170:173], v[28:31]
	v_mfma_f32_16x16x32_bf16 v[24:27], v[136:139], v[170:173], v[24:27]
	s_waitcnt lgkmcnt(4)
	s_nop 0
	v_mfma_f32_16x16x32_bf16 v[12:15], v[128:131], v[196:199], v[12:15]
	v_mfma_f32_16x16x32_bf16 v[8:11], v[136:139], v[196:199], v[8:11]
	s_waitcnt lgkmcnt(3)
	s_nop 0
	v_mfma_f32_16x16x32_bf16 v[60:63], v[132:135], v[148:151], v[60:63]
	v_mfma_f32_16x16x32_bf16 v[56:59], v[140:143], v[148:151], v[56:59]
	s_waitcnt lgkmcnt(2)
	s_nop 0
	v_mfma_f32_16x16x32_bf16 v[44:47], v[132:135], v[166:169], v[44:47]
	v_mfma_f32_16x16x32_bf16 v[40:43], v[140:143], v[166:169], v[40:43]
	s_waitcnt lgkmcnt(1)
	s_nop 0
	v_mfma_f32_16x16x32_bf16 v[28:31], v[132:135], v[188:191], v[28:31]
	v_mfma_f32_16x16x32_bf16 v[24:27], v[140:143], v[188:191], v[24:27]
	s_waitcnt lgkmcnt(0)
	s_nop 0
	v_mfma_f32_16x16x32_bf16 v[12:15], v[132:135], v[200:203], v[12:15]
	v_mfma_f32_16x16x32_bf16 v[8:11], v[140:143], v[200:203], v[8:11]
	s_barrier
	s_add_i32 s28, s29, s47
	v_lshl_add_u64 v[128:129], v[240:241], 0, s[40:41]
	s_mov_b32 m0, s28
	s_nop 0
	global_load_lds_dwordx4 v[128:129], off
	v_lshl_add_u64 v[128:129], v[242:243], 0, s[40:41]
	s_add_i32 m0, s28, 0x2000
	s_nop 0
	global_load_lds_dwordx4 v[128:129], off
	s_waitcnt vmcnt(6)
	s_barrier
	s_nop 0
	v_mfma_f32_16x16x32_bf16 v[52:55], v[204:207], v[144:147], v[52:55]
	v_mfma_f32_16x16x32_bf16 v[48:51], v[212:215], v[144:147], v[48:51]
	v_mfma_f32_16x16x32_bf16 v[36:39], v[204:207], v[162:165], v[36:39]
	v_mfma_f32_16x16x32_bf16 v[32:35], v[212:215], v[162:165], v[32:35]
	v_mfma_f32_16x16x32_bf16 v[20:23], v[204:207], v[170:173], v[20:23]
	v_mfma_f32_16x16x32_bf16 v[16:19], v[212:215], v[170:173], v[16:19]
	v_mfma_f32_16x16x32_bf16 v[4:7], v[204:207], v[196:199], v[4:7]
	v_mfma_f32_16x16x32_bf16 v[0:3], v[212:215], v[196:199], v[0:3]
	v_mfma_f32_16x16x32_bf16 v[52:55], v[208:211], v[148:151], v[52:55]
	v_mfma_f32_16x16x32_bf16 v[48:51], v[232:235], v[148:151], v[48:51]
	v_mfma_f32_16x16x32_bf16 v[36:39], v[208:211], v[166:169], v[36:39]
	v_mfma_f32_16x16x32_bf16 v[32:35], v[232:235], v[166:169], v[32:35]
	v_mfma_f32_16x16x32_bf16 v[20:23], v[208:211], v[188:191], v[20:23]
	v_mfma_f32_16x16x32_bf16 v[16:19], v[232:235], v[188:191], v[16:19]
	v_mfma_f32_16x16x32_bf16 v[4:7], v[208:211], v[200:203], v[4:7]
	v_mfma_f32_16x16x32_bf16 v[0:3], v[232:235], v[200:203], v[0:3]
	s_add_u32 s64, s64, 0x100
	s_addc_u32 s65, s65, 0
	s_add_u32 s91, s91, 0x100
	s_addc_u32 vcc_lo, vcc_lo, 0
	s_cmp_lt_i32 vcc_hi, s76
	s_mov_b32 s66, vcc_hi
	s_barrier
	s_cbranch_scc1 .LBB0_1114
	s_lshl_b32 s28, s84, 8
	v_mov_b32_e32 v128, v193
	v_mov_b32_e32 v129, v192
	s_add_i32 s28, s28, s78
	s_lshl_b32 s64, s24, 2
	v_add_u32_e32 v166, s28, v129
	s_lshl_b32 s28, s24, 8
	s_or_b32 s28, s28, s79
	v_lshl_add_u32 v162, v128, 3, s28
	v_ashrrev_i32_e32 v163, 31, v162
	v_lshlrev_b64 v[204:205], 1, v[162:163]
	v_ashrrev_i32_e32 v167, 31, v166
	v_lshl_add_u64 v[164:165], s[12:13], 0, v[204:205]
	v_lshlrev_b64 v[206:207], 11, v[166:167]
	v_cmp_eq_u32_e32 vcc, 0, v128
	v_lshl_add_u64 v[128:129], v[164:165], 0, v[206:207]
	global_load_dwordx4 v[196:199], v[128:129], off
	global_load_dwordx4 v[200:203], v[128:129], off offset:256
	v_add_u32_e32 v188, 16, v166
	v_ashrrev_i32_e32 v189, 31, v188
	v_add_u32_e32 v172, 32, v166
	v_lshlrev_b64 v[190:191], 11, v[188:189]
	v_ashrrev_i32_e32 v173, 31, v172
	v_add_u32_e32 v168, 48, v166
	v_lshl_add_u64 v[128:129], v[164:165], 0, v[190:191]
	v_lshlrev_b64 v[174:175], 11, v[172:173]
	v_ashrrev_i32_e32 v169, 31, v168
	global_load_dwordx4 v[148:151], v[128:129], off
	global_load_dwordx4 v[144:147], v[128:129], off offset:256
	v_lshl_add_u64 v[128:129], v[164:165], 0, v[174:175]
	v_lshlrev_b64 v[170:171], 11, v[168:169]
	global_load_dwordx4 v[140:143], v[128:129], off
	global_load_dwordx4 v[136:139], v[128:129], off offset:256
	v_lshl_add_u64 v[128:129], v[164:165], 0, v[170:171]
	global_load_dwordx4 v[132:135], v[128:129], off
	s_nop 0
	global_load_dwordx4 v[128:131], v[128:129], off offset:256
	v_lshl_add_u64 v[206:207], s[12:13], 0, v[206:207]
	v_lshl_add_u64 v[204:205], v[206:207], 0, v[204:205]
	s_ashr_i32 s65, s64, 31
	s_waitcnt vmcnt(0)
	v_lshlrev_b32_e32 v208, 16, v196
	v_and_b32_e32 v209, 0xffff0000, v196
	v_lshlrev_b32_e32 v196, 16, v197
	v_and_b32_e32 v197, 0xffff0000, v197
	v_lshlrev_b32_e32 v210, 16, v198
	v_and_b32_e32 v211, 0xffff0000, v198
	v_lshlrev_b32_e32 v198, 16, v199
	v_and_b32_e32 v199, 0xffff0000, v199
	v_pk_fma_f32 v[126:127], s[62:63], v[126:127], v[196:197]
	v_pk_fma_f32 v[124:125], s[10:11], v[124:125], v[208:209]
	v_pk_fma_f32 v[196:197], s[62:63], v[122:123], v[198:199]
	v_pk_fma_f32 v[198:199], s[10:11], v[120:121], v[210:211]
	v_cvt_pk_bf16_f32 v120, v124, v125
	v_cvt_pk_bf16_f32 v121, v126, v127
	s_nop 0
	v_cvt_pk_bf16_f32 v122, v198, v199
	v_cvt_pk_bf16_f32 v123, v196, v197
	global_store_dwordx4 v[204:205], v[120:123], off
	s_nop 1
	v_pk_mul_f32 v[120:121], v[198:199], v[198:199]
	v_pk_mul_f32 v[122:123], v[196:197], v[196:197]
	v_pk_fma_f32 v[120:121], v[124:125], v[124:125], v[120:121]
	v_pk_fma_f32 v[122:123], v[126:127], v[126:127], v[122:123]
	v_add_f32_e32 v120, v120, v121
	v_add_f32_e32 v121, v122, v123
	v_add_f32_e32 v196, v120, v121
	v_lshlrev_b32_e32 v120, 16, v200
	v_and_b32_e32 v121, 0xffff0000, v200
	v_lshlrev_b32_e32 v122, 16, v201
	v_and_b32_e32 v123, 0xffff0000, v201
	v_lshlrev_b32_e32 v124, 16, v202
	v_and_b32_e32 v125, 0xffff0000, v202
	v_lshlrev_b32_e32 v126, 16, v203
	v_and_b32_e32 v127, 0xffff0000, v203
	v_pk_fma_f32 v[118:119], s[62:63], v[118:119], v[122:123]
	v_pk_fma_f32 v[116:117], s[10:11], v[116:117], v[120:121]
	v_pk_fma_f32 v[120:121], s[62:63], v[114:115], v[126:127]
	v_pk_fma_f32 v[122:123], s[10:11], v[112:113], v[124:125]
	v_cvt_pk_bf16_f32 v112, v116, v117
	v_cvt_pk_bf16_f32 v113, v118, v119
	s_nop 0
	v_cvt_pk_bf16_f32 v114, v122, v123
	v_cvt_pk_bf16_f32 v115, v120, v121
	global_store_dwordx4 v[204:205], v[112:115], off offset:256
	s_nop 1
	v_pk_mul_f32 v[112:113], v[122:123], v[122:123]
	v_pk_mul_f32 v[114:115], v[120:121], v[120:121]
	v_pk_fma_f32 v[112:113], v[116:117], v[116:117], v[112:113]
	v_pk_fma_f32 v[114:115], v[118:119], v[118:119], v[114:115]
	v_add_f32_e32 v112, v112, v113
	v_add_f32_e32 v113, v114, v115
	v_add_f32_e32 v112, v112, v113
	v_add_f32_e32 v112, v196, v112
	ds_bpermute_b32 v113, v219, v112
	s_waitcnt lgkmcnt(0)
	v_add_f32_e32 v112, v112, v113
	ds_bpermute_b32 v113, v218, v112
	s_and_saveexec_b64 s[66:67], vcc
	s_cbranch_execz .LBB0_1117
	v_lshlrev_b64 v[114:115], 6, v[166:167]
	v_lshl_add_u64 v[114:115], s[8:9], 0, v[114:115]
	v_lshl_add_u64 v[114:115], s[64:65], 2, v[114:115]
	s_lshl_b32 s24, s77, 2
	v_lshl_add_u64 v[114:115], v[114:115], 0, s[24:25]
	s_waitcnt lgkmcnt(0)
	v_add_f32_e32 v112, v112, v113
	global_store_dword v[114:115], v112, off

.LBB0_1282:
	s_add_i32 s81, s60, 2
	s_add_u32 s28, s58, 0x80
	s_addc_u32 s29, s59, 0
	s_add_i32 s82, 0, 0x10000
	v_add_u32_e32 v140, s82, v195
	ds_read_b128 v[128:131], v140
	ds_read_b128 v[132:135], v140 offset:1024
	ds_read_b128 v[136:139], v140 offset:2048
	ds_read_b128 v[140:143], v140 offset:3072
	s_cmp_eq_u32 s5, s60
	s_cselect_b32 s60, s56, s28
	s_cselect_b32 s61, s57, s29
	s_cselect_b32 s63, s3, s80
	s_cselect_b32 s62, s2, s21
	s_add_i32 m0, s66, 0xc000
	ds_read_b128 v[144:147], v196
	ds_read_b128 v[162:165], v196 offset:2048
	ds_read_b128 v[170:173], v196 offset:4096
	ds_read_b128 v[198:201], v196 offset:6144
	ds_read_b128 v[148:151], v196 offset:1024
	ds_read_b128 v[166:169], v196 offset:3072
	ds_read_b128 v[188:191], v196 offset:5120
	ds_read_b128 v[202:205], v196 offset:7168
	global_load_lds_dwordx4 v158, s[58:59]
	v_lshl_add_u64 v[174:175], s[58:59], 0, v[160:161]
	s_add_i32 m0, s66, 0xe000
	s_nop 0
	global_load_lds_dwordx4 v[174:175], off
	s_waitcnt lgkmcnt(8)
	s_barrier
	s_waitcnt lgkmcnt(7)
	s_nop 0
	v_mfma_f32_16x16x32_bf16 v[124:127], v[128:131], v[144:147], v[124:127]
	v_mfma_f32_16x16x32_bf16 v[120:123], v[136:139], v[144:147], v[120:123]
	s_waitcnt lgkmcnt(6)
	s_nop 0
	v_mfma_f32_16x16x32_bf16 v[108:111], v[128:131], v[162:165], v[108:111]
	v_mfma_f32_16x16x32_bf16 v[104:107], v[136:139], v[162:165], v[104:107]
	s_waitcnt lgkmcnt(5)
	s_nop 0
	v_mfma_f32_16x16x32_bf16 v[92:95], v[128:131], v[170:173], v[92:95]
	v_mfma_f32_16x16x32_bf16 v[88:91], v[136:139], v[170:173], v[88:91]
	s_waitcnt lgkmcnt(4)
	s_nop 0
	v_mfma_f32_16x16x32_bf16 v[76:79], v[128:131], v[198:201], v[76:79]
	v_mfma_f32_16x16x32_bf16 v[72:75], v[136:139], v[198:201], v[72:75]
	s_waitcnt lgkmcnt(3)
	s_nop 0
	v_mfma_f32_16x16x32_bf16 v[124:127], v[132:135], v[148:151], v[124:127]
	v_mfma_f32_16x16x32_bf16 v[120:123], v[140:143], v[148:151], v[120:123]
	s_waitcnt lgkmcnt(2)
	s_nop 0
	v_mfma_f32_16x16x32_bf16 v[108:111], v[132:135], v[166:169], v[108:111]
	v_mfma_f32_16x16x32_bf16 v[104:107], v[140:143], v[166:169], v[104:107]
	s_waitcnt lgkmcnt(1)
	s_nop 0
	v_mfma_f32_16x16x32_bf16 v[92:95], v[132:135], v[188:191], v[92:95]
	v_mfma_f32_16x16x32_bf16 v[88:91], v[140:143], v[188:191], v[88:91]
	s_waitcnt lgkmcnt(0)
	s_nop 0
	v_mfma_f32_16x16x32_bf16 v[76:79], v[132:135], v[202:205], v[76:79]
	v_mfma_f32_16x16x32_bf16 v[72:75], v[140:143], v[202:205], v[72:75]
	s_barrier
	s_add_i32 s28, 0, 0x14000
	v_add_u32_e32 v174, s28, v195
	s_add_i32 s29, s82, s65
	ds_read_b128 v[206:209], v174
	ds_read_b128 v[210:213], v174 offset:1024
	ds_read_b128 v[214:217], v174 offset:2048
	ds_read_b128 v[232:235], v174 offset:3072
	v_lshl_add_u64 v[174:175], s[62:63], 0, v[176:177]
	s_mov_b32 m0, s29
	v_lshl_add_u64 v[236:237], s[62:63], 0, v[156:157]
	global_load_lds_dwordx4 v[174:175], off
	s_add_i32 m0, s29, 0x2000
	s_nop 0
	global_load_lds_dwordx4 v[236:237], off
	s_barrier
	s_waitcnt lgkmcnt(3)
	s_nop 0
	v_mfma_f32_16x16x32_bf16 v[116:119], v[206:209], v[144:147], v[116:119]
	s_waitcnt lgkmcnt(1)
	s_nop 0
	v_mfma_f32_16x16x32_bf16 v[112:115], v[214:217], v[144:147], v[112:115]
	v_mfma_f32_16x16x32_bf16 v[100:103], v[206:209], v[162:165], v[100:103]
	v_mfma_f32_16x16x32_bf16 v[96:99], v[214:217], v[162:165], v[96:99]
	v_mfma_f32_16x16x32_bf16 v[84:87], v[206:209], v[170:173], v[84:87]
	v_mfma_f32_16x16x32_bf16 v[80:83], v[214:217], v[170:173], v[80:83]
	v_mfma_f32_16x16x32_bf16 v[68:71], v[206:209], v[198:201], v[68:71]
	v_mfma_f32_16x16x32_bf16 v[64:67], v[214:217], v[198:201], v[64:67]
	v_mfma_f32_16x16x32_bf16 v[116:119], v[210:213], v[148:151], v[116:119]
	s_waitcnt lgkmcnt(0)
	s_nop 0
	v_mfma_f32_16x16x32_bf16 v[112:115], v[232:235], v[148:151], v[112:115]
	v_mfma_f32_16x16x32_bf16 v[100:103], v[210:213], v[166:169], v[100:103]
	v_mfma_f32_16x16x32_bf16 v[96:99], v[232:235], v[166:169], v[96:99]
	v_mfma_f32_16x16x32_bf16 v[84:87], v[210:213], v[188:191], v[84:87]
	v_mfma_f32_16x16x32_bf16 v[80:83], v[232:235], v[188:191], v[80:83]
	v_mfma_f32_16x16x32_bf16 v[68:71], v[210:213], v[202:205], v[68:71]
	v_mfma_f32_16x16x32_bf16 v[64:67], v[232:235], v[202:205], v[64:67]
	s_mov_b32 m0, s66
	v_lshl_add_u64 v[238:239], s[60:61], 0, v[152:153]
	s_barrier
	ds_read_b128 v[144:147], v196 offset:16384
	ds_read_b128 v[162:165], v196 offset:18432
	ds_read_b128 v[170:173], v196 offset:20480
	ds_read_b128 v[198:201], v196 offset:22528
	ds_read_b128 v[148:151], v196 offset:17408
	ds_read_b128 v[166:169], v196 offset:19456
	ds_read_b128 v[188:191], v196 offset:21504
	ds_read_b128 v[202:205], v196 offset:23552
	global_load_lds_dwordx4 v[238:239], off
	v_lshl_add_u64 v[240:241], s[60:61], 0, v[154:155]
	s_mov_b32 m0, s67
	s_nop 0
	global_load_lds_dwordx4 v[240:241], off
	s_barrier
	s_waitcnt lgkmcnt(7)
	v_mfma_f32_16x16x32_bf16 v[60:63], v[128:131], v[144:147], v[60:63]
	v_mfma_f32_16x16x32_bf16 v[56:59], v[136:139], v[144:147], v[56:59]
	s_waitcnt lgkmcnt(6)
	s_nop 0
	v_mfma_f32_16x16x32_bf16 v[44:47], v[128:131], v[162:165], v[44:47]
	v_mfma_f32_16x16x32_bf16 v[40:43], v[136:139], v[162:165], v[40:43]
	s_waitcnt lgkmcnt(5)
	s_nop 0
	v_mfma_f32_16x16x32_bf16 v[28:31], v[128:131], v[170:173], v[28:31]
	v_mfma_f32_16x16x32_bf16 v[24:27], v[136:139], v[170:173], v[24:27]
	s_waitcnt lgkmcnt(4)
	s_nop 0
	v_mfma_f32_16x16x32_bf16 v[12:15], v[128:131], v[198:201], v[12:15]
	v_mfma_f32_16x16x32_bf16 v[8:11], v[136:139], v[198:201], v[8:11]
	s_waitcnt lgkmcnt(3)
	s_nop 0
	v_mfma_f32_16x16x32_bf16 v[60:63], v[132:135], v[148:151], v[60:63]
	v_mfma_f32_16x16x32_bf16 v[56:59], v[140:143], v[148:151], v[56:59]
	s_waitcnt lgkmcnt(2)
	s_nop 0
	v_mfma_f32_16x16x32_bf16 v[44:47], v[132:135], v[166:169], v[44:47]
	v_mfma_f32_16x16x32_bf16 v[40:43], v[140:143], v[166:169], v[40:43]
	s_waitcnt lgkmcnt(1)
	s_nop 0
	v_mfma_f32_16x16x32_bf16 v[28:31], v[132:135], v[188:191], v[28:31]
	v_mfma_f32_16x16x32_bf16 v[24:27], v[140:143], v[188:191], v[24:27]
	s_waitcnt lgkmcnt(0)
	s_nop 0
	v_mfma_f32_16x16x32_bf16 v[12:15], v[132:135], v[202:205], v[12:15]
	v_mfma_f32_16x16x32_bf16 v[8:11], v[140:143], v[202:205], v[8:11]
	s_barrier
	s_add_u32 s62, s62, s4
	s_addc_u32 s63, s63, 0
	s_add_i32 s28, s28, s65
	v_lshl_add_u64 v[242:243], s[62:63], 0, v[176:177]
	s_mov_b32 m0, s28
	v_lshl_add_u64 v[244:245], s[62:63], 0, v[156:157]
	global_load_lds_dwordx4 v[242:243], off
	s_add_i32 m0, s28, 0x2000
	s_nop 0
	global_load_lds_dwordx4 v[244:245], off
	s_waitcnt vmcnt(6)
	s_barrier
	v_mfma_f32_16x16x32_bf16 v[52:55], v[206:209], v[144:147], v[52:55]
	v_mfma_f32_16x16x32_bf16 v[48:51], v[214:217], v[144:147], v[48:51]
	v_mfma_f32_16x16x32_bf16 v[36:39], v[206:209], v[162:165], v[36:39]
	v_mfma_f32_16x16x32_bf16 v[32:35], v[214:217], v[162:165], v[32:35]
	v_mfma_f32_16x16x32_bf16 v[20:23], v[206:209], v[170:173], v[20:23]
	v_mfma_f32_16x16x32_bf16 v[16:19], v[214:217], v[170:173], v[16:19]
	v_mfma_f32_16x16x32_bf16 v[4:7], v[206:209], v[198:201], v[4:7]
	v_mfma_f32_16x16x32_bf16 v[0:3], v[214:217], v[198:201], v[0:3]
	v_mfma_f32_16x16x32_bf16 v[52:55], v[210:213], v[148:151], v[52:55]
	v_mfma_f32_16x16x32_bf16 v[48:51], v[232:235], v[148:151], v[48:51]
	v_mfma_f32_16x16x32_bf16 v[36:39], v[210:213], v[166:169], v[36:39]
	v_mfma_f32_16x16x32_bf16 v[32:35], v[232:235], v[166:169], v[32:35]
	v_mfma_f32_16x16x32_bf16 v[20:23], v[210:213], v[188:191], v[20:23]
	v_mfma_f32_16x16x32_bf16 v[16:19], v[232:235], v[188:191], v[16:19]
	v_mfma_f32_16x16x32_bf16 v[4:7], v[210:213], v[202:205], v[4:7]
	v_mfma_f32_16x16x32_bf16 v[0:3], v[232:235], v[202:205], v[0:3]
	s_add_i32 s28, 0, 0x18000
	v_add_u32_e32 v140, s28, v195
	s_barrier
	ds_read_b128 v[128:131], v140
	ds_read_b128 v[132:135], v140 offset:1024
	ds_read_b128 v[136:139], v140 offset:2048
	ds_read_b128 v[140:143], v140 offset:3072
	s_add_u32 s60, s60, s4
	s_addc_u32 s61, s61, 0
	s_mov_b32 m0, s68
	ds_read_b128 v[144:147], v196 offset:32768
	ds_read_b128 v[162:165], v196 offset:34816
	ds_read_b128 v[170:173], v196 offset:36864
	ds_read_b128 v[198:201], v196 offset:38912
	ds_read_b128 v[148:151], v196 offset:33792
	ds_read_b128 v[166:169], v196 offset:35840
	ds_read_b128 v[188:191], v196 offset:37888
	ds_read_b128 v[202:205], v196 offset:39936
	global_load_lds_dwordx4 v152, s[60:61]
	s_mov_b32 m0, s69
	s_nop 0
	global_load_lds_dwordx4 v154, s[60:61]
	s_waitcnt lgkmcnt(8)
	s_barrier
	s_waitcnt lgkmcnt(7)
	v_mfma_f32_16x16x32_bf16 v[124:127], v[128:131], v[144:147], v[124:127]
	v_mfma_f32_16x16x32_bf16 v[120:123], v[136:139], v[144:147], v[120:123]
	s_waitcnt lgkmcnt(6)
	s_nop 0
	v_mfma_f32_16x16x32_bf16 v[108:111], v[128:131], v[162:165], v[108:111]
	v_mfma_f32_16x16x32_bf16 v[104:107], v[136:139], v[162:165], v[104:107]
	s_waitcnt lgkmcnt(5)
	s_nop 0
	v_mfma_f32_16x16x32_bf16 v[92:95], v[128:131], v[170:173], v[92:95]
	v_mfma_f32_16x16x32_bf16 v[88:91], v[136:139], v[170:173], v[88:91]
	s_waitcnt lgkmcnt(4)
	s_nop 0
	v_mfma_f32_16x16x32_bf16 v[76:79], v[128:131], v[198:201], v[76:79]
	v_mfma_f32_16x16x32_bf16 v[72:75], v[136:139], v[198:201], v[72:75]
	s_waitcnt lgkmcnt(3)
	s_nop 0
	v_mfma_f32_16x16x32_bf16 v[124:127], v[132:135], v[148:151], v[124:127]
	v_mfma_f32_16x16x32_bf16 v[120:123], v[140:143], v[148:151], v[120:123]
	s_waitcnt lgkmcnt(2)
	s_nop 0
	v_mfma_f32_16x16x32_bf16 v[108:111], v[132:135], v[166:169], v[108:111]
	v_mfma_f32_16x16x32_bf16 v[104:107], v[140:143], v[166:169], v[104:107]
	s_waitcnt lgkmcnt(1)
	s_nop 0
	v_mfma_f32_16x16x32_bf16 v[92:95], v[132:135], v[188:191], v[92:95]
	v_mfma_f32_16x16x32_bf16 v[88:91], v[140:143], v[188:191], v[88:91]
	s_waitcnt lgkmcnt(0)
	s_nop 0
	v_mfma_f32_16x16x32_bf16 v[76:79], v[132:135], v[202:205], v[76:79]
	v_mfma_f32_16x16x32_bf16 v[72:75], v[140:143], v[202:205], v[72:75]
	s_barrier
	s_add_i32 s29, 0, 0x1c000
	s_add_i32 s28, s28, s65
	v_add_u32_e32 v197, s29, v195
	v_lshl_add_u64 v[174:175], v[174:175], 0, s[40:41]
	s_mov_b32 m0, s28
	ds_read_b128 v[206:209], v197
	ds_read_b128 v[210:213], v197 offset:1024
	ds_read_b128 v[214:217], v197 offset:2048
	ds_read_b128 v[232:235], v197 offset:3072
	global_load_lds_dwordx4 v[174:175], off
	v_lshl_add_u64 v[174:175], v[236:237], 0, s[40:41]
	s_add_i32 m0, s28, 0x2000
	s_nop 0
	global_load_lds_dwordx4 v[174:175], off
	s_barrier
	s_waitcnt lgkmcnt(3)
	s_nop 0
	v_mfma_f32_16x16x32_bf16 v[116:119], v[206:209], v[144:147], v[116:119]
	s_waitcnt lgkmcnt(1)
	s_nop 0
	v_mfma_f32_16x16x32_bf16 v[112:115], v[214:217], v[144:147], v[112:115]
	v_mfma_f32_16x16x32_bf16 v[100:103], v[206:209], v[162:165], v[100:103]
	v_mfma_f32_16x16x32_bf16 v[96:99], v[214:217], v[162:165], v[96:99]
	v_mfma_f32_16x16x32_bf16 v[84:87], v[206:209], v[170:173], v[84:87]
	v_mfma_f32_16x16x32_bf16 v[80:83], v[214:217], v[170:173], v[80:83]
	v_mfma_f32_16x16x32_bf16 v[68:71], v[206:209], v[198:201], v[68:71]
	v_mfma_f32_16x16x32_bf16 v[64:67], v[214:217], v[198:201], v[64:67]
	v_mfma_f32_16x16x32_bf16 v[116:119], v[210:213], v[148:151], v[116:119]
	s_waitcnt lgkmcnt(0)
	s_nop 0
	v_mfma_f32_16x16x32_bf16 v[112:115], v[232:235], v[148:151], v[112:115]
	v_mfma_f32_16x16x32_bf16 v[100:103], v[210:213], v[166:169], v[100:103]
	v_mfma_f32_16x16x32_bf16 v[96:99], v[232:235], v[166:169], v[96:99]
	v_mfma_f32_16x16x32_bf16 v[84:87], v[210:213], v[188:191], v[84:87]
	v_mfma_f32_16x16x32_bf16 v[80:83], v[232:235], v[188:191], v[80:83]
	v_mfma_f32_16x16x32_bf16 v[68:71], v[210:213], v[202:205], v[68:71]
	v_mfma_f32_16x16x32_bf16 v[64:67], v[232:235], v[202:205], v[64:67]
	s_mov_b32 m0, s71
	v_lshl_add_u64 v[174:175], v[238:239], 0, s[40:41]
	s_barrier
	ds_read_b128 v[144:147], v196 offset:49152
	ds_read_b128 v[162:165], v196 offset:51200
	ds_read_b128 v[170:173], v196 offset:53248
	ds_read_b128 v[198:201], v196 offset:55296
	ds_read_b128 v[148:151], v196 offset:50176
	ds_read_b128 v[166:169], v196 offset:52224
	ds_read_b128 v[188:191], v196 offset:54272
	ds_read_b128 v[202:205], v196 offset:56320
	global_load_lds_dwordx4 v[174:175], off
	v_lshl_add_u64 v[174:175], v[240:241], 0, s[40:41]
	s_mov_b32 m0, s72
	s_nop 0
	global_load_lds_dwordx4 v[174:175], off
	s_barrier
	s_waitcnt lgkmcnt(7)
	v_mfma_f32_16x16x32_bf16 v[60:63], v[128:131], v[144:147], v[60:63]
	v_mfma_f32_16x16x32_bf16 v[56:59], v[136:139], v[144:147], v[56:59]
	s_waitcnt lgkmcnt(6)
	s_nop 0
	v_mfma_f32_16x16x32_bf16 v[44:47], v[128:131], v[162:165], v[44:47]
	v_mfma_f32_16x16x32_bf16 v[40:43], v[136:139], v[162:165], v[40:43]
	s_waitcnt lgkmcnt(5)
	s_nop 0
	v_mfma_f32_16x16x32_bf16 v[28:31], v[128:131], v[170:173], v[28:31]
	v_mfma_f32_16x16x32_bf16 v[24:27], v[136:139], v[170:173], v[24:27]
	s_waitcnt lgkmcnt(4)
	s_nop 0
	v_mfma_f32_16x16x32_bf16 v[12:15], v[128:131], v[198:201], v[12:15]
	v_mfma_f32_16x16x32_bf16 v[8:11], v[136:139], v[198:201], v[8:11]
	s_waitcnt lgkmcnt(3)
	s_nop 0
	v_mfma_f32_16x16x32_bf16 v[60:63], v[132:135], v[148:151], v[60:63]
	v_mfma_f32_16x16x32_bf16 v[56:59], v[140:143], v[148:151], v[56:59]
	s_waitcnt lgkmcnt(2)
	s_nop 0
	v_mfma_f32_16x16x32_bf16 v[44:47], v[132:135], v[166:169], v[44:47]
	v_mfma_f32_16x16x32_bf16 v[40:43], v[140:143], v[166:169], v[40:43]
	s_waitcnt lgkmcnt(1)
	s_nop 0
	v_mfma_f32_16x16x32_bf16 v[28:31], v[132:135], v[188:191], v[28:31]
	v_mfma_f32_16x16x32_bf16 v[24:27], v[140:143], v[188:191], v[24:27]
	s_waitcnt lgkmcnt(0)
	s_nop 0
	v_mfma_f32_16x16x32_bf16 v[12:15], v[132:135], v[202:205], v[12:15]
	v_mfma_f32_16x16x32_bf16 v[8:11], v[140:143], v[202:205], v[8:11]
	s_barrier
	s_add_i32 s28, s29, s65
	v_lshl_add_u64 v[128:129], v[242:243], 0, s[40:41]
	s_mov_b32 m0, s28
	s_nop 0
	global_load_lds_dwordx4 v[128:129], off
	v_lshl_add_u64 v[128:129], v[244:245], 0, s[40:41]
	s_add_i32 m0, s28, 0x2000
	s_nop 0
	global_load_lds_dwordx4 v[128:129], off
	s_waitcnt vmcnt(6)
	s_barrier
	s_nop 0
	v_mfma_f32_16x16x32_bf16 v[52:55], v[206:209], v[144:147], v[52:55]
	v_mfma_f32_16x16x32_bf16 v[48:51], v[214:217], v[144:147], v[48:51]
	v_mfma_f32_16x16x32_bf16 v[36:39], v[206:209], v[162:165], v[36:39]
	v_mfma_f32_16x16x32_bf16 v[32:35], v[214:217], v[162:165], v[32:35]
	v_mfma_f32_16x16x32_bf16 v[20:23], v[206:209], v[170:173], v[20:23]
	v_mfma_f32_16x16x32_bf16 v[16:19], v[214:217], v[170:173], v[16:19]
	v_mfma_f32_16x16x32_bf16 v[4:7], v[206:209], v[198:201], v[4:7]
	v_mfma_f32_16x16x32_bf16 v[0:3], v[214:217], v[198:201], v[0:3]
	v_mfma_f32_16x16x32_bf16 v[52:55], v[210:213], v[148:151], v[52:55]
	v_mfma_f32_16x16x32_bf16 v[48:51], v[232:235], v[148:151], v[48:51]
	v_mfma_f32_16x16x32_bf16 v[36:39], v[210:213], v[166:169], v[36:39]
	v_mfma_f32_16x16x32_bf16 v[32:35], v[232:235], v[166:169], v[32:35]
	v_mfma_f32_16x16x32_bf16 v[20:23], v[210:213], v[188:191], v[20:23]
	v_mfma_f32_16x16x32_bf16 v[16:19], v[232:235], v[188:191], v[16:19]
	v_mfma_f32_16x16x32_bf16 v[4:7], v[210:213], v[202:205], v[4:7]
	v_mfma_f32_16x16x32_bf16 v[0:3], v[232:235], v[202:205], v[0:3]
	s_add_u32 s58, s58, 0x100
	s_addc_u32 s59, s59, 0
	s_add_u32 s21, s21, 0x100
	s_addc_u32 s80, s80, 0
	s_cmp_ge_i32 s81, s79
	s_mov_b32 s60, s81
	s_barrier
	s_cbranch_scc0 .LBB0_1282
	s_cmp_gt_i32 s24, -1
	s_mov_b64 s[58:59], -1
	s_cbranch_scc0 .LBB0_1285
	s_lshl_b64 s[58:59], s[24:25], 17
	v_mov_b32_e32 v128, v231
	s_add_u32 s58, s37, s58
	s_addc_u32 s59, s46, s59
	v_ashrrev_i32_e32 v129, 31, v128
	v_lshl_add_u64 v[128:129], v[128:129], 4, s[58:59]
	v_add_co_u32_e32 v134, vcc, s36, v128
	v_cvt_pk_bf16_f32 v130, v124, v125
	v_cvt_pk_bf16_f32 v131, v126, v127
	v_cvt_pk_bf16_f32 v132, v120, v121
	v_cvt_pk_bf16_f32 v133, v122, v123
	s_nop 1
	v_addc_co_u32_e32 v135, vcc, 0, v129, vcc
	s_movk_i32 s5, 0x4000
	global_store_dwordx4 v[128:129], v[130:133], off
	s_mov_b64 s[58:59], 0
	s_nop 0
	v_cvt_pk_bf16_f32 v130, v108, v109
	v_cvt_pk_bf16_f32 v131, v110, v111
	v_cvt_pk_bf16_f32 v132, v104, v105
	v_cvt_pk_bf16_f32 v133, v106, v107
	global_store_dwordx4 v[134:135], v[130:133], off
	v_add_co_u32_e32 v134, vcc, s5, v128
	s_movk_i32 s5, 0x6000
	s_nop 0
	v_addc_co_u32_e32 v135, vcc, 0, v129, vcc
	v_cvt_pk_bf16_f32 v130, v92, v93
	v_cvt_pk_bf16_f32 v131, v94, v95
	v_cvt_pk_bf16_f32 v132, v88, v89
	v_cvt_pk_bf16_f32 v133, v90, v91
	global_store_dwordx4 v[134:135], v[130:133], off
	v_add_co_u32_e32 v134, vcc, s5, v128
	s_nop 0
	v_cvt_pk_bf16_f32 v130, v76, v77
	v_cvt_pk_bf16_f32 v131, v78, v79
	v_cvt_pk_bf16_f32 v132, v72, v73
	v_cvt_pk_bf16_f32 v133, v74, v75
	s_nop 0
	v_addc_co_u32_e32 v135, vcc, 0, v129, vcc
	global_store_dwordx4 v[134:135], v[130:133], off
	v_add_co_u32_e32 v134, vcc, s92, v128
	s_mov_b32 s5, 0xa000
	s_nop 0
	v_addc_co_u32_e32 v135, vcc, 0, v129, vcc
	v_cvt_pk_bf16_f32 v130, v116, v117
	v_cvt_pk_bf16_f32 v131, v118, v119
	v_cvt_pk_bf16_f32 v132, v112, v113
	v_cvt_pk_bf16_f32 v133, v114, v115
	global_store_dwordx4 v[134:135], v[130:133], off
	v_add_co_u32_e32 v134, vcc, s5, v128
	s_mov_b32 s5, 0xc000
	s_nop 0
	v_addc_co_u32_e32 v135, vcc, 0, v129, vcc
	v_cvt_pk_bf16_f32 v130, v100, v101
	v_cvt_pk_bf16_f32 v131, v102, v103
	v_cvt_pk_bf16_f32 v132, v96, v97
	v_cvt_pk_bf16_f32 v133, v98, v99
	global_store_dwordx4 v[134:135], v[130:133], off
	v_add_co_u32_e32 v134, vcc, s5, v128
	s_mov_b32 s5, 0xe000
	s_nop 0
	v_addc_co_u32_e32 v135, vcc, 0, v129, vcc
	v_cvt_pk_bf16_f32 v130, v84, v85
	v_cvt_pk_bf16_f32 v131, v86, v87
	v_cvt_pk_bf16_f32 v132, v80, v81
	v_cvt_pk_bf16_f32 v133, v82, v83
	global_store_dwordx4 v[134:135], v[130:133], off
	v_add_co_u32_e32 v134, vcc, s5, v128
	s_mov_b32 s5, 0x10000
	s_nop 0
	v_addc_co_u32_e32 v135, vcc, 0, v129, vcc
	v_cvt_pk_bf16_f32 v130, v68, v69
	v_cvt_pk_bf16_f32 v131, v70, v71
	v_cvt_pk_bf16_f32 v132, v64, v65
	v_cvt_pk_bf16_f32 v133, v66, v67
	global_store_dwordx4 v[134:135], v[130:133], off
	v_add_co_u32_e32 v134, vcc, s5, v128
	s_mov_b32 s5, 0x12000
	s_nop 0
	v_addc_co_u32_e32 v135, vcc, 0, v129, vcc
	v_cvt_pk_bf16_f32 v130, v60, v61
	v_cvt_pk_bf16_f32 v131, v62, v63
	v_cvt_pk_bf16_f32 v132, v56, v57
	v_cvt_pk_bf16_f32 v133, v58, v59
	global_store_dwordx4 v[134:135], v[130:133], off
	v_add_co_u32_e32 v134, vcc, s5, v128
	s_mov_b32 s5, 0x14000
	s_nop 0
	v_addc_co_u32_e32 v135, vcc, 0, v129, vcc
	v_cvt_pk_bf16_f32 v130, v44, v45
	v_cvt_pk_bf16_f32 v131, v46, v47
	v_cvt_pk_bf16_f32 v132, v40, v41
	v_cvt_pk_bf16_f32 v133, v42, v43
	global_store_dwordx4 v[134:135], v[130:133], off
	v_add_co_u32_e32 v134, vcc, s5, v128
	s_mov_b32 s5, 0x16000
	s_nop 0
	v_addc_co_u32_e32 v135, vcc, 0, v129, vcc
	v_cvt_pk_bf16_f32 v130, v28, v29
	v_cvt_pk_bf16_f32 v131, v30, v31
	v_cvt_pk_bf16_f32 v132, v24, v25
	v_cvt_pk_bf16_f32 v133, v26, v27
	global_store_dwordx4 v[134:135], v[130:133], off
	v_add_co_u32_e32 v134, vcc, s5, v128
	s_mov_b32 s5, 0x18000
	s_nop 0
	v_addc_co_u32_e32 v135, vcc, 0, v129, vcc
	v_cvt_pk_bf16_f32 v130, v12, v13
	v_cvt_pk_bf16_f32 v131, v14, v15
	v_cvt_pk_bf16_f32 v132, v8, v9
	v_cvt_pk_bf16_f32 v133, v10, v11
	global_store_dwordx4 v[134:135], v[130:133], off
	v_add_co_u32_e32 v134, vcc, s5, v128
	s_mov_b32 s5, 0x1a000
	s_nop 0
	v_addc_co_u32_e32 v135, vcc, 0, v129, vcc
	v_cvt_pk_bf16_f32 v130, v52, v53
	v_cvt_pk_bf16_f32 v131, v54, v55
	v_cvt_pk_bf16_f32 v132, v48, v49
	v_cvt_pk_bf16_f32 v133, v50, v51
	global_store_dwordx4 v[134:135], v[130:133], off
	v_add_co_u32_e32 v134, vcc, s5, v128
	s_mov_b32 s5, 0x1c000
	s_nop 0
	v_addc_co_u32_e32 v135, vcc, 0, v129, vcc
	v_cvt_pk_bf16_f32 v130, v36, v37
	v_cvt_pk_bf16_f32 v131, v38, v39
	v_cvt_pk_bf16_f32 v132, v32, v33
	v_cvt_pk_bf16_f32 v133, v34, v35
	global_store_dwordx4 v[134:135], v[130:133], off
	v_add_co_u32_e32 v134, vcc, s5, v128
	s_nop 0
	v_cvt_pk_bf16_f32 v130, v20, v21
	v_cvt_pk_bf16_f32 v131, v22, v23
	v_cvt_pk_bf16_f32 v132, v16, v17
	v_cvt_pk_bf16_f32 v133, v18, v19
	s_nop 0
	v_addc_co_u32_e32 v135, vcc, 0, v129, vcc
	v_add_co_u32_e32 v128, vcc, 0x1e000, v128
	global_store_dwordx4 v[134:135], v[130:133], off
	s_nop 0
	v_addc_co_u32_e32 v129, vcc, 0, v129, vcc
	v_cvt_pk_bf16_f32 v130, v4, v5
	v_cvt_pk_bf16_f32 v131, v6, v7
	v_cvt_pk_bf16_f32 v132, v0, v1
	v_cvt_pk_bf16_f32 v133, v2, v3
	global_store_dwordx4 v[128:129], v[130:133], off

.LBB0_1436:
	s_add_u32 s28, s6, 0xfffc0080
	s_addc_u32 s29, s7, -1
	s_add_i32 s71, 0, 0x10000
	v_add_u32_e32 v140, s71, v200
	ds_read_b128 v[128:131], v140
	ds_read_b128 v[132:135], v140 offset:1024
	ds_read_b128 v[136:139], v140 offset:2048
	ds_read_b128 v[140:143], v140 offset:3072
	s_cmp_eq_u32 s70, 12
	s_cselect_b32 s53, s17, s29
	s_cselect_b32 s52, s66, s28
	s_cselect_b32 s51, s13, s69
	s_cselect_b32 s50, s67, s68
	s_add_i32 m0, s56, 0xc000
	ds_read_b128 v[144:147], v201
	ds_read_b128 v[152:155], v201 offset:2048
	ds_read_b128 v[170:173], v201 offset:4096
	ds_read_b128 v[192:195], v201 offset:6144
	ds_read_b128 v[148:151], v201 offset:1024
	ds_read_b128 v[166:169], v201 offset:3072
	ds_read_b128 v[188:191], v201 offset:5120
	ds_read_b128 v[202:205], v201 offset:7168
	global_load_lds_dwordx4 v162, s[6:7]
	v_lshl_add_u64 v[174:175], s[6:7], 0, v[164:165]
	s_add_i32 m0, s56, 0xe000
	s_nop 0
	global_load_lds_dwordx4 v[174:175], off
	s_waitcnt lgkmcnt(8)
	s_barrier
	s_waitcnt lgkmcnt(7)
	v_mfma_f32_16x16x32_bf16 v[124:127], v[128:131], v[144:147], v[124:127]
	v_mfma_f32_16x16x32_bf16 v[116:119], v[136:139], v[144:147], v[116:119]
	s_waitcnt lgkmcnt(6)
	s_nop 0
	v_mfma_f32_16x16x32_bf16 v[108:111], v[128:131], v[152:155], v[108:111]
	v_mfma_f32_16x16x32_bf16 v[100:103], v[136:139], v[152:155], v[100:103]
	s_waitcnt lgkmcnt(5)
	s_nop 0
	v_mfma_f32_16x16x32_bf16 v[92:95], v[128:131], v[170:173], v[92:95]
	v_mfma_f32_16x16x32_bf16 v[84:87], v[136:139], v[170:173], v[84:87]
	s_waitcnt lgkmcnt(4)
	s_nop 0
	v_mfma_f32_16x16x32_bf16 v[76:79], v[128:131], v[192:195], v[76:79]
	v_mfma_f32_16x16x32_bf16 v[68:71], v[136:139], v[192:195], v[68:71]
	s_waitcnt lgkmcnt(3)
	s_nop 0
	v_mfma_f32_16x16x32_bf16 v[124:127], v[132:135], v[148:151], v[124:127]
	v_mfma_f32_16x16x32_bf16 v[116:119], v[140:143], v[148:151], v[116:119]
	s_waitcnt lgkmcnt(2)
	s_nop 0
	v_mfma_f32_16x16x32_bf16 v[108:111], v[132:135], v[166:169], v[108:111]
	v_mfma_f32_16x16x32_bf16 v[100:103], v[140:143], v[166:169], v[100:103]
	s_waitcnt lgkmcnt(1)
	s_nop 0
	v_mfma_f32_16x16x32_bf16 v[92:95], v[132:135], v[188:191], v[92:95]
	v_mfma_f32_16x16x32_bf16 v[84:87], v[140:143], v[188:191], v[84:87]
	s_waitcnt lgkmcnt(0)
	s_nop 0
	v_mfma_f32_16x16x32_bf16 v[76:79], v[132:135], v[202:205], v[76:79]
	v_mfma_f32_16x16x32_bf16 v[68:71], v[140:143], v[202:205], v[68:71]
	s_barrier
	s_add_i32 s28, 0, 0x14000
	v_add_u32_e32 v174, s28, v200
	s_add_i32 s29, s71, s55
	ds_read_b128 v[206:209], v174
	ds_read_b128 v[210:213], v174 offset:1024
	ds_read_b128 v[214:217], v174 offset:2048
	ds_read_b128 v[232:235], v174 offset:3072
	v_lshl_add_u64 v[174:175], s[50:51], 0, v[176:177]
	s_mov_b32 m0, s29
	v_lshl_add_u64 v[196:197], s[50:51], 0, v[160:161]
	global_load_lds_dwordx4 v[174:175], off
	s_add_i32 m0, s29, 0x2000
	s_nop 0
	global_load_lds_dwordx4 v[196:197], off
	s_barrier
	s_waitcnt lgkmcnt(3)
	s_nop 0
	v_mfma_f32_16x16x32_bf16 v[120:123], v[206:209], v[144:147], v[120:123]
	s_waitcnt lgkmcnt(1)
	s_nop 0
	v_mfma_f32_16x16x32_bf16 v[112:115], v[214:217], v[144:147], v[112:115]
	v_mfma_f32_16x16x32_bf16 v[104:107], v[206:209], v[152:155], v[104:107]
	v_mfma_f32_16x16x32_bf16 v[96:99], v[214:217], v[152:155], v[96:99]
	v_mfma_f32_16x16x32_bf16 v[88:91], v[206:209], v[170:173], v[88:91]
	v_mfma_f32_16x16x32_bf16 v[80:83], v[214:217], v[170:173], v[80:83]
	v_mfma_f32_16x16x32_bf16 v[72:75], v[206:209], v[192:195], v[72:75]
	v_mfma_f32_16x16x32_bf16 v[64:67], v[214:217], v[192:195], v[64:67]
	v_mfma_f32_16x16x32_bf16 v[120:123], v[210:213], v[148:151], v[120:123]
	s_waitcnt lgkmcnt(0)
	s_nop 0
	v_mfma_f32_16x16x32_bf16 v[112:115], v[232:235], v[148:151], v[112:115]
	v_mfma_f32_16x16x32_bf16 v[104:107], v[210:213], v[166:169], v[104:107]
	v_mfma_f32_16x16x32_bf16 v[96:99], v[232:235], v[166:169], v[96:99]
	v_mfma_f32_16x16x32_bf16 v[88:91], v[210:213], v[188:191], v[88:91]
	v_mfma_f32_16x16x32_bf16 v[80:83], v[232:235], v[188:191], v[80:83]
	v_mfma_f32_16x16x32_bf16 v[72:75], v[210:213], v[202:205], v[72:75]
	v_mfma_f32_16x16x32_bf16 v[64:67], v[232:235], v[202:205], v[64:67]
	s_mov_b32 m0, s56
	v_lshl_add_u64 v[236:237], s[52:53], 0, v[156:157]
	s_barrier
	ds_read_b128 v[144:147], v201 offset:16384
	ds_read_b128 v[152:155], v201 offset:18432
	ds_read_b128 v[170:173], v201 offset:20480
	ds_read_b128 v[192:195], v201 offset:22528
	ds_read_b128 v[148:151], v201 offset:17408
	ds_read_b128 v[166:169], v201 offset:19456
	ds_read_b128 v[188:191], v201 offset:21504
	ds_read_b128 v[202:205], v201 offset:23552
	global_load_lds_dwordx4 v[236:237], off
	v_lshl_add_u64 v[238:239], s[52:53], 0, v[158:159]
	s_mov_b32 m0, s57
	s_nop 0
	global_load_lds_dwordx4 v[238:239], off
	s_barrier
	s_waitcnt lgkmcnt(7)
	v_mfma_f32_16x16x32_bf16 v[60:63], v[128:131], v[144:147], v[60:63]
	v_mfma_f32_16x16x32_bf16 v[52:55], v[136:139], v[144:147], v[52:55]
	s_waitcnt lgkmcnt(6)
	s_nop 0
	v_mfma_f32_16x16x32_bf16 v[44:47], v[128:131], v[152:155], v[44:47]
	v_mfma_f32_16x16x32_bf16 v[36:39], v[136:139], v[152:155], v[36:39]
	s_waitcnt lgkmcnt(5)
	s_nop 0
	v_mfma_f32_16x16x32_bf16 v[28:31], v[128:131], v[170:173], v[28:31]
	v_mfma_f32_16x16x32_bf16 v[20:23], v[136:139], v[170:173], v[20:23]
	s_waitcnt lgkmcnt(4)
	s_nop 0
	v_mfma_f32_16x16x32_bf16 v[12:15], v[128:131], v[192:195], v[12:15]
	v_mfma_f32_16x16x32_bf16 v[4:7], v[136:139], v[192:195], v[4:7]
	s_waitcnt lgkmcnt(3)
	s_nop 0
	v_mfma_f32_16x16x32_bf16 v[60:63], v[132:135], v[148:151], v[60:63]
	v_mfma_f32_16x16x32_bf16 v[52:55], v[140:143], v[148:151], v[52:55]
	s_waitcnt lgkmcnt(2)
	s_nop 0
	v_mfma_f32_16x16x32_bf16 v[44:47], v[132:135], v[166:169], v[44:47]
	v_mfma_f32_16x16x32_bf16 v[36:39], v[140:143], v[166:169], v[36:39]
	s_waitcnt lgkmcnt(1)
	s_nop 0
	v_mfma_f32_16x16x32_bf16 v[28:31], v[132:135], v[188:191], v[28:31]
	v_mfma_f32_16x16x32_bf16 v[20:23], v[140:143], v[188:191], v[20:23]
	s_waitcnt lgkmcnt(0)
	s_nop 0
	v_mfma_f32_16x16x32_bf16 v[12:15], v[132:135], v[202:205], v[12:15]
	v_mfma_f32_16x16x32_bf16 v[4:7], v[140:143], v[202:205], v[4:7]
	s_barrier
	s_add_u32 s72, s50, 0x40000
	s_addc_u32 s73, s51, 0
	s_add_i32 s28, s28, s55
	s_mov_b32 m0, s28
	s_nop 0
	global_load_lds_dwordx4 v176, s[72:73]
	s_add_i32 m0, s28, 0x2000
	s_nop 0
	global_load_lds_dwordx4 v160, s[72:73]
	s_waitcnt vmcnt(6)
	s_barrier
	v_mfma_f32_16x16x32_bf16 v[56:59], v[206:209], v[144:147], v[56:59]
	v_mfma_f32_16x16x32_bf16 v[48:51], v[214:217], v[144:147], v[48:51]
	v_mfma_f32_16x16x32_bf16 v[40:43], v[206:209], v[152:155], v[40:43]
	v_mfma_f32_16x16x32_bf16 v[32:35], v[214:217], v[152:155], v[32:35]
	v_mfma_f32_16x16x32_bf16 v[24:27], v[206:209], v[170:173], v[24:27]
	v_mfma_f32_16x16x32_bf16 v[16:19], v[214:217], v[170:173], v[16:19]
	v_mfma_f32_16x16x32_bf16 v[8:11], v[206:209], v[192:195], v[8:11]
	v_mfma_f32_16x16x32_bf16 v[0:3], v[214:217], v[192:195], v[0:3]
	v_mfma_f32_16x16x32_bf16 v[56:59], v[210:213], v[148:151], v[56:59]
	v_mfma_f32_16x16x32_bf16 v[48:51], v[232:235], v[148:151], v[48:51]
	v_mfma_f32_16x16x32_bf16 v[40:43], v[210:213], v[166:169], v[40:43]
	v_mfma_f32_16x16x32_bf16 v[32:35], v[232:235], v[166:169], v[32:35]
	v_mfma_f32_16x16x32_bf16 v[24:27], v[210:213], v[188:191], v[24:27]
	v_mfma_f32_16x16x32_bf16 v[16:19], v[232:235], v[188:191], v[16:19]
	v_mfma_f32_16x16x32_bf16 v[8:11], v[210:213], v[202:205], v[8:11]
	v_mfma_f32_16x16x32_bf16 v[0:3], v[232:235], v[202:205], v[0:3]
	s_add_i32 s28, 0, 0x18000
	v_add_u32_e32 v140, s28, v200
	s_barrier
	ds_read_b128 v[128:131], v140
	ds_read_b128 v[132:135], v140 offset:1024
	ds_read_b128 v[136:139], v140 offset:2048
	ds_read_b128 v[140:143], v140 offset:3072
	s_add_u32 s52, s52, 0x40000
	s_addc_u32 s53, s53, 0
	s_mov_b32 m0, s58
	ds_read_b128 v[144:147], v201 offset:32768
	ds_read_b128 v[152:155], v201 offset:34816
	ds_read_b128 v[170:173], v201 offset:36864
	ds_read_b128 v[192:195], v201 offset:38912
	ds_read_b128 v[148:151], v201 offset:33792
	ds_read_b128 v[166:169], v201 offset:35840
	ds_read_b128 v[188:191], v201 offset:37888
	ds_read_b128 v[202:205], v201 offset:39936
	global_load_lds_dwordx4 v156, s[52:53]
	s_mov_b32 m0, s59
	s_nop 0
	global_load_lds_dwordx4 v158, s[52:53]
	s_waitcnt lgkmcnt(8)
	s_barrier
	s_waitcnt lgkmcnt(7)
	s_nop 0
	v_mfma_f32_16x16x32_bf16 v[124:127], v[128:131], v[144:147], v[124:127]
	v_mfma_f32_16x16x32_bf16 v[116:119], v[136:139], v[144:147], v[116:119]
	s_waitcnt lgkmcnt(6)
	s_nop 0
	v_mfma_f32_16x16x32_bf16 v[108:111], v[128:131], v[152:155], v[108:111]
	v_mfma_f32_16x16x32_bf16 v[100:103], v[136:139], v[152:155], v[100:103]
	s_waitcnt lgkmcnt(5)
	s_nop 0
	v_mfma_f32_16x16x32_bf16 v[92:95], v[128:131], v[170:173], v[92:95]
	v_mfma_f32_16x16x32_bf16 v[84:87], v[136:139], v[170:173], v[84:87]
	s_waitcnt lgkmcnt(4)
	s_nop 0
	v_mfma_f32_16x16x32_bf16 v[76:79], v[128:131], v[192:195], v[76:79]
	v_mfma_f32_16x16x32_bf16 v[68:71], v[136:139], v[192:195], v[68:71]
	s_waitcnt lgkmcnt(3)
	s_nop 0
	v_mfma_f32_16x16x32_bf16 v[124:127], v[132:135], v[148:151], v[124:127]
	v_mfma_f32_16x16x32_bf16 v[116:119], v[140:143], v[148:151], v[116:119]
	s_waitcnt lgkmcnt(2)
	s_nop 0
	v_mfma_f32_16x16x32_bf16 v[108:111], v[132:135], v[166:169], v[108:111]
	v_mfma_f32_16x16x32_bf16 v[100:103], v[140:143], v[166:169], v[100:103]
	s_waitcnt lgkmcnt(1)
	s_nop 0
	v_mfma_f32_16x16x32_bf16 v[92:95], v[132:135], v[188:191], v[92:95]
	v_mfma_f32_16x16x32_bf16 v[84:87], v[140:143], v[188:191], v[84:87]
	s_waitcnt lgkmcnt(0)
	s_nop 0
	v_mfma_f32_16x16x32_bf16 v[76:79], v[132:135], v[202:205], v[76:79]
	v_mfma_f32_16x16x32_bf16 v[68:71], v[140:143], v[202:205], v[68:71]
	s_barrier
	s_add_i32 s29, 0, 0x1c000
	s_add_i32 s28, s28, s55
	v_add_u32_e32 v232, s29, v200
	v_lshl_add_u64 v[174:175], v[174:175], 0, s[40:41]
	s_mov_b32 m0, s28
	ds_read_b128 v[206:209], v232
	ds_read_b128 v[210:213], v232 offset:1024
	ds_read_b128 v[214:217], v232 offset:2048
	ds_read_b128 v[232:235], v232 offset:3072
	global_load_lds_dwordx4 v[174:175], off
	v_lshl_add_u64 v[174:175], v[196:197], 0, s[40:41]
	s_add_i32 m0, s28, 0x2000
	s_nop 0
	global_load_lds_dwordx4 v[174:175], off
	s_barrier
	s_waitcnt lgkmcnt(3)
	s_nop 0
	v_mfma_f32_16x16x32_bf16 v[120:123], v[206:209], v[144:147], v[120:123]
	s_waitcnt lgkmcnt(1)
	s_nop 0
	v_mfma_f32_16x16x32_bf16 v[112:115], v[214:217], v[144:147], v[112:115]
	v_mfma_f32_16x16x32_bf16 v[104:107], v[206:209], v[152:155], v[104:107]
	v_mfma_f32_16x16x32_bf16 v[96:99], v[214:217], v[152:155], v[96:99]
	v_mfma_f32_16x16x32_bf16 v[88:91], v[206:209], v[170:173], v[88:91]
	v_mfma_f32_16x16x32_bf16 v[80:83], v[214:217], v[170:173], v[80:83]
	v_mfma_f32_16x16x32_bf16 v[72:75], v[206:209], v[192:195], v[72:75]
	v_mfma_f32_16x16x32_bf16 v[64:67], v[214:217], v[192:195], v[64:67]
	v_mfma_f32_16x16x32_bf16 v[120:123], v[210:213], v[148:151], v[120:123]
	s_waitcnt lgkmcnt(0)
	s_nop 0
	v_mfma_f32_16x16x32_bf16 v[112:115], v[232:235], v[148:151], v[112:115]
	v_mfma_f32_16x16x32_bf16 v[104:107], v[210:213], v[166:169], v[104:107]
	v_mfma_f32_16x16x32_bf16 v[96:99], v[232:235], v[166:169], v[96:99]
	v_mfma_f32_16x16x32_bf16 v[88:91], v[210:213], v[188:191], v[88:91]
	v_mfma_f32_16x16x32_bf16 v[80:83], v[232:235], v[188:191], v[80:83]
	v_mfma_f32_16x16x32_bf16 v[72:75], v[210:213], v[202:205], v[72:75]
	v_mfma_f32_16x16x32_bf16 v[64:67], v[232:235], v[202:205], v[64:67]
	s_mov_b32 m0, s62
	v_lshl_add_u64 v[174:175], v[236:237], 0, s[40:41]
	s_barrier
	ds_read_b128 v[144:147], v201 offset:49152
	ds_read_b128 v[152:155], v201 offset:51200
	ds_read_b128 v[170:173], v201 offset:53248
	ds_read_b128 v[192:195], v201 offset:55296
	ds_read_b128 v[148:151], v201 offset:50176
	ds_read_b128 v[166:169], v201 offset:52224
	ds_read_b128 v[188:191], v201 offset:54272
	ds_read_b128 v[202:205], v201 offset:56320
	global_load_lds_dwordx4 v[174:175], off
	v_lshl_add_u64 v[174:175], v[238:239], 0, s[40:41]
	s_mov_b32 m0, s63
	s_nop 0
	global_load_lds_dwordx4 v[174:175], off
	s_barrier
	s_waitcnt lgkmcnt(7)
	v_mfma_f32_16x16x32_bf16 v[60:63], v[128:131], v[144:147], v[60:63]
	v_mfma_f32_16x16x32_bf16 v[52:55], v[136:139], v[144:147], v[52:55]
	s_waitcnt lgkmcnt(6)
	s_nop 0
	v_mfma_f32_16x16x32_bf16 v[44:47], v[128:131], v[152:155], v[44:47]
	v_mfma_f32_16x16x32_bf16 v[36:39], v[136:139], v[152:155], v[36:39]
	s_waitcnt lgkmcnt(5)
	s_nop 0
	v_mfma_f32_16x16x32_bf16 v[28:31], v[128:131], v[170:173], v[28:31]
	v_mfma_f32_16x16x32_bf16 v[20:23], v[136:139], v[170:173], v[20:23]
	s_waitcnt lgkmcnt(4)
	s_nop 0
	v_mfma_f32_16x16x32_bf16 v[12:15], v[128:131], v[192:195], v[12:15]
	v_mfma_f32_16x16x32_bf16 v[4:7], v[136:139], v[192:195], v[4:7]
	s_waitcnt lgkmcnt(3)
	s_nop 0
	v_mfma_f32_16x16x32_bf16 v[60:63], v[132:135], v[148:151], v[60:63]
	v_mfma_f32_16x16x32_bf16 v[52:55], v[140:143], v[148:151], v[52:55]
	s_waitcnt lgkmcnt(2)
	s_nop 0
	v_mfma_f32_16x16x32_bf16 v[44:47], v[132:135], v[166:169], v[44:47]
	v_mfma_f32_16x16x32_bf16 v[36:39], v[140:143], v[166:169], v[36:39]
	s_waitcnt lgkmcnt(1)
	s_nop 0
	v_mfma_f32_16x16x32_bf16 v[28:31], v[132:135], v[188:191], v[28:31]
	v_mfma_f32_16x16x32_bf16 v[20:23], v[140:143], v[188:191], v[20:23]
	s_waitcnt lgkmcnt(0)
	s_nop 0
	v_mfma_f32_16x16x32_bf16 v[12:15], v[132:135], v[202:205], v[12:15]
	v_mfma_f32_16x16x32_bf16 v[4:7], v[140:143], v[202:205], v[4:7]
	s_barrier
	s_add_u32 s50, s50, 0x40080
	s_addc_u32 s51, s51, 0
	s_add_i32 s28, s29, s55
	s_mov_b32 m0, s28
	s_nop 0
	global_load_lds_dwordx4 v176, s[50:51]
	s_add_i32 m0, s28, 0x2000
	s_nop 0
	global_load_lds_dwordx4 v160, s[50:51]
	s_waitcnt vmcnt(6)
	s_barrier
	v_mfma_f32_16x16x32_bf16 v[56:59], v[206:209], v[144:147], v[56:59]
	v_mfma_f32_16x16x32_bf16 v[48:51], v[214:217], v[144:147], v[48:51]
	v_mfma_f32_16x16x32_bf16 v[40:43], v[206:209], v[152:155], v[40:43]
	v_mfma_f32_16x16x32_bf16 v[32:35], v[214:217], v[152:155], v[32:35]
	v_mfma_f32_16x16x32_bf16 v[24:27], v[206:209], v[170:173], v[24:27]
	v_mfma_f32_16x16x32_bf16 v[16:19], v[214:217], v[170:173], v[16:19]
	v_mfma_f32_16x16x32_bf16 v[8:11], v[206:209], v[192:195], v[8:11]
	v_mfma_f32_16x16x32_bf16 v[0:3], v[214:217], v[192:195], v[0:3]
	v_mfma_f32_16x16x32_bf16 v[56:59], v[210:213], v[148:151], v[56:59]
	v_mfma_f32_16x16x32_bf16 v[48:51], v[232:235], v[148:151], v[48:51]
	v_mfma_f32_16x16x32_bf16 v[40:43], v[210:213], v[166:169], v[40:43]
	v_mfma_f32_16x16x32_bf16 v[32:35], v[232:235], v[166:169], v[32:35]
	v_mfma_f32_16x16x32_bf16 v[24:27], v[210:213], v[188:191], v[24:27]
	v_mfma_f32_16x16x32_bf16 v[16:19], v[232:235], v[188:191], v[16:19]
	v_mfma_f32_16x16x32_bf16 v[8:11], v[210:213], v[202:205], v[8:11]
	v_mfma_f32_16x16x32_bf16 v[0:3], v[232:235], v[202:205], v[0:3]
	s_add_i32 s70, s70, 2
	s_add_u32 s6, s6, 0x100
	s_addc_u32 s7, s7, 0
	s_add_u32 s68, s68, 0x100
	s_addc_u32 s69, s69, 0
	s_cmp_lt_u32 s70, 14
	s_barrier
	s_cbranch_scc1 .LBB0_1436
	v_mov_b32_e32 v134, v199
	v_mov_b32_e32 v128, v198
	s_lshl_b32 s4, s4, 8
	s_add_i32 s4, s4, s60
	v_add_u32_e32 v192, s4, v128
	v_lshlrev_b32_e32 v128, 2, v134
	v_ashrrev_i32_e32 v129, 31, v128
	v_ashrrev_i32_e32 v193, 31, v192
	v_add_u32_e32 v190, 16, v192
	v_lshl_add_u64 v[132:133], v[128:129], 2, s[8:9]
	v_lshlrev_b64 v[128:129], 6, v[192:193]
	v_ashrrev_i32_e32 v191, 31, v190
	v_add_u32_e32 v188, 32, v192
	v_lshl_add_u64 v[128:129], v[132:133], 0, v[128:129]
	v_lshlrev_b64 v[130:131], 6, v[190:191]
	v_ashrrev_i32_e32 v189, 31, v188
	v_lshl_add_u64 v[130:131], v[132:133], 0, v[130:131]
	global_load_dwordx4 v[202:205], v[128:129], off
	global_load_dwordx4 v[144:147], v[130:131], off
	v_lshlrev_b64 v[128:129], 6, v[188:189]
	v_add_u32_e32 v174, 48, v192
	v_lshl_add_u64 v[128:129], v[132:133], 0, v[128:129]
	v_ashrrev_i32_e32 v175, 31, v174
	global_load_dwordx4 v[148:151], v[128:129], off
	v_lshlrev_b64 v[128:129], 6, v[174:175]
	v_lshl_add_u64 v[128:129], v[132:133], 0, v[128:129]
	global_load_dwordx4 v[152:155], v[128:129], off
	v_add_u32_e32 v172, 0x80, v192
	v_ashrrev_i32_e32 v173, 31, v172
	v_lshlrev_b64 v[128:129], 6, v[172:173]
	v_lshl_add_u64 v[128:129], v[132:133], 0, v[128:129]
	global_load_dwordx4 v[140:143], v[128:129], off
	v_add_u32_e32 v170, 0x90, v192
	v_ashrrev_i32_e32 v171, 31, v170
	v_lshlrev_b64 v[128:129], 6, v[170:171]
	v_lshl_add_u64 v[128:129], v[132:133], 0, v[128:129]
	global_load_dwordx4 v[128:131], v[128:129], off
	s_lshl_b32 s5, s5, 7
	v_add_u32_e32 v168, 0xa0, v192
	v_add_u32_e32 v166, 0xb0, v192
	s_or_b32 s5, s5, s61
	v_ashrrev_i32_e32 v169, 31, v168
	v_ashrrev_i32_e32 v167, 31, v166
	v_lshl_add_u32 v194, v134, 3, s5
	v_lshlrev_b64 v[134:135], 6, v[168:169]
	v_lshlrev_b64 v[136:137], 6, v[166:167]
	v_lshl_add_u64 v[134:135], v[132:133], 0, v[134:135]
	v_lshl_add_u64 v[132:133], v[132:133], 0, v[136:137]
	global_load_dwordx4 v[136:139], v[134:135], off
	s_nop 0
	global_load_dwordx4 v[132:135], v[132:133], off
	s_mov_b32 s4, 0x358637bd
	v_mov_b64_e32 v[196:197], s[4:5]
	v_ashrrev_i32_e32 v195, 31, v194
	s_mov_b64 s[50:51], s[20:21]
	s_waitcnt vmcnt(0)
	v_mov_b32_e32 v206, v203
	v_mov_b32_e32 v207, v204
	v_mov_b32_e32 v203, v205
	v_mov_b32_e32 v204, v145
	v_mov_b32_e32 v205, v146
	v_mov_b32_e32 v145, v147
	v_pk_add_f32 v[202:203], v[206:207], v[202:203]
	v_mov_b32_e32 v146, v149
	v_mov_b32_e32 v147, v150
	v_mov_b32_e32 v149, v151
	v_mov_b32_e32 v150, v153
	v_mov_b32_e32 v151, v154
	v_mov_b32_e32 v153, v155
	v_pk_add_f32 v[144:145], v[204:205], v[144:145]
	v_mov_b32_e32 v155, v202
	v_pk_add_f32 v[146:147], v[146:147], v[148:149]
	v_pk_add_f32 v[148:149], v[150:151], v[152:153]
	v_mov_b32_e32 v154, v144
	v_mov_b32_e32 v202, v145
	v_mov_b32_e32 v144, v148
	v_mov_b32_e32 v145, v146
	v_mov_b32_e32 v146, v149
	v_pk_add_f32 v[148:149], v[154:155], v[202:203]
	v_pk_add_f32 v[144:145], v[144:145], v[146:147]
	ds_bpermute_b32 v147, v219, v149
	ds_bpermute_b32 v146, v219, v148
	ds_bpermute_b32 v151, v219, v145
	ds_bpermute_b32 v150, v219, v144
	v_mov_b32_e32 v152, v141
	v_mov_b32_e32 v153, v142
	v_mov_b32_e32 v141, v143
	s_waitcnt lgkmcnt(0)
	v_pk_add_f32 v[142:143], v[148:149], v[146:147]
	ds_bpermute_b32 v147, v218, v143
	ds_bpermute_b32 v146, v218, v142
	v_pk_add_f32 v[144:145], v[144:145], v[150:151]
	ds_bpermute_b32 v149, v218, v145
	ds_bpermute_b32 v148, v218, v144
	v_mov_b32_e32 v150, v129
	s_waitcnt lgkmcnt(2)
	v_pk_add_f32 v[142:143], v[142:143], v[146:147]
	v_mov_b32_e32 v151, v130
	v_pk_fma_f32 v[142:143], v[142:143], s[30:31], v[196:197] op_sel_hi:[1,0,0]
	s_waitcnt lgkmcnt(0)
	v_pk_add_f32 v[144:145], v[144:145], v[148:149]
	v_mul_f32_e32 v129, 0x4b800000, v143
	v_cmp_gt_f32_e32 vcc, s86, v143
	v_pk_fma_f32 v[146:147], v[144:145], s[30:31], v[196:197] op_sel_hi:[1,0,0]
	v_mul_f32_e32 v130, 0x4b800000, v142
	v_cndmask_b32_e32 v129, v143, v129, vcc
	v_rsq_f32_e32 v129, v129
	v_cmp_gt_f32_e64 s[4:5], s86, v142
	v_mul_f32_e32 v144, 0x4b800000, v147
	v_cmp_gt_f32_e64 s[6:7], s86, v147
	v_cndmask_b32_e64 v130, v142, v130, s[4:5]
	v_rsq_f32_e32 v142, v130
	v_cndmask_b32_e64 v130, v147, v144, s[6:7]
	v_rsq_f32_e32 v143, v130
	v_mul_f32_e32 v130, 0x45800000, v129
	v_cndmask_b32_e32 v144, v129, v130, vcc
	v_mov_b32_e32 v129, v131
	v_pk_add_f32 v[140:141], v[152:153], v[140:141]
	v_pk_add_f32 v[128:129], v[150:151], v[128:129]
	v_mov_b32_e32 v131, v140
	v_mov_b32_e32 v130, v128
	v_mov_b32_e32 v140, v129
	v_pk_add_f32 v[128:129], v[130:131], v[140:141]
	ds_bpermute_b32 v131, v219, v129
	ds_bpermute_b32 v130, v219, v128
	v_mul_f32_e32 v145, 0x45800000, v142
	v_cndmask_b32_e64 v142, v142, v145, s[4:5]
	v_mul_f32_e32 v140, 0x4b800000, v146
	v_cmp_gt_f32_e32 vcc, s86, v146
	s_waitcnt lgkmcnt(0)
	v_pk_add_f32 v[128:129], v[128:129], v[130:131]
	ds_bpermute_b32 v131, v218, v129
	ds_bpermute_b32 v130, v218, v128
	v_cndmask_b32_e32 v140, v146, v140, vcc
	v_rsq_f32_e32 v141, v140
	v_mul_f32_e32 v140, 0x45800000, v143
	v_cndmask_b32_e64 v140, v143, v140, s[6:7]
	s_waitcnt lgkmcnt(0)
	v_pk_add_f32 v[128:129], v[128:129], v[130:131]
	v_mov_b32_e32 v131, v138
	v_pk_fma_f32 v[128:129], v[128:129], s[30:31], v[196:197] op_sel_hi:[1,0,0]
	v_mul_f32_e32 v143, 0x45800000, v141
	v_mul_f32_e32 v130, 0x4b800000, v129
	v_cmp_gt_f32_e64 s[4:5], s86, v129
	v_cmp_gt_f32_e64 s[6:7], s86, v128
	v_pk_mul_f32 v[110:111], v[110:111], v[142:143] op_sel_hi:[1,0]
	v_cndmask_b32_e64 v129, v129, v130, s[4:5]
	v_mov_b32_e32 v130, v137
	v_mov_b32_e32 v137, v139
	v_pk_add_f32 v[130:131], v[130:131], v[136:137]
	v_mov_b32_e32 v136, v133
	v_mov_b32_e32 v137, v134
	v_mov_b32_e32 v133, v135
	v_pk_add_f32 v[132:133], v[136:137], v[132:133]
	v_mov_b32_e32 v135, v130
	v_mov_b32_e32 v134, v132
	v_mov_b32_e32 v130, v133
	v_pk_add_f32 v[130:131], v[134:135], v[130:131]
	ds_bpermute_b32 v133, v219, v131
	ds_bpermute_b32 v132, v219, v130
	v_rsq_f32_e32 v145, v129
	v_mul_f32_e32 v129, 0x4b800000, v128
	v_cndmask_b32_e64 v128, v128, v129, s[6:7]
	v_rsq_f32_e32 v135, v128
	s_waitcnt lgkmcnt(0)
	v_pk_add_f32 v[128:129], v[130:131], v[132:133]
	ds_bpermute_b32 v131, v218, v129
	ds_bpermute_b32 v130, v218, v128
	v_pk_mul_f32 v[126:127], v[126:127], v[144:145] op_sel_hi:[1,0]
	v_pk_mul_f32 v[122:123], v[122:123], v[144:145] op_sel_hi:[1,0]
	v_pk_mul_f32 v[116:117], v[116:117], v[144:145] op_sel_hi:[1,0]
	v_pk_mul_f32 v[124:125], v[124:125], v[144:145] op_sel_hi:[1,0]
	v_pk_mul_f32 v[138:139], v[126:127], s[44:45] op_sel_hi:[1,0]
	v_pk_mul_f32 v[120:121], v[120:121], v[144:145] op_sel_hi:[1,0]
	v_pk_mul_f32 v[122:123], v[126:127], v[122:123]
	v_pk_mul_f32 v[118:119], v[118:119], v[144:145] op_sel_hi:[1,0]
	v_pk_mul_f32 v[126:127], v[116:117], s[44:45] op_sel_hi:[1,0]
	v_pk_mul_f32 v[146:147], v[124:125], s[44:45] op_sel_hi:[1,0]
	v_pk_mul_f32 v[120:121], v[124:125], v[120:121]
	v_pk_mul_f32 v[124:125], v[118:119], s[44:45] op_sel_hi:[1,0]
	v_exp_f32_e32 v126, v126
	v_exp_f32_e32 v127, v127
	s_waitcnt lgkmcnt(0)
	v_pk_add_f32 v[128:129], v[128:129], v[130:131]
	v_exp_f32_e32 v146, v146
	v_exp_f32_e32 v138, v138
	v_exp_f32_e32 v139, v139
	v_exp_f32_e32 v147, v147
	v_exp_f32_e32 v124, v124
	v_exp_f32_e32 v125, v125
	v_pk_fma_f32 v[128:129], v[128:129], s[30:31], v[196:197] op_sel_hi:[1,0,0]
	v_cndmask_b32_e32 v136, v141, v143, vcc
	v_mul_f32_e32 v132, 0x45800000, v145
	v_mul_f32_e32 v130, 0x4b800000, v129
	v_cmp_gt_f32_e32 vcc, s86, v129
	v_cndmask_b32_e64 v134, v145, v132, s[4:5]
	v_cmp_gt_f32_e64 s[4:5], s86, v128
	v_cndmask_b32_e32 v129, v129, v130, vcc
	v_mul_f32_e32 v130, 0x4b800000, v128
	v_pk_add_f32 v[126:127], v[126:127], 1.0 op_sel_hi:[1,0]
	v_rsq_f32_e32 v129, v129
	v_cndmask_b32_e64 v128, v128, v130, s[4:5]
	v_pk_add_f32 v[138:139], v[138:139], 1.0 op_sel_hi:[1,0]
	v_pk_add_f32 v[146:147], v[146:147], 1.0 op_sel_hi:[1,0]
	v_pk_add_f32 v[124:125], v[124:125], 1.0 op_sel_hi:[1,0]
	v_rcp_f32_e32 v126, v126
	v_rcp_f32_e32 v127, v127
	v_rsq_f32_e32 v128, v128
	v_rcp_f32_e32 v146, v146
	v_rcp_f32_e32 v138, v138
	v_rcp_f32_e32 v139, v139
	v_rcp_f32_e32 v147, v147
	v_rcp_f32_e32 v124, v124
	v_rcp_f32_e32 v125, v125
	v_pk_mul_f32 v[112:113], v[112:113], v[144:145] op_sel_hi:[1,0]
	v_pk_mul_f32 v[114:115], v[114:115], v[144:145] op_sel_hi:[1,0]
	v_pk_mul_f32 v[112:113], v[116:117], v[112:113]
	v_mul_f32_e32 v130, 0x45800000, v129
	v_pk_mul_f32 v[114:115], v[118:119], v[114:115]
	v_pk_mul_f32 v[112:113], v[112:113], v[126:127]
	v_cndmask_b32_e32 v130, v129, v130, vcc
	v_mul_f32_e32 v129, 0x45800000, v128
	v_pk_mul_f32 v[122:123], v[122:123], v[138:139]
	v_pk_mul_f32 v[120:121], v[120:121], v[146:147]
	v_pk_mul_f32 v[114:115], v[114:115], v[124:125]
	v_cvt_pk_bf16_f32 v116, v120, v121
	v_cvt_pk_bf16_f32 v117, v122, v123
	v_cvt_pk_bf16_f32 v118, v112, v113
	v_mov_b64_e32 v[112:113], s[10:11]
	v_cndmask_b32_e64 v128, v128, v129, s[4:5]
	v_cvt_pk_bf16_f32 v119, v114, v115
	v_mad_i64_i32 v[120:121], s[4:5], v192, s35, v[112:113]
	v_lshlrev_b64 v[114:115], 1, v[194:195]
	v_lshl_add_u64 v[120:121], v[120:121], 0, v[114:115]
	v_pk_mul_f32 v[108:109], v[108:109], v[142:143] op_sel_hi:[1,0]
	v_pk_mul_f32 v[106:107], v[106:107], v[142:143] op_sel_hi:[1,0]
	v_pk_mul_f32 v[104:105], v[104:105], v[142:143] op_sel_hi:[1,0]
	v_pk_mul_f32 v[102:103], v[102:103], v[142:143] op_sel_hi:[1,0]
	v_pk_mul_f32 v[100:101], v[100:101], v[142:143] op_sel_hi:[1,0]
	global_store_dwordx4 v[120:121], v[116:119], off
	v_pk_mul_f32 v[104:105], v[108:109], v[104:105]
	v_pk_mul_f32 v[106:107], v[110:111], v[106:107]
	v_pk_mul_f32 v[116:117], v[110:111], s[44:45] op_sel_hi:[1,0]
	v_pk_mul_f32 v[118:119], v[108:109], s[44:45] op_sel_hi:[1,0]
	v_pk_mul_f32 v[108:109], v[102:103], s[44:45] op_sel_hi:[1,0]
	v_pk_mul_f32 v[110:111], v[100:101], s[44:45] op_sel_hi:[1,0]
	v_exp_f32_e32 v108, v108
	v_exp_f32_e32 v110, v110
	v_exp_f32_e32 v109, v109
	v_exp_f32_e32 v111, v111
	v_exp_f32_e32 v118, v118
	v_exp_f32_e32 v116, v116
	v_exp_f32_e32 v117, v117
	v_exp_f32_e32 v119, v119
	v_pk_add_f32 v[108:109], v[108:109], 1.0 op_sel_hi:[1,0]
	v_pk_add_f32 v[110:111], v[110:111], 1.0 op_sel_hi:[1,0]
	v_pk_add_f32 v[116:117], v[116:117], 1.0 op_sel_hi:[1,0]
	v_pk_add_f32 v[118:119], v[118:119], 1.0 op_sel_hi:[1,0]
	v_rcp_f32_e32 v110, v110
	v_rcp_f32_e32 v108, v108
	v_rcp_f32_e32 v109, v109
	v_rcp_f32_e32 v111, v111
	v_rcp_f32_e32 v118, v118
	v_rcp_f32_e32 v116, v116
	v_rcp_f32_e32 v117, v117
	v_rcp_f32_e32 v119, v119
	v_pk_mul_f32 v[98:99], v[98:99], v[142:143] op_sel_hi:[1,0]
	v_pk_mul_f32 v[96:97], v[96:97], v[142:143] op_sel_hi:[1,0]
	v_pk_mul_f32 v[98:99], v[102:103], v[98:99]
	v_pk_mul_f32 v[96:97], v[100:101], v[96:97]
	v_pk_mul_f32 v[100:101], v[98:99], v[108:109]
	v_pk_mul_f32 v[98:99], v[96:97], v[110:111]
	v_pk_mul_f32 v[106:107], v[106:107], v[116:117]
	v_pk_mul_f32 v[104:105], v[104:105], v[118:119]
	v_pk_mul_f32 v[94:95], v[94:95], v[140:141] op_sel_hi:[1,0]
	v_cvt_pk_bf16_f32 v96, v104, v105
	v_cvt_pk_bf16_f32 v97, v106, v107
	v_cvt_pk_bf16_f32 v98, v98, v99
	v_cvt_pk_bf16_f32 v99, v100, v101
	v_mad_i64_i32 v[100:101], s[4:5], v190, s35, v[112:113]
	v_lshl_add_u64 v[100:101], v[100:101], 0, v[114:115]
	v_pk_mul_f32 v[92:93], v[92:93], v[140:141] op_sel_hi:[1,0]
	v_pk_mul_f32 v[90:91], v[90:91], v[140:141] op_sel_hi:[1,0]
	v_pk_mul_f32 v[88:89], v[88:89], v[140:141] op_sel_hi:[1,0]
	v_pk_mul_f32 v[86:87], v[86:87], v[140:141] op_sel_hi:[1,0]
	v_pk_mul_f32 v[84:85], v[84:85], v[140:141] op_sel_hi:[1,0]
	global_store_dwordx4 v[100:101], v[96:99], off
	v_pk_mul_f32 v[88:89], v[92:93], v[88:89]
	v_pk_mul_f32 v[90:91], v[94:95], v[90:91]
	v_pk_mul_f32 v[96:97], v[94:95], s[44:45] op_sel_hi:[1,0]
	v_pk_mul_f32 v[98:99], v[92:93], s[44:45] op_sel_hi:[1,0]
	v_pk_mul_f32 v[92:93], v[86:87], s[44:45] op_sel_hi:[1,0]
	v_pk_mul_f32 v[94:95], v[84:85], s[44:45] op_sel_hi:[1,0]
	v_exp_f32_e32 v92, v92
	v_exp_f32_e32 v94, v94
	v_exp_f32_e32 v93, v93
	v_exp_f32_e32 v95, v95
	v_exp_f32_e32 v98, v98
	v_exp_f32_e32 v96, v96
	v_exp_f32_e32 v97, v97
	v_exp_f32_e32 v99, v99
	v_pk_add_f32 v[92:93], v[92:93], 1.0 op_sel_hi:[1,0]
	v_pk_add_f32 v[94:95], v[94:95], 1.0 op_sel_hi:[1,0]
	v_pk_add_f32 v[96:97], v[96:97], 1.0 op_sel_hi:[1,0]
	v_pk_add_f32 v[98:99], v[98:99], 1.0 op_sel_hi:[1,0]
	v_rcp_f32_e32 v94, v94
	v_rcp_f32_e32 v92, v92
	v_rcp_f32_e32 v93, v93
	v_rcp_f32_e32 v95, v95
	v_rcp_f32_e32 v98, v98
	v_rcp_f32_e32 v96, v96
	v_rcp_f32_e32 v97, v97
	v_rcp_f32_e32 v99, v99
	v_pk_mul_f32 v[82:83], v[82:83], v[140:141] op_sel_hi:[1,0]
	v_pk_mul_f32 v[80:81], v[80:81], v[140:141] op_sel_hi:[1,0]
	v_pk_mul_f32 v[82:83], v[86:87], v[82:83]
	v_pk_mul_f32 v[80:81], v[84:85], v[80:81]
	v_pk_mul_f32 v[84:85], v[82:83], v[92:93]
	v_pk_mul_f32 v[82:83], v[80:81], v[94:95]
	v_pk_mul_f32 v[90:91], v[90:91], v[96:97]
	v_pk_mul_f32 v[88:89], v[88:89], v[98:99]
	v_pk_mul_f32 v[78:79], v[78:79], v[136:137] op_sel_hi:[1,0]
	v_cvt_pk_bf16_f32 v80, v88, v89
	v_cvt_pk_bf16_f32 v81, v90, v91
	v_cvt_pk_bf16_f32 v82, v82, v83
	v_cvt_pk_bf16_f32 v83, v84, v85
	v_mad_i64_i32 v[84:85], s[4:5], v188, s35, v[112:113]
	v_lshl_add_u64 v[84:85], v[84:85], 0, v[114:115]
	v_pk_mul_f32 v[76:77], v[76:77], v[136:137] op_sel_hi:[1,0]
	v_pk_mul_f32 v[74:75], v[74:75], v[136:137] op_sel_hi:[1,0]
	v_pk_mul_f32 v[72:73], v[72:73], v[136:137] op_sel_hi:[1,0]
	v_pk_mul_f32 v[70:71], v[70:71], v[136:137] op_sel_hi:[1,0]
	v_pk_mul_f32 v[68:69], v[68:69], v[136:137] op_sel_hi:[1,0]
	global_store_dwordx4 v[84:85], v[80:83], off
	v_pk_mul_f32 v[72:73], v[76:77], v[72:73]
	v_pk_mul_f32 v[74:75], v[78:79], v[74:75]
	v_pk_mul_f32 v[80:81], v[78:79], s[44:45] op_sel_hi:[1,0]
	v_pk_mul_f32 v[82:83], v[76:77], s[44:45] op_sel_hi:[1,0]
	v_pk_mul_f32 v[76:77], v[70:71], s[44:45] op_sel_hi:[1,0]
	v_pk_mul_f32 v[78:79], v[68:69], s[44:45] op_sel_hi:[1,0]
	v_exp_f32_e32 v76, v76
	v_exp_f32_e32 v78, v78
	v_exp_f32_e32 v77, v77
	v_exp_f32_e32 v79, v79
	v_exp_f32_e32 v82, v82
	v_exp_f32_e32 v80, v80
	v_exp_f32_e32 v81, v81
	v_exp_f32_e32 v83, v83
	v_pk_add_f32 v[76:77], v[76:77], 1.0 op_sel_hi:[1,0]
	v_pk_add_f32 v[78:79], v[78:79], 1.0 op_sel_hi:[1,0]
	v_pk_add_f32 v[80:81], v[80:81], 1.0 op_sel_hi:[1,0]
	v_pk_add_f32 v[82:83], v[82:83], 1.0 op_sel_hi:[1,0]
	v_rcp_f32_e32 v78, v78
	v_rcp_f32_e32 v76, v76
	v_rcp_f32_e32 v77, v77
	v_rcp_f32_e32 v79, v79
	v_rcp_f32_e32 v82, v82
	v_rcp_f32_e32 v80, v80
	v_rcp_f32_e32 v81, v81
	v_rcp_f32_e32 v83, v83
	v_pk_mul_f32 v[66:67], v[66:67], v[136:137] op_sel_hi:[1,0]
	v_pk_mul_f32 v[64:65], v[64:65], v[136:137] op_sel_hi:[1,0]
	v_pk_mul_f32 v[66:67], v[70:71], v[66:67]
	v_pk_mul_f32 v[64:65], v[68:69], v[64:65]
	v_pk_mul_f32 v[68:69], v[66:67], v[76:77]
	v_pk_mul_f32 v[66:67], v[64:65], v[78:79]
	v_pk_mul_f32 v[74:75], v[74:75], v[80:81]
	v_pk_mul_f32 v[72:73], v[72:73], v[82:83]
	v_pk_mul_f32 v[62:63], v[62:63], v[134:135] op_sel_hi:[1,0]
	v_cvt_pk_bf16_f32 v64, v72, v73
	v_cvt_pk_bf16_f32 v65, v74, v75
	v_cvt_pk_bf16_f32 v66, v66, v67
	v_cvt_pk_bf16_f32 v67, v68, v69
	v_mad_i64_i32 v[68:69], s[4:5], v174, s35, v[112:113]
	v_lshl_add_u64 v[68:69], v[68:69], 0, v[114:115]
	v_pk_mul_f32 v[60:61], v[60:61], v[134:135] op_sel_hi:[1,0]
	v_pk_mul_f32 v[58:59], v[58:59], v[134:135] op_sel_hi:[1,0]
	v_pk_mul_f32 v[56:57], v[56:57], v[134:135] op_sel_hi:[1,0]
	v_pk_mul_f32 v[54:55], v[54:55], v[134:135] op_sel_hi:[1,0]
	v_pk_mul_f32 v[52:53], v[52:53], v[134:135] op_sel_hi:[1,0]
	global_store_dwordx4 v[68:69], v[64:67], off
	v_pk_mul_f32 v[56:57], v[60:61], v[56:57]
	v_pk_mul_f32 v[58:59], v[62:63], v[58:59]
	v_pk_mul_f32 v[64:65], v[62:63], s[44:45] op_sel_hi:[1,0]
	v_pk_mul_f32 v[66:67], v[60:61], s[44:45] op_sel_hi:[1,0]
	v_pk_mul_f32 v[60:61], v[54:55], s[44:45] op_sel_hi:[1,0]
	v_pk_mul_f32 v[62:63], v[52:53], s[44:45] op_sel_hi:[1,0]
	v_exp_f32_e32 v60, v60
	v_exp_f32_e32 v62, v62
	v_exp_f32_e32 v61, v61
	v_exp_f32_e32 v63, v63
	v_exp_f32_e32 v66, v66
	v_exp_f32_e32 v64, v64
	v_exp_f32_e32 v65, v65
	v_exp_f32_e32 v67, v67
	v_pk_add_f32 v[60:61], v[60:61], 1.0 op_sel_hi:[1,0]
	v_pk_add_f32 v[62:63], v[62:63], 1.0 op_sel_hi:[1,0]
	v_pk_add_f32 v[64:65], v[64:65], 1.0 op_sel_hi:[1,0]
	v_pk_add_f32 v[66:67], v[66:67], 1.0 op_sel_hi:[1,0]
	v_rcp_f32_e32 v62, v62
	v_rcp_f32_e32 v60, v60
	v_rcp_f32_e32 v61, v61
	v_rcp_f32_e32 v63, v63
	v_rcp_f32_e32 v66, v66
	v_rcp_f32_e32 v64, v64
	v_rcp_f32_e32 v65, v65
	v_rcp_f32_e32 v67, v67
	v_pk_mul_f32 v[50:51], v[50:51], v[134:135] op_sel_hi:[1,0]
	v_pk_mul_f32 v[48:49], v[48:49], v[134:135] op_sel_hi:[1,0]
	v_pk_mul_f32 v[50:51], v[54:55], v[50:51]
	v_pk_mul_f32 v[48:49], v[52:53], v[48:49]
	v_mul_f32_e32 v132, 0x45800000, v135
	v_pk_mul_f32 v[52:53], v[50:51], v[60:61]
	v_pk_mul_f32 v[50:51], v[48:49], v[62:63]
	v_cndmask_b32_e64 v132, v135, v132, s[6:7]
	v_pk_mul_f32 v[58:59], v[58:59], v[64:65]
	v_pk_mul_f32 v[56:57], v[56:57], v[66:67]
	v_pk_mul_f32 v[46:47], v[46:47], v[132:133] op_sel_hi:[1,0]
	v_cvt_pk_bf16_f32 v48, v56, v57
	v_cvt_pk_bf16_f32 v49, v58, v59
	v_cvt_pk_bf16_f32 v50, v50, v51
	v_cvt_pk_bf16_f32 v51, v52, v53
	v_mad_i64_i32 v[52:53], s[4:5], v172, s35, v[112:113]
	v_lshl_add_u64 v[52:53], v[52:53], 0, v[114:115]
	v_pk_mul_f32 v[44:45], v[44:45], v[132:133] op_sel_hi:[1,0]
	v_pk_mul_f32 v[42:43], v[42:43], v[132:133] op_sel_hi:[1,0]
	v_pk_mul_f32 v[40:41], v[40:41], v[132:133] op_sel_hi:[1,0]
	v_pk_mul_f32 v[38:39], v[38:39], v[132:133] op_sel_hi:[1,0]
	v_pk_mul_f32 v[36:37], v[36:37], v[132:133] op_sel_hi:[1,0]
	global_store_dwordx4 v[52:53], v[48:51], off
	v_pk_mul_f32 v[40:41], v[44:45], v[40:41]
	v_pk_mul_f32 v[42:43], v[46:47], v[42:43]
	v_pk_mul_f32 v[48:49], v[46:47], s[44:45] op_sel_hi:[1,0]
	v_pk_mul_f32 v[50:51], v[44:45], s[44:45] op_sel_hi:[1,0]
	v_pk_mul_f32 v[44:45], v[38:39], s[44:45] op_sel_hi:[1,0]
	v_pk_mul_f32 v[46:47], v[36:37], s[44:45] op_sel_hi:[1,0]
	v_exp_f32_e32 v44, v44
	v_exp_f32_e32 v46, v46
	v_exp_f32_e32 v45, v45
	v_exp_f32_e32 v47, v47
	v_exp_f32_e32 v50, v50
	v_exp_f32_e32 v48, v48
	v_exp_f32_e32 v49, v49
	v_exp_f32_e32 v51, v51
	v_pk_add_f32 v[44:45], v[44:45], 1.0 op_sel_hi:[1,0]
	v_pk_add_f32 v[46:47], v[46:47], 1.0 op_sel_hi:[1,0]
	v_pk_add_f32 v[48:49], v[48:49], 1.0 op_sel_hi:[1,0]
	v_pk_add_f32 v[50:51], v[50:51], 1.0 op_sel_hi:[1,0]
	v_rcp_f32_e32 v46, v46
	v_rcp_f32_e32 v44, v44
	v_rcp_f32_e32 v45, v45
	v_rcp_f32_e32 v47, v47
	v_rcp_f32_e32 v50, v50
	v_rcp_f32_e32 v48, v48
	v_rcp_f32_e32 v49, v49
	v_rcp_f32_e32 v51, v51
	v_pk_mul_f32 v[34:35], v[34:35], v[132:133] op_sel_hi:[1,0]
	v_pk_mul_f32 v[32:33], v[32:33], v[132:133] op_sel_hi:[1,0]
	v_pk_mul_f32 v[34:35], v[38:39], v[34:35]
	v_pk_mul_f32 v[32:33], v[36:37], v[32:33]
	v_pk_mul_f32 v[36:37], v[34:35], v[44:45]
	v_pk_mul_f32 v[34:35], v[32:33], v[46:47]
	v_pk_mul_f32 v[42:43], v[42:43], v[48:49]
	v_pk_mul_f32 v[40:41], v[40:41], v[50:51]
	v_pk_mul_f32 v[30:31], v[30:31], v[130:131] op_sel_hi:[1,0]
	v_cvt_pk_bf16_f32 v32, v40, v41
	v_cvt_pk_bf16_f32 v33, v42, v43
	v_cvt_pk_bf16_f32 v34, v34, v35
	v_cvt_pk_bf16_f32 v35, v36, v37
	v_mad_i64_i32 v[36:37], s[4:5], v170, s35, v[112:113]
	v_lshl_add_u64 v[36:37], v[36:37], 0, v[114:115]
	v_pk_mul_f32 v[28:29], v[28:29], v[130:131] op_sel_hi:[1,0]
	v_pk_mul_f32 v[26:27], v[26:27], v[130:131] op_sel_hi:[1,0]
	v_pk_mul_f32 v[24:25], v[24:25], v[130:131] op_sel_hi:[1,0]
	v_pk_mul_f32 v[22:23], v[22:23], v[130:131] op_sel_hi:[1,0]
	v_pk_mul_f32 v[20:21], v[20:21], v[130:131] op_sel_hi:[1,0]
	global_store_dwordx4 v[36:37], v[32:35], off
	v_pk_mul_f32 v[24:25], v[28:29], v[24:25]
	v_pk_mul_f32 v[26:27], v[30:31], v[26:27]
	v_pk_mul_f32 v[32:33], v[30:31], s[44:45] op_sel_hi:[1,0]
	v_pk_mul_f32 v[34:35], v[28:29], s[44:45] op_sel_hi:[1,0]
	v_pk_mul_f32 v[28:29], v[22:23], s[44:45] op_sel_hi:[1,0]
	v_pk_mul_f32 v[30:31], v[20:21], s[44:45] op_sel_hi:[1,0]
	v_exp_f32_e32 v28, v28
	v_exp_f32_e32 v30, v30
	v_exp_f32_e32 v29, v29
	v_exp_f32_e32 v31, v31
	v_exp_f32_e32 v34, v34
	v_exp_f32_e32 v32, v32
	v_exp_f32_e32 v33, v33
	v_exp_f32_e32 v35, v35
	v_pk_add_f32 v[28:29], v[28:29], 1.0 op_sel_hi:[1,0]
	v_pk_add_f32 v[30:31], v[30:31], 1.0 op_sel_hi:[1,0]
	v_pk_add_f32 v[32:33], v[32:33], 1.0 op_sel_hi:[1,0]
	v_pk_add_f32 v[34:35], v[34:35], 1.0 op_sel_hi:[1,0]
	v_rcp_f32_e32 v30, v30
	v_rcp_f32_e32 v28, v28
	v_rcp_f32_e32 v29, v29
	v_rcp_f32_e32 v31, v31
	v_rcp_f32_e32 v34, v34
	v_rcp_f32_e32 v32, v32
	v_rcp_f32_e32 v33, v33
	v_rcp_f32_e32 v35, v35
	v_pk_mul_f32 v[18:19], v[18:19], v[130:131] op_sel_hi:[1,0]
	v_pk_mul_f32 v[16:17], v[16:17], v[130:131] op_sel_hi:[1,0]
	v_pk_mul_f32 v[18:19], v[22:23], v[18:19]
	v_pk_mul_f32 v[16:17], v[20:21], v[16:17]
	v_pk_mul_f32 v[20:21], v[18:19], v[28:29]
	v_pk_mul_f32 v[18:19], v[16:17], v[30:31]
	v_pk_mul_f32 v[26:27], v[26:27], v[32:33]
	v_pk_mul_f32 v[24:25], v[24:25], v[34:35]
	v_pk_mul_f32 v[14:15], v[14:15], v[128:129] op_sel_hi:[1,0]
	v_cvt_pk_bf16_f32 v16, v24, v25
	v_cvt_pk_bf16_f32 v17, v26, v27
	v_cvt_pk_bf16_f32 v18, v18, v19
	v_cvt_pk_bf16_f32 v19, v20, v21
	v_mad_i64_i32 v[20:21], s[4:5], v168, s35, v[112:113]
	v_lshl_add_u64 v[20:21], v[20:21], 0, v[114:115]
	v_pk_mul_f32 v[12:13], v[12:13], v[128:129] op_sel_hi:[1,0]
	v_pk_mul_f32 v[10:11], v[10:11], v[128:129] op_sel_hi:[1,0]
	v_pk_mul_f32 v[8:9], v[8:9], v[128:129] op_sel_hi:[1,0]
	v_pk_mul_f32 v[6:7], v[6:7], v[128:129] op_sel_hi:[1,0]
	v_pk_mul_f32 v[4:5], v[4:5], v[128:129] op_sel_hi:[1,0]
	global_store_dwordx4 v[20:21], v[16:19], off
	v_pk_mul_f32 v[8:9], v[12:13], v[8:9]
	v_pk_mul_f32 v[10:11], v[14:15], v[10:11]
	v_pk_mul_f32 v[16:17], v[14:15], s[44:45] op_sel_hi:[1,0]
	v_pk_mul_f32 v[18:19], v[12:13], s[44:45] op_sel_hi:[1,0]
	v_pk_mul_f32 v[12:13], v[6:7], s[44:45] op_sel_hi:[1,0]
	v_pk_mul_f32 v[14:15], v[4:5], s[44:45] op_sel_hi:[1,0]
	v_exp_f32_e32 v12, v12
	v_exp_f32_e32 v14, v14
	v_exp_f32_e32 v13, v13
	v_exp_f32_e32 v15, v15
	v_exp_f32_e32 v18, v18
	v_exp_f32_e32 v16, v16
	v_exp_f32_e32 v17, v17
	v_exp_f32_e32 v19, v19
	v_pk_add_f32 v[12:13], v[12:13], 1.0 op_sel_hi:[1,0]
	v_pk_add_f32 v[14:15], v[14:15], 1.0 op_sel_hi:[1,0]
	v_pk_add_f32 v[16:17], v[16:17], 1.0 op_sel_hi:[1,0]
	v_pk_add_f32 v[18:19], v[18:19], 1.0 op_sel_hi:[1,0]
	v_rcp_f32_e32 v14, v14
	v_rcp_f32_e32 v12, v12
	v_rcp_f32_e32 v13, v13
	v_rcp_f32_e32 v15, v15
	v_rcp_f32_e32 v18, v18
	v_rcp_f32_e32 v16, v16
	v_rcp_f32_e32 v17, v17
	v_rcp_f32_e32 v19, v19
	v_pk_mul_f32 v[2:3], v[2:3], v[128:129] op_sel_hi:[1,0]
	v_pk_mul_f32 v[0:1], v[0:1], v[128:129] op_sel_hi:[1,0]
	v_pk_mul_f32 v[2:3], v[6:7], v[2:3]
	v_pk_mul_f32 v[0:1], v[4:5], v[0:1]
	v_pk_mul_f32 v[4:5], v[2:3], v[12:13]
	v_pk_mul_f32 v[2:3], v[0:1], v[14:15]
	v_pk_mul_f32 v[10:11], v[10:11], v[16:17]
	v_pk_mul_f32 v[8:9], v[8:9], v[18:19]
	s_andn2_b64 vcc, exec, s[2:3]
	v_cvt_pk_bf16_f32 v0, v8, v9
	v_cvt_pk_bf16_f32 v1, v10, v11
	v_cvt_pk_bf16_f32 v2, v2, v3
	v_cvt_pk_bf16_f32 v3, v4, v5
	v_mad_i64_i32 v[4:5], s[4:5], v166, s35, v[112:113]
	v_lshl_add_u64 v[4:5], v[4:5], 0, v[114:115]
	s_mov_b32 s4, s16
	s_mov_b32 s5, s12
	s_mov_b64 s[6:7], s[18:19]
	global_store_dwordx4 v[4:5], v[0:3], off
	s_cbranch_vccnz .LBB0_1429
	s_waitcnt vmcnt(0)
	s_cmpk_gt_u32 s24, 0xff
	s_cbranch_scc1 .LBB0_1440
	s_barrier
